# one static s_setprio 1 for waves 4-7 before the layer loop; the per-cluster s_setprio 1/0 flips in the six GEMM main loops deleted
# speedup vs baseline: 1.0126x; 1.0000x over previous
.Lcvth_done2:
.LBB0_156:
	v_readlane_b32 s0, v251, 36
	s_cmp_ge_u32 s0, 4
	s_cbranch_scc0 .Lprio_done
	s_setprio 1

.LBB0_403:
	s_add_u32 s14, s4, 0x100
	s_addc_u32 s15, s5, 0
	s_add_i32 s38, 0, 0x10000
	v_add_u32_e32 v12, s38, v193
	ds_read_b128 v[0:3], v12
	ds_read_b128 v[8:11], v12 offset:2048
	ds_read_b128 v[4:7], v12 offset:1024
	ds_read_b128 v[12:15], v12 offset:3072
	s_cmp_eq_u32 s37, 12
	s_cselect_b32 s19, s9, s15
	s_cselect_b32 s18, s8, s14
	s_cselect_b32 s17, s11, s36
	s_cselect_b32 s16, s10, s7
	v_lshl_add_u64 v[190:191], s[4:5], 0, v[186:187]
	s_add_i32 m0, s23, 0xc000
	ds_read_b128 v[16:19], v206
	ds_read_b128 v[24:27], v206 offset:2048
	ds_read_b128 v[162:165], v206 offset:4096
	ds_read_b128 v[170:173], v206 offset:6144
	ds_read_b128 v[20:23], v206 offset:1024
	ds_read_b128 v[28:31], v206 offset:3072
	ds_read_b128 v[166:169], v206 offset:5120
	ds_read_b128 v[174:177], v206 offset:7168
	global_load_lds_dwordx4 v[190:191], off
	v_lshl_add_u64 v[190:191], s[4:5], 0, v[188:189]
	s_add_i32 m0, s23, 0xe000
	s_nop 0
	global_load_lds_dwordx4 v[190:191], off
	s_waitcnt lgkmcnt(8)
	s_barrier
	s_waitcnt lgkmcnt(7)
	v_mfma_f32_16x16x32_f16 v[158:161], v[0:3], v[16:19], v[158:161]
	v_mfma_f32_16x16x32_f16 v[142:145], v[8:11], v[16:19], v[142:145]
	s_waitcnt lgkmcnt(6)
	v_mfma_f32_16x16x32_f16 v[150:153], v[0:3], v[24:27], v[150:153]
	v_mfma_f32_16x16x32_f16 v[134:137], v[8:11], v[24:27], v[134:137]
	s_waitcnt lgkmcnt(5)
	v_mfma_f32_16x16x32_f16 v[154:157], v[0:3], v[162:165], v[154:157]
	v_mfma_f32_16x16x32_f16 v[138:141], v[8:11], v[162:165], v[138:141]
	s_waitcnt lgkmcnt(4)
	v_mfma_f32_16x16x32_f16 v[146:149], v[0:3], v[170:173], v[146:149]
	v_mfma_f32_16x16x32_f16 v[130:133], v[8:11], v[170:173], v[130:133]
	s_waitcnt lgkmcnt(3)
	v_mfma_f32_16x16x32_f16 v[158:161], v[4:7], v[20:23], v[158:161]
	v_mfma_f32_16x16x32_f16 v[142:145], v[12:15], v[20:23], v[142:145]
	s_waitcnt lgkmcnt(2)
	v_mfma_f32_16x16x32_f16 v[150:153], v[4:7], v[28:31], v[150:153]
	v_mfma_f32_16x16x32_f16 v[134:137], v[12:15], v[28:31], v[134:137]
	s_waitcnt lgkmcnt(1)
	v_mfma_f32_16x16x32_f16 v[154:157], v[4:7], v[166:169], v[154:157]
	v_mfma_f32_16x16x32_f16 v[138:141], v[12:15], v[166:169], v[138:141]
	s_waitcnt lgkmcnt(0)
	v_mfma_f32_16x16x32_f16 v[146:149], v[4:7], v[174:177], v[146:149]
	v_mfma_f32_16x16x32_f16 v[130:133], v[12:15], v[174:177], v[130:133]
	s_barrier
	s_add_i32 s39, 0, 0x14000
	s_add_i32 s4, s38, s22
	v_add_u32_e32 v32, s39, v193
	v_lshl_add_u64 v[190:191], s[16:17], 0, v[178:179]
	s_mov_b32 m0, s4
	ds_read_b128 v[208:211], v32
	ds_read_b128 v[216:219], v32 offset:2048
	ds_read_b128 v[212:215], v32 offset:1024
	ds_read_b128 v[230:233], v32 offset:3072
	global_load_lds_dwordx4 v[190:191], off
	v_lshl_add_u64 v[238:239], s[16:17], 0, v[180:181]
	s_add_i32 m0, s4, 0x2000
	s_nop 0
	global_load_lds_dwordx4 v[238:239], off
	s_barrier
	s_waitcnt lgkmcnt(2)
	v_mfma_f32_16x16x32_f16 v[94:97], v[208:211], v[16:19], v[94:97]
	v_mfma_f32_16x16x32_f16 v[16:19], v[216:219], v[16:19], v[78:81]
	s_waitcnt lgkmcnt(0)
	v_mfma_f32_16x16x32_f16 v[94:97], v[212:215], v[20:23], v[94:97]
	v_mfma_f32_16x16x32_f16 v[16:19], v[230:233], v[20:23], v[16:19]
	v_mfma_f32_16x16x32_f16 v[20:23], v[208:211], v[24:27], v[86:89]
	v_mfma_f32_16x16x32_f16 v[24:27], v[216:219], v[24:27], v[70:73]
	v_mfma_f32_16x16x32_f16 v[70:73], v[216:219], v[162:165], v[74:77]
	v_mfma_f32_16x16x32_f16 v[74:77], v[230:233], v[166:169], v[70:73]
	v_mfma_f32_16x16x32_f16 v[70:73], v[208:211], v[170:173], v[82:85]
	v_mfma_f32_16x16x32_f16 v[66:69], v[216:219], v[170:173], v[66:69]
	v_mfma_f32_16x16x32_f16 v[20:23], v[212:215], v[28:31], v[20:23]
	v_mfma_f32_16x16x32_f16 v[24:27], v[230:233], v[28:31], v[24:27]
	v_mfma_f32_16x16x32_f16 v[28:31], v[208:211], v[162:165], v[90:93]
	v_mfma_f32_16x16x32_f16 v[82:85], v[212:215], v[174:177], v[70:73]
	v_mfma_f32_16x16x32_f16 v[66:69], v[230:233], v[174:177], v[66:69]
	v_mfma_f32_16x16x32_f16 v[28:31], v[212:215], v[166:169], v[28:31]
	s_mov_b32 m0, s23
	v_lshl_add_u64 v[240:241], s[18:19], 0, v[178:179]
	s_barrier
	ds_read_b128 v[70:73], v206 offset:16384
	ds_read_b128 v[86:89], v206 offset:18432
	ds_read_b128 v[162:165], v206 offset:20480
	ds_read_b128 v[170:173], v206 offset:22528
	ds_read_b128 v[78:81], v206 offset:17408
	ds_read_b128 v[90:93], v206 offset:19456
	ds_read_b128 v[166:169], v206 offset:21504
	ds_read_b128 v[174:177], v206 offset:23552
	global_load_lds_dwordx4 v[240:241], off
	v_lshl_add_u64 v[242:243], s[18:19], 0, v[180:181]
	s_mov_b32 m0, s24
	s_nop 0
	global_load_lds_dwordx4 v[242:243], off
	s_barrier
	s_waitcnt lgkmcnt(7)
	v_mfma_f32_16x16x32_f16 v[126:129], v[0:3], v[70:73], v[126:129]
	v_mfma_f32_16x16x32_f16 v[110:113], v[8:11], v[70:73], v[110:113]
	s_waitcnt lgkmcnt(6)
	v_mfma_f32_16x16x32_f16 v[118:121], v[0:3], v[86:89], v[118:121]
	v_mfma_f32_16x16x32_f16 v[102:105], v[8:11], v[86:89], v[102:105]
	s_waitcnt lgkmcnt(5)
	v_mfma_f32_16x16x32_f16 v[122:125], v[0:3], v[162:165], v[122:125]
	v_mfma_f32_16x16x32_f16 v[106:109], v[8:11], v[162:165], v[106:109]
	s_waitcnt lgkmcnt(3)
	v_mfma_f32_16x16x32_f16 v[0:3], v[0:3], v[170:173], v[114:117]
	v_mfma_f32_16x16x32_f16 v[126:129], v[4:7], v[78:81], v[126:129]
	s_waitcnt lgkmcnt(2)
	v_mfma_f32_16x16x32_f16 v[110:113], v[12:15], v[78:81], v[110:113]
	v_mfma_f32_16x16x32_f16 v[118:121], v[4:7], v[90:93], v[118:121]
	s_waitcnt lgkmcnt(1)
	v_mfma_f32_16x16x32_f16 v[102:105], v[12:15], v[90:93], v[102:105]
	v_mfma_f32_16x16x32_f16 v[122:125], v[4:7], v[166:169], v[122:125]
	s_waitcnt lgkmcnt(0)
	v_mfma_f32_16x16x32_f16 v[106:109], v[12:15], v[166:169], v[106:109]
	v_mfma_f32_16x16x32_f16 v[0:3], v[4:7], v[174:177], v[0:3]
	v_mfma_f32_16x16x32_f16 v[4:7], v[8:11], v[170:173], v[98:101]
	v_mfma_f32_16x16x32_f16 v[4:7], v[12:15], v[174:177], v[4:7]
	s_barrier
	s_add_u32 s4, s16, 0x40000
	s_addc_u32 s5, s17, 0
	s_add_i32 s38, s39, s22
	v_lshl_add_u64 v[8:9], s[4:5], 0, v[178:179]
	s_mov_b32 m0, s38
	s_nop 0
	global_load_lds_dwordx4 v[8:9], off
	v_lshl_add_u64 v[8:9], s[4:5], 0, v[180:181]
	s_add_i32 m0, s38, 0x2000
	s_nop 0
	global_load_lds_dwordx4 v[8:9], off
	s_waitcnt vmcnt(6)
	s_barrier
	v_mfma_f32_16x16x32_f16 v[12:15], v[216:219], v[70:73], v[46:49]
	v_mfma_f32_16x16x32_f16 v[46:49], v[208:211], v[86:89], v[54:57]
	v_mfma_f32_16x16x32_f16 v[54:57], v[212:215], v[90:93], v[46:49]
	v_mfma_f32_16x16x32_f16 v[46:49], v[208:211], v[162:165], v[58:61]
	v_mfma_f32_16x16x32_f16 v[38:41], v[216:219], v[86:89], v[38:41]
	v_mfma_f32_16x16x32_f16 v[58:61], v[212:215], v[166:169], v[46:49]
	v_mfma_f32_16x16x32_f16 v[42:45], v[216:219], v[162:165], v[42:45]
	v_mfma_f32_16x16x32_f16 v[46:49], v[208:211], v[170:173], v[50:53]
	v_mfma_f32_16x16x32_f16 v[34:37], v[216:219], v[170:173], v[34:37]
	v_mfma_f32_16x16x32_f16 v[8:11], v[208:211], v[70:73], v[62:65]
	v_mfma_f32_16x16x32_f16 v[38:41], v[230:233], v[90:93], v[38:41]
	v_mfma_f32_16x16x32_f16 v[42:45], v[230:233], v[166:169], v[42:45]
	v_mfma_f32_16x16x32_f16 v[50:53], v[212:215], v[174:177], v[46:49]
	v_mfma_f32_16x16x32_f16 v[34:37], v[230:233], v[174:177], v[34:37]
	v_mfma_f32_16x16x32_f16 v[8:11], v[212:215], v[78:81], v[8:11]
	v_mfma_f32_16x16x32_f16 v[12:15], v[230:233], v[78:81], v[12:15]
	s_add_i32 s38, 0, 0x18000
	v_add_u32_e32 v32, s38, v193
	s_barrier
	ds_read_b128 v[46:49], v32
	ds_read_b128 v[62:65], v32 offset:1024
	ds_read_b128 v[98:101], v32 offset:2048
	ds_read_b128 v[162:165], v32 offset:3072
	s_add_u32 s4, s18, 0x40000
	s_addc_u32 s5, s19, 0
	s_mov_b32 m0, s25
	v_lshl_add_u64 v[86:87], s[4:5], 0, v[178:179]
	ds_read_b128 v[70:73], v206 offset:32768
	ds_read_b128 v[78:81], v206 offset:33792
	ds_read_b128 v[90:93], v206 offset:34816
	ds_read_b128 v[114:117], v206 offset:35840
	ds_read_b128 v[166:169], v206 offset:36864
	ds_read_b128 v[170:173], v206 offset:37888
	ds_read_b128 v[174:177], v206 offset:38912
	ds_read_b128 v[208:211], v206 offset:39936
	global_load_lds_dwordx4 v[86:87], off
	v_lshl_add_u64 v[86:87], s[4:5], 0, v[180:181]
	s_mov_b32 m0, s26
	s_nop 0
	global_load_lds_dwordx4 v[86:87], off
	s_waitcnt lgkmcnt(8)
	s_barrier
	s_waitcnt lgkmcnt(6)
	v_mfma_f32_16x16x32_f16 v[86:89], v[46:49], v[70:73], v[158:161]
	v_mfma_f32_16x16x32_f16 v[158:161], v[62:65], v[78:81], v[86:89]
	v_mfma_f32_16x16x32_f16 v[86:89], v[98:101], v[70:73], v[142:145]
	v_mfma_f32_16x16x32_f16 v[142:145], v[162:165], v[78:81], v[86:89]
	s_waitcnt lgkmcnt(4)
	v_mfma_f32_16x16x32_f16 v[86:89], v[46:49], v[90:93], v[150:153]
	v_mfma_f32_16x16x32_f16 v[150:153], v[62:65], v[114:117], v[86:89]
	v_mfma_f32_16x16x32_f16 v[86:89], v[98:101], v[90:93], v[134:137]
	v_mfma_f32_16x16x32_f16 v[134:137], v[162:165], v[114:117], v[86:89]
	s_waitcnt lgkmcnt(2)
	v_mfma_f32_16x16x32_f16 v[86:89], v[46:49], v[166:169], v[154:157]
	v_mfma_f32_16x16x32_f16 v[154:157], v[62:65], v[170:173], v[86:89]
	v_mfma_f32_16x16x32_f16 v[86:89], v[98:101], v[166:169], v[138:141]
	v_mfma_f32_16x16x32_f16 v[138:141], v[162:165], v[170:173], v[86:89]
	s_waitcnt lgkmcnt(0)
	v_mfma_f32_16x16x32_f16 v[86:89], v[46:49], v[174:177], v[146:149]
	v_mfma_f32_16x16x32_f16 v[146:149], v[62:65], v[208:211], v[86:89]
	v_mfma_f32_16x16x32_f16 v[86:89], v[98:101], v[174:177], v[130:133]
	v_mfma_f32_16x16x32_f16 v[130:133], v[162:165], v[208:211], v[86:89]
	s_barrier
	s_add_i32 s18, 0, 0x1c000
	s_add_i32 s4, s38, s22
	v_add_u32_e32 v32, s18, v193
	s_nop 1
	v_lshl_add_u64 v[86:87], v[190:191], 0, s[84:85]
	s_mov_b32 m0, s4
	ds_read_b128 v[212:215], v32
	ds_read_b128 v[230:233], v32 offset:2048
	ds_read_b128 v[216:219], v32 offset:1024
	ds_read_b128 v[234:237], v32 offset:3072
	global_load_lds_dwordx4 v[86:87], off
	v_lshl_add_u64 v[86:87], v[238:239], 0, s[84:85]
	s_add_i32 m0, s4, 0x2000
	s_nop 0
	global_load_lds_dwordx4 v[86:87], off
	s_barrier
	s_waitcnt lgkmcnt(2)
	v_mfma_f32_16x16x32_f16 v[86:89], v[212:215], v[70:73], v[94:97]
	v_mfma_f32_16x16x32_f16 v[16:19], v[230:233], v[70:73], v[16:19]
	s_waitcnt lgkmcnt(0)
	v_mfma_f32_16x16x32_f16 v[94:97], v[216:219], v[78:81], v[86:89]
	v_mfma_f32_16x16x32_f16 v[78:81], v[234:237], v[78:81], v[16:19]
	v_mfma_f32_16x16x32_f16 v[16:19], v[212:215], v[90:93], v[20:23]
	v_mfma_f32_16x16x32_f16 v[86:89], v[216:219], v[114:117], v[16:19]
	v_mfma_f32_16x16x32_f16 v[16:19], v[230:233], v[90:93], v[24:27]
	v_mfma_f32_16x16x32_f16 v[70:73], v[234:237], v[114:117], v[16:19]
	v_mfma_f32_16x16x32_f16 v[16:19], v[212:215], v[166:169], v[28:31]
	v_mfma_f32_16x16x32_f16 v[90:93], v[216:219], v[170:173], v[16:19]
	v_mfma_f32_16x16x32_f16 v[16:19], v[230:233], v[166:169], v[74:77]
	v_mfma_f32_16x16x32_f16 v[74:77], v[234:237], v[170:173], v[16:19]
	v_mfma_f32_16x16x32_f16 v[16:19], v[212:215], v[174:177], v[82:85]
	v_mfma_f32_16x16x32_f16 v[82:85], v[216:219], v[208:211], v[16:19]
	v_mfma_f32_16x16x32_f16 v[16:19], v[230:233], v[174:177], v[66:69]
	v_mfma_f32_16x16x32_f16 v[66:69], v[234:237], v[208:211], v[16:19]
	s_mov_b32 m0, s28
	v_lshl_add_u64 v[114:115], v[240:241], 0, s[84:85]
	s_barrier
	s_nop 2
	ds_read_b128 v[16:19], v206 offset:49152
	ds_read_b128 v[20:23], v206 offset:50176
	ds_read_b128 v[24:27], v206 offset:51200
	ds_read_b128 v[28:31], v206 offset:52224
	ds_read_b128 v[166:169], v206 offset:53248
	ds_read_b128 v[174:177], v206 offset:55296
	ds_read_b128 v[170:173], v206 offset:54272
	ds_read_b128 v[208:211], v206 offset:56320
	global_load_lds_dwordx4 v[114:115], off
	v_lshl_add_u64 v[114:115], v[242:243], 0, s[84:85]
	s_mov_b32 m0, s29
	s_nop 0
	global_load_lds_dwordx4 v[114:115], off
	s_barrier
	s_waitcnt lgkmcnt(6)
	v_mfma_f32_16x16x32_f16 v[114:117], v[46:49], v[16:19], v[126:129]
	v_mfma_f32_16x16x32_f16 v[126:129], v[62:65], v[20:23], v[114:117]
	s_waitcnt lgkmcnt(4)
	v_mfma_f32_16x16x32_f16 v[114:117], v[46:49], v[24:27], v[118:121]
	v_mfma_f32_16x16x32_f16 v[118:121], v[62:65], v[28:31], v[114:117]
	s_waitcnt lgkmcnt(2)
	v_mfma_f32_16x16x32_f16 v[114:117], v[46:49], v[166:169], v[122:125]
	v_mfma_f32_16x16x32_f16 v[0:3], v[46:49], v[174:177], v[0:3]
	v_mfma_f32_16x16x32_f16 v[110:113], v[98:101], v[16:19], v[110:113]
	v_mfma_f32_16x16x32_f16 v[102:105], v[98:101], v[24:27], v[102:105]
	s_waitcnt lgkmcnt(1)
	v_mfma_f32_16x16x32_f16 v[122:125], v[62:65], v[170:173], v[114:117]
	v_mfma_f32_16x16x32_f16 v[106:109], v[98:101], v[166:169], v[106:109]
	s_waitcnt lgkmcnt(0)
	v_mfma_f32_16x16x32_f16 v[114:117], v[62:65], v[208:211], v[0:3]
	v_mfma_f32_16x16x32_f16 v[0:3], v[98:101], v[174:177], v[4:7]
	v_mfma_f32_16x16x32_f16 v[110:113], v[162:165], v[20:23], v[110:113]
	v_mfma_f32_16x16x32_f16 v[102:105], v[162:165], v[28:31], v[102:105]
	v_mfma_f32_16x16x32_f16 v[106:109], v[162:165], v[170:173], v[106:109]
	v_mfma_f32_16x16x32_f16 v[98:101], v[162:165], v[208:211], v[0:3]
	s_barrier
	s_add_u32 s4, s16, 0x40080
	s_addc_u32 s5, s17, 0
	s_add_i32 s16, s18, s22
	v_lshl_add_u64 v[0:1], s[4:5], 0, v[178:179]
	s_mov_b32 m0, s16
	s_nop 0
	global_load_lds_dwordx4 v[0:1], off
	v_lshl_add_u64 v[0:1], s[4:5], 0, v[180:181]
	s_add_i32 m0, s16, 0x2000
	s_nop 0
	global_load_lds_dwordx4 v[0:1], off
	s_waitcnt vmcnt(6)
	s_barrier
	v_mfma_f32_16x16x32_f16 v[0:3], v[212:215], v[16:19], v[8:11]
	v_mfma_f32_16x16x32_f16 v[62:65], v[216:219], v[20:23], v[0:3]
	v_mfma_f32_16x16x32_f16 v[0:3], v[230:233], v[16:19], v[12:15]
	v_mfma_f32_16x16x32_f16 v[46:49], v[234:237], v[20:23], v[0:3]
	v_mfma_f32_16x16x32_f16 v[0:3], v[212:215], v[24:27], v[54:57]
	v_mfma_f32_16x16x32_f16 v[54:57], v[216:219], v[28:31], v[0:3]
	v_mfma_f32_16x16x32_f16 v[0:3], v[230:233], v[24:27], v[38:41]
	v_mfma_f32_16x16x32_f16 v[38:41], v[234:237], v[28:31], v[0:3]
	v_mfma_f32_16x16x32_f16 v[0:3], v[212:215], v[166:169], v[58:61]
	v_mfma_f32_16x16x32_f16 v[58:61], v[216:219], v[170:173], v[0:3]
	v_mfma_f32_16x16x32_f16 v[0:3], v[230:233], v[166:169], v[42:45]
	v_mfma_f32_16x16x32_f16 v[42:45], v[234:237], v[170:173], v[0:3]
	v_mfma_f32_16x16x32_f16 v[0:3], v[212:215], v[174:177], v[50:53]
	v_mfma_f32_16x16x32_f16 v[50:53], v[216:219], v[208:211], v[0:3]
	v_mfma_f32_16x16x32_f16 v[0:3], v[230:233], v[174:177], v[34:37]
	v_mfma_f32_16x16x32_f16 v[34:37], v[234:237], v[208:211], v[0:3]
	s_add_i32 s37, s37, 2
	s_add_u32 s7, s7, 0x100
	s_addc_u32 s36, s36, 0
	s_cmp_gt_u32 s37, 13
	s_mov_b64 s[4:5], s[14:15]
	s_barrier
	s_cbranch_scc0 .LBB0_403
	s_lshl_b32 s7, s34, 8
	s_cmp_lt_i32 s35, 28
	s_mov_b64 s[4:5], -1
	s_cbranch_scc0 .LBB0_431
	s_add_i32 s16, s7, s27
	v_or_b32_e32 v207, s16, v192
	s_cmp_gt_i32 s35, 3
	s_cbranch_scc0 .LBB0_411
	s_add_i32 s4, s35, -12
	s_cmp_gt_u32 s4, 7
	s_mov_b64 s[4:5], -1
	s_cbranch_scc0 .LBB0_408
	s_lshl_b32 s4, s35, 8
	s_add_i32 s5, s4, 0xfffffc00
	s_cmp_lt_u32 s35, 12
	s_cselect_b32 s4, s4, s5
	v_and_b32_e32 v10, 7, v220
	v_and_b32_e32 v11, 8, v220
	v_cmp_ne_u32_e32 vcc, 0, v11
	v_and_b32_e32 v12, 0x60, v194
	v_lshlrev_b32_e32 v12, 1, v12
	v_lshl_or_b32 v12, v11, 2, v12
	v_and_b32_e32 v13, 0x18, v194
	v_or_b32_e32 v12, v12, v13
	v_or_b32_e32 v32, s4, v12
	v_or_b32_e32 v14, s16, v10
	v_mov_b64_e32 v[4:5], s[70:71]
	v_mad_i64_i32 v[0:1], s[4:5], v14, s33, v[4:5]
	v_lshlrev_b64 v[6:7], 1, v[32:33]
	v_lshl_add_u64 v[16:17], v[0:1], 0, v[6:7]
	v_mov_b32_e32 v32, 0x30000
	v_lshl_add_u64 v[18:19], v[16:17], 0, v[32:33]
	v_lshl_add_u64 v[20:21], v[18:19], 0, v[32:33]
	v_lshl_add_u64 v[22:23], v[20:21], 0, v[32:33]
	v_mov_b32_e32 v8, 0x180000
	v_mov_b32_e32 v9, 0
	v_lshl_add_u64 v[24:25], v[16:17], 0, v[8:9]
	v_lshl_add_u64 v[26:27], v[24:25], 0, v[32:33]
	v_lshl_add_u64 v[28:29], v[26:27], 0, v[32:33]
	v_lshl_add_u64 v[30:31], v[28:29], 0, v[32:33]
	v_mov_b32_e32 v8, 0x18000
	v_cvt_pk_f16_f32 v158, v158, v159
	v_cvt_pk_f16_f32 v159, v160, v161
	v_cvt_pk_f16_f32 v160, v142, v143
	v_cvt_pk_f16_f32 v161, v144, v145
	v_cvt_pk_f16_f32 v94, v94, v95
	v_cvt_pk_f16_f32 v95, v96, v97
	v_cvt_pk_f16_f32 v96, v78, v79
	v_cvt_pk_f16_f32 v97, v80, v81
	v_mov_b32_dpp v0, v158 row_ror:8 row_mask:0xf bank_mask:0xf
	v_mov_b32_dpp v1, v159 row_ror:8 row_mask:0xf bank_mask:0xf
	v_mov_b32_dpp v2, v160 row_ror:8 row_mask:0xf bank_mask:0xf
	v_mov_b32_dpp v3, v161 row_ror:8 row_mask:0xf bank_mask:0xf
	v_mov_b32_dpp v4, v94 row_ror:8 row_mask:0xf bank_mask:0xf
	v_mov_b32_dpp v5, v95 row_ror:8 row_mask:0xf bank_mask:0xf
	v_mov_b32_dpp v6, v96 row_ror:8 row_mask:0xf bank_mask:0xf
	v_mov_b32_dpp v7, v97 row_ror:8 row_mask:0xf bank_mask:0xf
	v_cndmask_b32_e32 v158, v158, v4, vcc
	v_cndmask_b32_e32 v159, v159, v5, vcc
	v_cndmask_b32_e32 v160, v160, v6, vcc
	v_cndmask_b32_e32 v161, v161, v7, vcc
	v_cndmask_b32_e32 v94, v0, v94, vcc
	v_cndmask_b32_e32 v95, v1, v95, vcc
	v_cndmask_b32_e32 v96, v2, v96, vcc
	v_cndmask_b32_e32 v97, v3, v97, vcc
	v_lshl_add_u64 v[10:11], v[16:17], 0, v[8:9]
	global_store_dwordx4 v[16:17], v[158:161], off
	global_store_dwordx4 v[10:11], v[94:97], off
	v_cvt_pk_f16_f32 v150, v150, v151
	v_cvt_pk_f16_f32 v151, v152, v153
	v_cvt_pk_f16_f32 v152, v134, v135
	v_cvt_pk_f16_f32 v153, v136, v137
	v_cvt_pk_f16_f32 v86, v86, v87
	v_cvt_pk_f16_f32 v87, v88, v89
	v_cvt_pk_f16_f32 v88, v70, v71
	v_cvt_pk_f16_f32 v89, v72, v73
	v_mov_b32_dpp v0, v150 row_ror:8 row_mask:0xf bank_mask:0xf
	v_mov_b32_dpp v1, v151 row_ror:8 row_mask:0xf bank_mask:0xf
	v_mov_b32_dpp v2, v152 row_ror:8 row_mask:0xf bank_mask:0xf
	v_mov_b32_dpp v3, v153 row_ror:8 row_mask:0xf bank_mask:0xf
	v_mov_b32_dpp v4, v86 row_ror:8 row_mask:0xf bank_mask:0xf
	v_mov_b32_dpp v5, v87 row_ror:8 row_mask:0xf bank_mask:0xf
	v_mov_b32_dpp v6, v88 row_ror:8 row_mask:0xf bank_mask:0xf
	v_mov_b32_dpp v7, v89 row_ror:8 row_mask:0xf bank_mask:0xf
	v_cndmask_b32_e32 v150, v150, v4, vcc
	v_cndmask_b32_e32 v151, v151, v5, vcc
	v_cndmask_b32_e32 v152, v152, v6, vcc
	v_cndmask_b32_e32 v153, v153, v7, vcc
	v_cndmask_b32_e32 v86, v0, v86, vcc
	v_cndmask_b32_e32 v87, v1, v87, vcc
	v_cndmask_b32_e32 v88, v2, v88, vcc
	v_cndmask_b32_e32 v89, v3, v89, vcc
	v_lshl_add_u64 v[10:11], v[18:19], 0, v[8:9]
	global_store_dwordx4 v[18:19], v[150:153], off
	global_store_dwordx4 v[10:11], v[86:89], off
	v_cvt_pk_f16_f32 v154, v154, v155
	v_cvt_pk_f16_f32 v155, v156, v157
	v_cvt_pk_f16_f32 v156, v138, v139
	v_cvt_pk_f16_f32 v157, v140, v141
	v_cvt_pk_f16_f32 v90, v90, v91
	v_cvt_pk_f16_f32 v91, v92, v93
	v_cvt_pk_f16_f32 v92, v74, v75
	v_cvt_pk_f16_f32 v93, v76, v77
	v_mov_b32_dpp v0, v154 row_ror:8 row_mask:0xf bank_mask:0xf
	v_mov_b32_dpp v1, v155 row_ror:8 row_mask:0xf bank_mask:0xf
	v_mov_b32_dpp v2, v156 row_ror:8 row_mask:0xf bank_mask:0xf
	v_mov_b32_dpp v3, v157 row_ror:8 row_mask:0xf bank_mask:0xf
	v_mov_b32_dpp v4, v90 row_ror:8 row_mask:0xf bank_mask:0xf
	v_mov_b32_dpp v5, v91 row_ror:8 row_mask:0xf bank_mask:0xf
	v_mov_b32_dpp v6, v92 row_ror:8 row_mask:0xf bank_mask:0xf
	v_mov_b32_dpp v7, v93 row_ror:8 row_mask:0xf bank_mask:0xf
	v_cndmask_b32_e32 v154, v154, v4, vcc
	v_cndmask_b32_e32 v155, v155, v5, vcc
	v_cndmask_b32_e32 v156, v156, v6, vcc
	v_cndmask_b32_e32 v157, v157, v7, vcc
	v_cndmask_b32_e32 v90, v0, v90, vcc
	v_cndmask_b32_e32 v91, v1, v91, vcc
	v_cndmask_b32_e32 v92, v2, v92, vcc
	v_cndmask_b32_e32 v93, v3, v93, vcc
	v_lshl_add_u64 v[10:11], v[20:21], 0, v[8:9]
	global_store_dwordx4 v[20:21], v[154:157], off
	global_store_dwordx4 v[10:11], v[90:93], off
	v_cvt_pk_f16_f32 v146, v146, v147
	v_cvt_pk_f16_f32 v147, v148, v149
	v_cvt_pk_f16_f32 v148, v130, v131
	v_cvt_pk_f16_f32 v149, v132, v133
	v_cvt_pk_f16_f32 v82, v82, v83
	v_cvt_pk_f16_f32 v83, v84, v85
	v_cvt_pk_f16_f32 v84, v66, v67
	v_cvt_pk_f16_f32 v85, v68, v69
	v_mov_b32_dpp v0, v146 row_ror:8 row_mask:0xf bank_mask:0xf
	v_mov_b32_dpp v1, v147 row_ror:8 row_mask:0xf bank_mask:0xf
	v_mov_b32_dpp v2, v148 row_ror:8 row_mask:0xf bank_mask:0xf
	v_mov_b32_dpp v3, v149 row_ror:8 row_mask:0xf bank_mask:0xf
	v_mov_b32_dpp v4, v82 row_ror:8 row_mask:0xf bank_mask:0xf
	v_mov_b32_dpp v5, v83 row_ror:8 row_mask:0xf bank_mask:0xf
	v_mov_b32_dpp v6, v84 row_ror:8 row_mask:0xf bank_mask:0xf
	v_mov_b32_dpp v7, v85 row_ror:8 row_mask:0xf bank_mask:0xf
	v_cndmask_b32_e32 v146, v146, v4, vcc
	v_cndmask_b32_e32 v147, v147, v5, vcc
	v_cndmask_b32_e32 v148, v148, v6, vcc
	v_cndmask_b32_e32 v149, v149, v7, vcc
	v_cndmask_b32_e32 v82, v0, v82, vcc
	v_cndmask_b32_e32 v83, v1, v83, vcc
	v_cndmask_b32_e32 v84, v2, v84, vcc
	v_cndmask_b32_e32 v85, v3, v85, vcc
	v_lshl_add_u64 v[10:11], v[22:23], 0, v[8:9]
	global_store_dwordx4 v[22:23], v[146:149], off
	global_store_dwordx4 v[10:11], v[82:85], off
	v_cvt_pk_f16_f32 v126, v126, v127
	v_cvt_pk_f16_f32 v127, v128, v129
	v_cvt_pk_f16_f32 v128, v110, v111
	v_cvt_pk_f16_f32 v129, v112, v113
	v_cvt_pk_f16_f32 v62, v62, v63
	v_cvt_pk_f16_f32 v63, v64, v65
	v_cvt_pk_f16_f32 v64, v46, v47
	v_cvt_pk_f16_f32 v65, v48, v49
	v_mov_b32_dpp v0, v126 row_ror:8 row_mask:0xf bank_mask:0xf
	v_mov_b32_dpp v1, v127 row_ror:8 row_mask:0xf bank_mask:0xf
	v_mov_b32_dpp v2, v128 row_ror:8 row_mask:0xf bank_mask:0xf
	v_mov_b32_dpp v3, v129 row_ror:8 row_mask:0xf bank_mask:0xf
	v_mov_b32_dpp v4, v62 row_ror:8 row_mask:0xf bank_mask:0xf
	v_mov_b32_dpp v5, v63 row_ror:8 row_mask:0xf bank_mask:0xf
	v_mov_b32_dpp v6, v64 row_ror:8 row_mask:0xf bank_mask:0xf
	v_mov_b32_dpp v7, v65 row_ror:8 row_mask:0xf bank_mask:0xf
	v_cndmask_b32_e32 v126, v126, v4, vcc
	v_cndmask_b32_e32 v127, v127, v5, vcc
	v_cndmask_b32_e32 v128, v128, v6, vcc
	v_cndmask_b32_e32 v129, v129, v7, vcc
	v_cndmask_b32_e32 v62, v0, v62, vcc
	v_cndmask_b32_e32 v63, v1, v63, vcc
	v_cndmask_b32_e32 v64, v2, v64, vcc
	v_cndmask_b32_e32 v65, v3, v65, vcc
	v_lshl_add_u64 v[10:11], v[24:25], 0, v[8:9]
	global_store_dwordx4 v[24:25], v[126:129], off
	global_store_dwordx4 v[10:11], v[62:65], off
	v_cvt_pk_f16_f32 v118, v118, v119
	v_cvt_pk_f16_f32 v119, v120, v121
	v_cvt_pk_f16_f32 v120, v102, v103
	v_cvt_pk_f16_f32 v121, v104, v105
	v_cvt_pk_f16_f32 v54, v54, v55
	v_cvt_pk_f16_f32 v55, v56, v57
	v_cvt_pk_f16_f32 v56, v38, v39
	v_cvt_pk_f16_f32 v57, v40, v41
	v_mov_b32_dpp v0, v118 row_ror:8 row_mask:0xf bank_mask:0xf
	v_mov_b32_dpp v1, v119 row_ror:8 row_mask:0xf bank_mask:0xf
	v_mov_b32_dpp v2, v120 row_ror:8 row_mask:0xf bank_mask:0xf
	v_mov_b32_dpp v3, v121 row_ror:8 row_mask:0xf bank_mask:0xf
	v_mov_b32_dpp v4, v54 row_ror:8 row_mask:0xf bank_mask:0xf
	v_mov_b32_dpp v5, v55 row_ror:8 row_mask:0xf bank_mask:0xf
	v_mov_b32_dpp v6, v56 row_ror:8 row_mask:0xf bank_mask:0xf
	v_mov_b32_dpp v7, v57 row_ror:8 row_mask:0xf bank_mask:0xf
	v_cndmask_b32_e32 v118, v118, v4, vcc
	v_cndmask_b32_e32 v119, v119, v5, vcc
	v_cndmask_b32_e32 v120, v120, v6, vcc
	v_cndmask_b32_e32 v121, v121, v7, vcc
	v_cndmask_b32_e32 v54, v0, v54, vcc
	v_cndmask_b32_e32 v55, v1, v55, vcc
	v_cndmask_b32_e32 v56, v2, v56, vcc
	v_cndmask_b32_e32 v57, v3, v57, vcc
	v_lshl_add_u64 v[10:11], v[26:27], 0, v[8:9]
	global_store_dwordx4 v[26:27], v[118:121], off
	global_store_dwordx4 v[10:11], v[54:57], off
	v_cvt_pk_f16_f32 v122, v122, v123
	v_cvt_pk_f16_f32 v123, v124, v125
	v_cvt_pk_f16_f32 v124, v106, v107
	v_cvt_pk_f16_f32 v125, v108, v109
	v_cvt_pk_f16_f32 v58, v58, v59
	v_cvt_pk_f16_f32 v59, v60, v61
	v_cvt_pk_f16_f32 v60, v42, v43
	v_cvt_pk_f16_f32 v61, v44, v45
	v_mov_b32_dpp v0, v122 row_ror:8 row_mask:0xf bank_mask:0xf
	v_mov_b32_dpp v1, v123 row_ror:8 row_mask:0xf bank_mask:0xf
	v_mov_b32_dpp v2, v124 row_ror:8 row_mask:0xf bank_mask:0xf
	v_mov_b32_dpp v3, v125 row_ror:8 row_mask:0xf bank_mask:0xf
	v_mov_b32_dpp v4, v58 row_ror:8 row_mask:0xf bank_mask:0xf
	v_mov_b32_dpp v5, v59 row_ror:8 row_mask:0xf bank_mask:0xf
	v_mov_b32_dpp v6, v60 row_ror:8 row_mask:0xf bank_mask:0xf
	v_mov_b32_dpp v7, v61 row_ror:8 row_mask:0xf bank_mask:0xf
	v_cndmask_b32_e32 v122, v122, v4, vcc
	v_cndmask_b32_e32 v123, v123, v5, vcc
	v_cndmask_b32_e32 v124, v124, v6, vcc
	v_cndmask_b32_e32 v125, v125, v7, vcc
	v_cndmask_b32_e32 v58, v0, v58, vcc
	v_cndmask_b32_e32 v59, v1, v59, vcc
	v_cndmask_b32_e32 v60, v2, v60, vcc
	v_cndmask_b32_e32 v61, v3, v61, vcc
	v_lshl_add_u64 v[10:11], v[28:29], 0, v[8:9]
	global_store_dwordx4 v[28:29], v[122:125], off
	global_store_dwordx4 v[10:11], v[58:61], off
	v_cvt_pk_f16_f32 v114, v114, v115
	v_cvt_pk_f16_f32 v115, v116, v117
	v_cvt_pk_f16_f32 v116, v98, v99
	v_cvt_pk_f16_f32 v117, v100, v101
	v_cvt_pk_f16_f32 v50, v50, v51
	v_cvt_pk_f16_f32 v51, v52, v53
	v_cvt_pk_f16_f32 v52, v34, v35
	v_cvt_pk_f16_f32 v53, v36, v37
	v_mov_b32_dpp v0, v114 row_ror:8 row_mask:0xf bank_mask:0xf
	v_mov_b32_dpp v1, v115 row_ror:8 row_mask:0xf bank_mask:0xf
	v_mov_b32_dpp v2, v116 row_ror:8 row_mask:0xf bank_mask:0xf
	v_mov_b32_dpp v3, v117 row_ror:8 row_mask:0xf bank_mask:0xf
	v_mov_b32_dpp v4, v50 row_ror:8 row_mask:0xf bank_mask:0xf
	v_mov_b32_dpp v5, v51 row_ror:8 row_mask:0xf bank_mask:0xf
	v_mov_b32_dpp v6, v52 row_ror:8 row_mask:0xf bank_mask:0xf
	v_mov_b32_dpp v7, v53 row_ror:8 row_mask:0xf bank_mask:0xf
	v_cndmask_b32_e32 v114, v114, v4, vcc
	v_cndmask_b32_e32 v115, v115, v5, vcc
	v_cndmask_b32_e32 v116, v116, v6, vcc
	v_cndmask_b32_e32 v117, v117, v7, vcc
	v_cndmask_b32_e32 v50, v0, v50, vcc
	v_cndmask_b32_e32 v51, v1, v51, vcc
	v_cndmask_b32_e32 v52, v2, v52, vcc
	v_cndmask_b32_e32 v53, v3, v53, vcc
	v_lshl_add_u64 v[10:11], v[30:31], 0, v[8:9]
	global_store_dwordx4 v[30:31], v[114:117], off
	global_store_dwordx4 v[10:11], v[50:53], off
	s_mov_b64 s[4:5], 0

.LBB0_940:
	s_add_u32 s20, s14, 0x100
	s_addc_u32 s21, s15, 0
	s_add_i32 s40, 0, 0x10000
	v_add_u32_e32 v32, s40, v209
	ds_read_b128 v[132:135], v32
	ds_read_b128 v[140:143], v32 offset:2048
	ds_read_b128 v[136:139], v32 offset:1024
	ds_read_b128 v[144:147], v32 offset:3072
	s_cmp_eq_u32 s11, 12
	s_cselect_b32 s25, s17, s21
	s_cselect_b32 s24, s16, s20
	s_cselect_b32 s23, s19, s3
	s_cselect_b32 s22, s18, s1
	v_lshl_add_u64 v[34:35], s[14:15], 0, v[200:201]
	s_add_i32 m0, s30, 0xc000
	ds_read_b128 v[148:151], v211
	ds_read_b128 v[156:159], v211 offset:2048
	ds_read_b128 v[164:167], v211 offset:4096
	ds_read_b128 v[172:175], v211 offset:6144
	ds_read_b128 v[152:155], v211 offset:1024
	ds_read_b128 v[160:163], v211 offset:3072
	ds_read_b128 v[168:171], v211 offset:5120
	ds_read_b128 v[176:179], v211 offset:7168
	global_load_lds_dwordx4 v[34:35], off
	v_lshl_add_u64 v[34:35], s[14:15], 0, v[202:203]
	s_add_i32 m0, s30, 0xe000
	s_nop 0
	global_load_lds_dwordx4 v[34:35], off
	s_waitcnt lgkmcnt(8)
	s_barrier
	s_waitcnt lgkmcnt(7)
	v_mfma_f32_16x16x32_f16 v[128:131], v[132:135], v[148:151], v[128:131]
	v_mfma_f32_16x16x32_f16 v[124:127], v[140:143], v[148:151], v[124:127]
	s_waitcnt lgkmcnt(6)
	v_mfma_f32_16x16x32_f16 v[120:123], v[132:135], v[156:159], v[120:123]
	v_mfma_f32_16x16x32_f16 v[116:119], v[140:143], v[156:159], v[116:119]
	s_waitcnt lgkmcnt(5)
	v_mfma_f32_16x16x32_f16 v[112:115], v[132:135], v[164:167], v[112:115]
	v_mfma_f32_16x16x32_f16 v[108:111], v[140:143], v[164:167], v[108:111]
	s_waitcnt lgkmcnt(4)
	v_mfma_f32_16x16x32_f16 v[104:107], v[132:135], v[172:175], v[104:107]
	v_mfma_f32_16x16x32_f16 v[100:103], v[140:143], v[172:175], v[100:103]
	s_waitcnt lgkmcnt(3)
	v_mfma_f32_16x16x32_f16 v[128:131], v[136:139], v[152:155], v[128:131]
	v_mfma_f32_16x16x32_f16 v[124:127], v[144:147], v[152:155], v[124:127]
	s_waitcnt lgkmcnt(2)
	v_mfma_f32_16x16x32_f16 v[120:123], v[136:139], v[160:163], v[120:123]
	v_mfma_f32_16x16x32_f16 v[116:119], v[144:147], v[160:163], v[116:119]
	s_waitcnt lgkmcnt(1)
	v_mfma_f32_16x16x32_f16 v[112:115], v[136:139], v[168:171], v[112:115]
	v_mfma_f32_16x16x32_f16 v[108:111], v[144:147], v[168:171], v[108:111]
	s_waitcnt lgkmcnt(0)
	v_mfma_f32_16x16x32_f16 v[104:107], v[136:139], v[176:179], v[104:107]
	v_mfma_f32_16x16x32_f16 v[100:103], v[144:147], v[176:179], v[100:103]
	s_barrier
	s_add_i32 s41, 0, 0x14000
	s_add_i32 s14, s40, s29
	v_add_u32_e32 v32, s41, v209
	v_lshl_add_u64 v[204:205], s[22:23], 0, v[196:197]
	s_mov_b32 m0, s14
	ds_read_b128 v[180:183], v32
	ds_read_b128 v[188:191], v32 offset:2048
	ds_read_b128 v[184:187], v32 offset:1024
	ds_read_b128 v[192:195], v32 offset:3072
	global_load_lds_dwordx4 v[204:205], off
	v_lshl_add_u64 v[206:207], s[22:23], 0, v[198:199]
	s_add_i32 m0, s14, 0x2000
	s_nop 0
	global_load_lds_dwordx4 v[206:207], off
	s_barrier
	s_waitcnt lgkmcnt(2)
	v_mfma_f32_16x16x32_f16 v[96:99], v[180:183], v[148:151], v[96:99]
	v_mfma_f32_16x16x32_f16 v[92:95], v[188:191], v[148:151], v[92:95]
	v_mfma_f32_16x16x32_f16 v[88:91], v[180:183], v[156:159], v[88:91]
	v_mfma_f32_16x16x32_f16 v[84:87], v[188:191], v[156:159], v[84:87]
	v_mfma_f32_16x16x32_f16 v[80:83], v[180:183], v[164:167], v[80:83]
	v_mfma_f32_16x16x32_f16 v[76:79], v[188:191], v[164:167], v[76:79]
	v_mfma_f32_16x16x32_f16 v[72:75], v[180:183], v[172:175], v[72:75]
	v_mfma_f32_16x16x32_f16 v[68:71], v[188:191], v[172:175], v[68:71]
	s_waitcnt lgkmcnt(0)
	v_mfma_f32_16x16x32_f16 v[96:99], v[184:187], v[152:155], v[96:99]
	v_mfma_f32_16x16x32_f16 v[92:95], v[192:195], v[152:155], v[92:95]
	v_mfma_f32_16x16x32_f16 v[88:91], v[184:187], v[160:163], v[88:91]
	v_mfma_f32_16x16x32_f16 v[84:87], v[192:195], v[160:163], v[84:87]
	v_mfma_f32_16x16x32_f16 v[80:83], v[184:187], v[168:171], v[80:83]
	v_mfma_f32_16x16x32_f16 v[76:79], v[192:195], v[168:171], v[76:79]
	v_mfma_f32_16x16x32_f16 v[72:75], v[184:187], v[176:179], v[72:75]
	v_mfma_f32_16x16x32_f16 v[68:71], v[192:195], v[176:179], v[68:71]
	s_mov_b32 m0, s30
	v_lshl_add_u64 v[212:213], s[24:25], 0, v[196:197]
	s_barrier
	ds_read_b128 v[148:151], v211 offset:16384
	ds_read_b128 v[156:159], v211 offset:18432
	ds_read_b128 v[164:167], v211 offset:20480
	ds_read_b128 v[172:175], v211 offset:22528
	ds_read_b128 v[152:155], v211 offset:17408
	ds_read_b128 v[160:163], v211 offset:19456
	ds_read_b128 v[168:171], v211 offset:21504
	ds_read_b128 v[176:179], v211 offset:23552
	global_load_lds_dwordx4 v[212:213], off
	v_lshl_add_u64 v[214:215], s[24:25], 0, v[198:199]
	s_mov_b32 m0, s31
	s_nop 0
	global_load_lds_dwordx4 v[214:215], off
	s_barrier
	s_waitcnt lgkmcnt(7)
	v_mfma_f32_16x16x32_f16 v[64:67], v[132:135], v[148:151], v[64:67]
	v_mfma_f32_16x16x32_f16 v[60:63], v[140:143], v[148:151], v[60:63]
	s_waitcnt lgkmcnt(6)
	v_mfma_f32_16x16x32_f16 v[56:59], v[132:135], v[156:159], v[56:59]
	v_mfma_f32_16x16x32_f16 v[52:55], v[140:143], v[156:159], v[52:55]
	s_waitcnt lgkmcnt(5)
	v_mfma_f32_16x16x32_f16 v[48:51], v[132:135], v[164:167], v[48:51]
	v_mfma_f32_16x16x32_f16 v[44:47], v[140:143], v[164:167], v[44:47]
	s_waitcnt lgkmcnt(4)
	v_mfma_f32_16x16x32_f16 v[40:43], v[132:135], v[172:175], v[40:43]
	v_mfma_f32_16x16x32_f16 v[34:37], v[140:143], v[172:175], v[36:39]
	s_waitcnt lgkmcnt(3)
	v_mfma_f32_16x16x32_f16 v[64:67], v[136:139], v[152:155], v[64:67]
	v_mfma_f32_16x16x32_f16 v[60:63], v[144:147], v[152:155], v[60:63]
	s_waitcnt lgkmcnt(2)
	v_mfma_f32_16x16x32_f16 v[56:59], v[136:139], v[160:163], v[56:59]
	v_mfma_f32_16x16x32_f16 v[52:55], v[144:147], v[160:163], v[52:55]
	s_waitcnt lgkmcnt(1)
	v_mfma_f32_16x16x32_f16 v[48:51], v[136:139], v[168:171], v[48:51]
	v_mfma_f32_16x16x32_f16 v[44:47], v[144:147], v[168:171], v[44:47]
	s_waitcnt lgkmcnt(0)
	v_mfma_f32_16x16x32_f16 v[40:43], v[136:139], v[176:179], v[40:43]
	v_mfma_f32_16x16x32_f16 v[34:37], v[144:147], v[176:179], v[34:37]
	s_barrier
	s_add_u32 s14, s22, 0x40000
	s_addc_u32 s15, s23, 0
	s_add_i32 s40, s41, s29
	v_lshl_add_u64 v[38:39], s[14:15], 0, v[196:197]
	s_mov_b32 m0, s40
	s_nop 0
	global_load_lds_dwordx4 v[38:39], off
	v_lshl_add_u64 v[38:39], s[14:15], 0, v[198:199]
	s_add_i32 m0, s40, 0x2000
	s_nop 0
	global_load_lds_dwordx4 v[38:39], off
	s_waitcnt vmcnt(6)
	s_barrier
	v_mfma_f32_16x16x32_f16 v[28:31], v[180:183], v[148:151], v[28:31]
	v_mfma_f32_16x16x32_f16 v[24:27], v[188:191], v[148:151], v[24:27]
	v_mfma_f32_16x16x32_f16 v[20:23], v[180:183], v[156:159], v[20:23]
	v_mfma_f32_16x16x32_f16 v[16:19], v[188:191], v[156:159], v[16:19]
	v_mfma_f32_16x16x32_f16 v[12:15], v[180:183], v[164:167], v[12:15]
	v_mfma_f32_16x16x32_f16 v[8:11], v[188:191], v[164:167], v[8:11]
	v_mfma_f32_16x16x32_f16 v[4:7], v[180:183], v[172:175], v[4:7]
	v_mfma_f32_16x16x32_f16 v[0:3], v[188:191], v[172:175], v[0:3]
	v_mfma_f32_16x16x32_f16 v[28:31], v[184:187], v[152:155], v[28:31]
	v_mfma_f32_16x16x32_f16 v[24:27], v[192:195], v[152:155], v[24:27]
	v_mfma_f32_16x16x32_f16 v[20:23], v[184:187], v[160:163], v[20:23]
	v_mfma_f32_16x16x32_f16 v[16:19], v[192:195], v[160:163], v[16:19]
	v_mfma_f32_16x16x32_f16 v[12:15], v[184:187], v[168:171], v[12:15]
	v_mfma_f32_16x16x32_f16 v[8:11], v[192:195], v[168:171], v[8:11]
	v_mfma_f32_16x16x32_f16 v[4:7], v[184:187], v[176:179], v[4:7]
	v_mfma_f32_16x16x32_f16 v[0:3], v[192:195], v[176:179], v[0:3]
	s_add_i32 s40, 0, 0x18000
	v_add_u32_e32 v32, s40, v209
	s_barrier
	ds_read_b128 v[132:135], v32
	ds_read_b128 v[140:143], v32 offset:2048
	ds_read_b128 v[136:139], v32 offset:1024
	ds_read_b128 v[144:147], v32 offset:3072
	s_add_u32 s14, s24, 0x40000
	s_addc_u32 s15, s25, 0
	s_mov_b32 m0, s34
	v_lshl_add_u64 v[38:39], s[14:15], 0, v[196:197]
	ds_read_b128 v[148:151], v211 offset:32768
	ds_read_b128 v[156:159], v211 offset:34816
	ds_read_b128 v[164:167], v211 offset:36864
	ds_read_b128 v[172:175], v211 offset:38912
	ds_read_b128 v[152:155], v211 offset:33792
	ds_read_b128 v[160:163], v211 offset:35840
	ds_read_b128 v[168:171], v211 offset:37888
	ds_read_b128 v[176:179], v211 offset:39936
	global_load_lds_dwordx4 v[38:39], off
	v_lshl_add_u64 v[38:39], s[14:15], 0, v[198:199]
	s_mov_b32 m0, s35
	s_nop 0
	global_load_lds_dwordx4 v[38:39], off
	s_waitcnt lgkmcnt(8)
	s_barrier
	s_waitcnt lgkmcnt(7)
	v_mfma_f32_16x16x32_f16 v[128:131], v[132:135], v[148:151], v[128:131]
	v_mfma_f32_16x16x32_f16 v[124:127], v[140:143], v[148:151], v[124:127]
	s_waitcnt lgkmcnt(6)
	v_mfma_f32_16x16x32_f16 v[120:123], v[132:135], v[156:159], v[120:123]
	v_mfma_f32_16x16x32_f16 v[116:119], v[140:143], v[156:159], v[116:119]
	s_waitcnt lgkmcnt(5)
	v_mfma_f32_16x16x32_f16 v[112:115], v[132:135], v[164:167], v[112:115]
	v_mfma_f32_16x16x32_f16 v[108:111], v[140:143], v[164:167], v[108:111]
	s_waitcnt lgkmcnt(4)
	v_mfma_f32_16x16x32_f16 v[104:107], v[132:135], v[172:175], v[104:107]
	v_mfma_f32_16x16x32_f16 v[100:103], v[140:143], v[172:175], v[100:103]
	s_waitcnt lgkmcnt(3)
	v_mfma_f32_16x16x32_f16 v[128:131], v[136:139], v[152:155], v[128:131]
	v_mfma_f32_16x16x32_f16 v[124:127], v[144:147], v[152:155], v[124:127]
	s_waitcnt lgkmcnt(2)
	v_mfma_f32_16x16x32_f16 v[120:123], v[136:139], v[160:163], v[120:123]
	v_mfma_f32_16x16x32_f16 v[116:119], v[144:147], v[160:163], v[116:119]
	s_waitcnt lgkmcnt(1)
	v_mfma_f32_16x16x32_f16 v[112:115], v[136:139], v[168:171], v[112:115]
	v_mfma_f32_16x16x32_f16 v[108:111], v[144:147], v[168:171], v[108:111]
	s_waitcnt lgkmcnt(0)
	v_mfma_f32_16x16x32_f16 v[104:107], v[136:139], v[176:179], v[104:107]
	v_mfma_f32_16x16x32_f16 v[100:103], v[144:147], v[176:179], v[100:103]
	s_barrier
	s_add_i32 s24, 0, 0x1c000
	s_add_i32 s14, s40, s29
	v_add_u32_e32 v32, s24, v209
	v_lshl_add_u64 v[38:39], v[204:205], 0, s[84:85]
	s_mov_b32 m0, s14
	ds_read_b128 v[180:183], v32
	ds_read_b128 v[188:191], v32 offset:2048
	ds_read_b128 v[184:187], v32 offset:1024
	ds_read_b128 v[192:195], v32 offset:3072
	global_load_lds_dwordx4 v[38:39], off
	v_lshl_add_u64 v[38:39], v[206:207], 0, s[84:85]
	s_add_i32 m0, s14, 0x2000
	s_nop 0
	global_load_lds_dwordx4 v[38:39], off
	s_barrier
	s_waitcnt lgkmcnt(2)
	v_mfma_f32_16x16x32_f16 v[96:99], v[180:183], v[148:151], v[96:99]
	v_mfma_f32_16x16x32_f16 v[92:95], v[188:191], v[148:151], v[92:95]
	v_mfma_f32_16x16x32_f16 v[88:91], v[180:183], v[156:159], v[88:91]
	v_mfma_f32_16x16x32_f16 v[84:87], v[188:191], v[156:159], v[84:87]
	v_mfma_f32_16x16x32_f16 v[80:83], v[180:183], v[164:167], v[80:83]
	v_mfma_f32_16x16x32_f16 v[76:79], v[188:191], v[164:167], v[76:79]
	v_mfma_f32_16x16x32_f16 v[72:75], v[180:183], v[172:175], v[72:75]
	v_mfma_f32_16x16x32_f16 v[68:71], v[188:191], v[172:175], v[68:71]
	s_waitcnt lgkmcnt(0)
	v_mfma_f32_16x16x32_f16 v[96:99], v[184:187], v[152:155], v[96:99]
	v_mfma_f32_16x16x32_f16 v[92:95], v[192:195], v[152:155], v[92:95]
	v_mfma_f32_16x16x32_f16 v[88:91], v[184:187], v[160:163], v[88:91]
	v_mfma_f32_16x16x32_f16 v[84:87], v[192:195], v[160:163], v[84:87]
	v_mfma_f32_16x16x32_f16 v[80:83], v[184:187], v[168:171], v[80:83]
	v_mfma_f32_16x16x32_f16 v[76:79], v[192:195], v[168:171], v[76:79]
	v_mfma_f32_16x16x32_f16 v[72:75], v[184:187], v[176:179], v[72:75]
	v_mfma_f32_16x16x32_f16 v[68:71], v[192:195], v[176:179], v[68:71]
	s_mov_b32 m0, s36
	v_lshl_add_u64 v[38:39], v[212:213], 0, s[84:85]
	s_barrier
	ds_read_b128 v[148:151], v211 offset:49152
	ds_read_b128 v[156:159], v211 offset:51200
	ds_read_b128 v[164:167], v211 offset:53248
	ds_read_b128 v[172:175], v211 offset:55296
	ds_read_b128 v[152:155], v211 offset:50176
	ds_read_b128 v[160:163], v211 offset:52224
	ds_read_b128 v[168:171], v211 offset:54272
	ds_read_b128 v[176:179], v211 offset:56320
	global_load_lds_dwordx4 v[38:39], off
	v_lshl_add_u64 v[38:39], v[214:215], 0, s[84:85]
	s_mov_b32 m0, s37
	s_nop 0
	global_load_lds_dwordx4 v[38:39], off
	s_barrier
	s_waitcnt lgkmcnt(7)
	v_mfma_f32_16x16x32_f16 v[64:67], v[132:135], v[148:151], v[64:67]
	v_mfma_f32_16x16x32_f16 v[60:63], v[140:143], v[148:151], v[60:63]
	s_waitcnt lgkmcnt(6)
	v_mfma_f32_16x16x32_f16 v[56:59], v[132:135], v[156:159], v[56:59]
	v_mfma_f32_16x16x32_f16 v[52:55], v[140:143], v[156:159], v[52:55]
	s_waitcnt lgkmcnt(5)
	v_mfma_f32_16x16x32_f16 v[48:51], v[132:135], v[164:167], v[48:51]
	v_mfma_f32_16x16x32_f16 v[44:47], v[140:143], v[164:167], v[44:47]
	s_waitcnt lgkmcnt(4)
	v_mfma_f32_16x16x32_f16 v[38:41], v[132:135], v[172:175], v[40:43]
	v_mfma_f32_16x16x32_f16 v[34:37], v[140:143], v[172:175], v[34:37]
	s_waitcnt lgkmcnt(3)
	v_mfma_f32_16x16x32_f16 v[64:67], v[136:139], v[152:155], v[64:67]
	v_mfma_f32_16x16x32_f16 v[60:63], v[144:147], v[152:155], v[60:63]
	s_waitcnt lgkmcnt(2)
	v_mfma_f32_16x16x32_f16 v[56:59], v[136:139], v[160:163], v[56:59]
	v_mfma_f32_16x16x32_f16 v[52:55], v[144:147], v[160:163], v[52:55]
	s_waitcnt lgkmcnt(1)
	v_mfma_f32_16x16x32_f16 v[48:51], v[136:139], v[168:171], v[48:51]
	v_mfma_f32_16x16x32_f16 v[44:47], v[144:147], v[168:171], v[44:47]
	s_waitcnt lgkmcnt(0)
	v_mfma_f32_16x16x32_f16 v[40:43], v[136:139], v[176:179], v[38:41]
	v_mfma_f32_16x16x32_f16 v[36:39], v[144:147], v[176:179], v[34:37]
	s_barrier
	s_add_u32 s14, s22, 0x40080
	s_addc_u32 s15, s23, 0
	s_add_i32 s22, s24, s29
	v_lshl_add_u64 v[34:35], s[14:15], 0, v[196:197]
	s_mov_b32 m0, s22
	s_nop 0
	global_load_lds_dwordx4 v[34:35], off
	v_lshl_add_u64 v[34:35], s[14:15], 0, v[198:199]
	s_add_i32 m0, s22, 0x2000
	s_nop 0
	global_load_lds_dwordx4 v[34:35], off
	s_waitcnt vmcnt(6)
	s_barrier
	v_mfma_f32_16x16x32_f16 v[28:31], v[180:183], v[148:151], v[28:31]
	v_mfma_f32_16x16x32_f16 v[24:27], v[188:191], v[148:151], v[24:27]
	v_mfma_f32_16x16x32_f16 v[20:23], v[180:183], v[156:159], v[20:23]
	v_mfma_f32_16x16x32_f16 v[16:19], v[188:191], v[156:159], v[16:19]
	v_mfma_f32_16x16x32_f16 v[12:15], v[180:183], v[164:167], v[12:15]
	v_mfma_f32_16x16x32_f16 v[8:11], v[188:191], v[164:167], v[8:11]
	v_mfma_f32_16x16x32_f16 v[4:7], v[180:183], v[172:175], v[4:7]
	v_mfma_f32_16x16x32_f16 v[0:3], v[188:191], v[172:175], v[0:3]
	v_mfma_f32_16x16x32_f16 v[28:31], v[184:187], v[152:155], v[28:31]
	v_mfma_f32_16x16x32_f16 v[24:27], v[192:195], v[152:155], v[24:27]
	v_mfma_f32_16x16x32_f16 v[20:23], v[184:187], v[160:163], v[20:23]
	v_mfma_f32_16x16x32_f16 v[16:19], v[192:195], v[160:163], v[16:19]
	v_mfma_f32_16x16x32_f16 v[12:15], v[184:187], v[168:171], v[12:15]
	v_mfma_f32_16x16x32_f16 v[8:11], v[192:195], v[168:171], v[8:11]
	v_mfma_f32_16x16x32_f16 v[4:7], v[184:187], v[176:179], v[4:7]
	v_mfma_f32_16x16x32_f16 v[0:3], v[192:195], v[176:179], v[0:3]
	s_add_i32 s11, s11, 2
	s_add_u32 s1, s1, 0x100
	s_addc_u32 s3, s3, 0
	s_cmp_gt_u32 s11, 13
	s_mov_b64 s[14:15], s[20:21]
	s_barrier
	s_cbranch_scc0 .LBB0_940
	v_lshl_add_u32 v34, s12, 8, v208
	v_lshl_or_b32 v156, s10, 8, v210
	s_cmp_lg_u32 s13, 0
	s_cselect_b64 s[10:11], -1, 0
	s_cmp_eq_u32 s13, 0
	v_ashrrev_i32_e32 v157, 31, v156
	v_ashrrev_i32_e32 v35, 31, v34
	v_mad_i64_i32 v[158:159], s[12:13], v34, s33, 0
	v_or_b32_e32 v160, 16, v34
	v_or_b32_e32 v162, 32, v34
	v_or_b32_e32 v164, 48, v34
	s_cbranch_scc1 .LBB0_946
	v_lshl_add_u64 v[132:133], s[70:71], 0, v[158:159]
	v_lshlrev_b64 v[166:167], 1, v[156:157]
	v_lshl_add_u64 v[132:133], v[132:133], 0, v[166:167]
	s_mov_b64 s[16:17], 0x2800
	v_mov_b64_e32 v[168:169], s[70:71]
	s_movk_i32 s1, 0x2000
	v_lshl_add_u64 v[134:135], v[132:133], 0, s[16:17]
	v_mad_i64_i32 v[136:137], s[12:13], v160, s33, v[168:169]
	v_add_co_u32_e32 v132, vcc, s1, v132
	v_lshl_add_u64 v[136:137], v[136:137], 0, v[166:167]
	s_nop 0
	v_addc_co_u32_e32 v133, vcc, 0, v133, vcc
	v_lshl_add_u64 v[138:139], v[136:137], 0, s[16:17]
	v_mad_i64_i32 v[140:141], s[12:13], v162, s33, v[168:169]
	v_add_co_u32_e32 v136, vcc, s1, v136
	v_lshl_add_u64 v[140:141], v[140:141], 0, v[166:167]
	s_nop 0
	v_addc_co_u32_e32 v137, vcc, 0, v137, vcc
	v_mad_i64_i32 v[144:145], s[12:13], v164, s33, v[168:169]
	global_load_dwordx4 v[170:173], v[132:133], off offset:2048
	global_load_dwordx4 v[152:155], v[136:137], off offset:2048
	global_load_dwordx4 v[174:177], v[134:135], off offset:256
	global_load_dwordx4 v[148:151], v[138:139], off offset:256
	v_add_co_u32_e32 v132, vcc, s1, v140
	v_lshl_add_u64 v[144:145], v[144:145], 0, v[166:167]
	s_nop 0
	v_addc_co_u32_e32 v133, vcc, 0, v141, vcc
	v_add_co_u32_e32 v134, vcc, s1, v144
	v_lshl_add_u64 v[142:143], v[140:141], 0, s[16:17]
	s_nop 0
	v_addc_co_u32_e32 v135, vcc, 0, v145, vcc
	v_lshl_add_u64 v[178:179], v[144:145], 0, s[16:17]
	global_load_dwordx4 v[144:147], v[132:133], off offset:2048
	global_load_dwordx4 v[136:139], v[134:135], off offset:2048
	s_nop 0
	global_load_dwordx4 v[140:143], v[142:143], off offset:256
	s_nop 0
	global_load_dwordx4 v[132:135], v[178:179], off offset:256
	v_ashrrev_i32_e32 v161, 31, v160
	v_ashrrev_i32_e32 v163, 31, v162
	v_ashrrev_i32_e32 v165, 31, v164
	s_waitcnt vmcnt(0)
	v_cvt_f32_f16_e32 v32, v170
	v_cvt_f32_f16_sdwa v170, v170 dst_sel:DWORD dst_unused:UNUSED_PAD src0_sel:WORD_1
	v_lshlrev_b64 v[178:179], 11, v[34:35]
	v_readlane_b32 s14, v252, 9
	v_max_f32_e32 v32, 0xc1f00000, v32
	v_max_f32_e32 v35, 0xc1f00000, v170
	v_cvt_f32_f16_e32 v170, v171
	v_cvt_f32_f16_sdwa v171, v171 dst_sel:DWORD dst_unused:UNUSED_PAD src0_sel:WORD_1
	v_mul_f32_e32 v35, 0xbfb8aa3b, v35
	v_exp_f32_e32 v35, v35
	v_max_f32_e32 v170, 0xc1f00000, v170
	v_mul_f32_e32 v170, 0xbfb8aa3b, v170
	v_exp_f32_e32 v180, v170
	v_max_f32_e32 v170, 0xc1f00000, v171
	v_mul_f32_e32 v170, 0xbfb8aa3b, v170
	v_cvt_f32_f16_e32 v171, v172
	v_exp_f32_e32 v181, v170
	v_cvt_f32_f16_sdwa v170, v172 dst_sel:DWORD dst_unused:UNUSED_PAD src0_sel:WORD_1
	v_mul_f32_e32 v32, 0xbfb8aa3b, v32
	v_max_f32_e32 v171, 0xc1f00000, v171
	v_mul_f32_e32 v171, 0xbfb8aa3b, v171
	v_max_f32_e32 v170, 0xc1f00000, v170
	v_mul_f32_e32 v170, 0xbfb8aa3b, v170
	v_exp_f32_e32 v182, v171
	v_cvt_f32_f16_e32 v171, v173
	v_exp_f32_e32 v183, v170
	v_cvt_f32_f16_sdwa v170, v173 dst_sel:DWORD dst_unused:UNUSED_PAD src0_sel:WORD_1
	v_exp_f32_e32 v32, v32
	v_max_f32_e32 v171, 0xc1f00000, v171
	v_mul_f32_e32 v171, 0xbfb8aa3b, v171
	v_max_f32_e32 v170, 0xc1f00000, v170
	v_mul_f32_e32 v170, 0xbfb8aa3b, v170
	v_add_f32_e32 v35, 1.0, v35
	v_exp_f32_e32 v184, v171
	v_exp_f32_e32 v185, v170
	v_rcp_f32_e32 v170, v35
	v_add_f32_e32 v35, 1.0, v180
	v_rcp_f32_e32 v171, v35
	v_add_f32_e32 v35, 1.0, v181
	v_add_f32_e32 v32, 1.0, v32
	v_rcp_f32_e32 v172, v35
	v_add_f32_e32 v35, 1.0, v182
	v_rcp_f32_e32 v32, v32
	v_rcp_f32_e32 v173, v35
	v_add_f32_e32 v35, 1.0, v183
	v_rcp_f32_e32 v180, v35
	v_add_f32_e32 v35, 1.0, v184
	v_rcp_f32_e32 v181, v35
	v_mov_b32_e32 v182, v129
	v_mov_b32_e32 v183, v130
	v_pk_mul_f32 v[170:171], v[182:183], v[170:171]
	v_pk_mov_b32 v[182:183], v[130:131], v[124:125] op_sel:[1,0]
	v_add_f32_e32 v35, 1.0, v185
	v_fma_mixlo_f16 v32, v128, v32, 0
	v_cvt_pk_f16_f32 v171, v170, v171
	v_pk_mul_f32 v[172:173], v[182:183], v[172:173]
	v_rcp_f32_e32 v35, v35
	v_pack_b32_f16 v170, v32, v171
	v_cvt_pk_f16_f32 v32, v172, v173
	v_mov_b32_e32 v172, v125
	v_mov_b32_e32 v173, v126
	v_pk_mul_f32 v[172:173], v[172:173], v[180:181]
	v_readlane_b32 s15, v252, 10
	v_cvt_pk_f16_f32 v173, v172, v173
	v_alignbit_b32 v172, v173, v32, 16
	v_lshrrev_b32_e32 v173, 16, v173
	v_lshl_add_u64 v[178:179], s[14:15], 0, v[178:179]
	v_alignbit_b32 v171, v32, v171, 16
	v_fma_mixhi_f16 v173, v127, v35, 0
	v_lshl_add_u64 v[178:179], v[178:179], 0, v[166:167]
	global_store_dwordx4 v[178:179], v[170:173], off
	v_cvt_f32_f16_sdwa v35, v174 dst_sel:DWORD dst_unused:UNUSED_PAD src0_sel:WORD_1
	v_cvt_f32_f16_e32 v32, v174
	v_cvt_f32_f16_e32 v170, v175
	v_cvt_f32_f16_sdwa v171, v175 dst_sel:DWORD dst_unused:UNUSED_PAD src0_sel:WORD_1
	v_max_f32_e32 v35, 0xc1f00000, v35
	v_mul_f32_e32 v35, 0xbfb8aa3b, v35
	v_max_f32_e32 v170, 0xc1f00000, v170
	v_mul_f32_e32 v170, 0xbfb8aa3b, v170
	v_exp_f32_e32 v172, v170
	v_max_f32_e32 v170, 0xc1f00000, v171
	v_mul_f32_e32 v170, 0xbfb8aa3b, v170
	v_cvt_f32_f16_e32 v171, v176
	v_exp_f32_e32 v173, v170
	v_cvt_f32_f16_sdwa v170, v176 dst_sel:DWORD dst_unused:UNUSED_PAD src0_sel:WORD_1
	v_exp_f32_e32 v35, v35
	v_max_f32_e32 v171, 0xc1f00000, v171
	v_mul_f32_e32 v171, 0xbfb8aa3b, v171
	v_max_f32_e32 v170, 0xc1f00000, v170
	v_mul_f32_e32 v170, 0xbfb8aa3b, v170
	v_exp_f32_e32 v174, v171
	v_cvt_f32_f16_e32 v171, v177
	v_exp_f32_e32 v175, v170
	v_cvt_f32_f16_sdwa v170, v177 dst_sel:DWORD dst_unused:UNUSED_PAD src0_sel:WORD_1
	v_max_f32_e32 v32, 0xc1f00000, v32
	v_mul_f32_e32 v32, 0xbfb8aa3b, v32
	v_exp_f32_e32 v32, v32
	v_max_f32_e32 v171, 0xc1f00000, v171
	v_max_f32_e32 v170, 0xc1f00000, v170
	v_mul_f32_e32 v171, 0xbfb8aa3b, v171
	v_mul_f32_e32 v170, 0xbfb8aa3b, v170
	v_add_f32_e32 v35, 1.0, v35
	v_exp_f32_e32 v176, v171
	v_exp_f32_e32 v177, v170
	v_rcp_f32_e32 v170, v35
	v_add_f32_e32 v35, 1.0, v172
	v_rcp_f32_e32 v171, v35
	v_add_f32_e32 v35, 1.0, v173
	v_add_f32_e32 v32, 1.0, v32
	v_rcp_f32_e32 v172, v35
	v_add_f32_e32 v35, 1.0, v174
	v_rcp_f32_e32 v32, v32
	v_rcp_f32_e32 v173, v35
	v_add_f32_e32 v35, 1.0, v175
	v_rcp_f32_e32 v174, v35
	v_add_f32_e32 v35, 1.0, v176
	v_rcp_f32_e32 v175, v35
	v_add_f32_e32 v35, 1.0, v177
	v_mov_b32_e32 v176, v97
	v_mov_b32_e32 v177, v98
	v_pk_mul_f32 v[170:171], v[176:177], v[170:171]
	v_pk_mov_b32 v[176:177], v[98:99], v[92:93] op_sel:[1,0]
	v_fma_mixlo_f16 v32, v96, v32, 0
	v_cvt_pk_f16_f32 v171, v170, v171
	v_pk_mul_f32 v[172:173], v[176:177], v[172:173]
	v_rcp_f32_e32 v35, v35
	v_pack_b32_f16 v170, v32, v171
	v_cvt_pk_f16_f32 v32, v172, v173
	v_mov_b32_e32 v172, v93
	v_mov_b32_e32 v173, v94
	v_pk_mul_f32 v[172:173], v[172:173], v[174:175]
	v_alignbit_b32 v171, v32, v171, 16
	v_cvt_pk_f16_f32 v173, v172, v173
	v_alignbit_b32 v172, v173, v32, 16
	v_lshrrev_b32_e32 v173, 16, v173
	v_fma_mixhi_f16 v173, v95, v35, 0
	v_cvt_f32_f16_e32 v32, v152
	v_cvt_f32_f16_sdwa v35, v152 dst_sel:DWORD dst_unused:UNUSED_PAD src0_sel:WORD_1
	v_cvt_f32_f16_e32 v152, v153
	v_cvt_f32_f16_sdwa v153, v153 dst_sel:DWORD dst_unused:UNUSED_PAD src0_sel:WORD_1
	global_store_dwordx4 v[178:179], v[170:173], off offset:256
	v_max_f32_e32 v35, 0xc1f00000, v35
	v_max_f32_e32 v152, 0xc1f00000, v152
	v_mul_f32_e32 v152, 0xbfb8aa3b, v152
	v_lshlrev_b64 v[170:171], 11, v[160:161]
	v_exp_f32_e32 v161, v152
	v_max_f32_e32 v152, 0xc1f00000, v153
	v_mul_f32_e32 v152, 0xbfb8aa3b, v152
	v_cvt_f32_f16_e32 v153, v154
	v_exp_f32_e32 v172, v152
	v_cvt_f32_f16_sdwa v152, v154 dst_sel:DWORD dst_unused:UNUSED_PAD src0_sel:WORD_1
	v_mul_f32_e32 v35, 0xbfb8aa3b, v35
	v_max_f32_e32 v153, 0xc1f00000, v153
	v_mul_f32_e32 v153, 0xbfb8aa3b, v153
	v_max_f32_e32 v152, 0xc1f00000, v152
	v_mul_f32_e32 v152, 0xbfb8aa3b, v152
	v_exp_f32_e32 v173, v153
	v_cvt_f32_f16_e32 v153, v155
	v_exp_f32_e32 v174, v152
	v_cvt_f32_f16_sdwa v152, v155 dst_sel:DWORD dst_unused:UNUSED_PAD src0_sel:WORD_1
	v_exp_f32_e32 v35, v35
	v_max_f32_e32 v32, 0xc1f00000, v32
	v_mul_f32_e32 v32, 0xbfb8aa3b, v32
	v_exp_f32_e32 v32, v32
	v_max_f32_e32 v153, 0xc1f00000, v153
	v_max_f32_e32 v152, 0xc1f00000, v152
	v_mul_f32_e32 v153, 0xbfb8aa3b, v153
	v_mul_f32_e32 v152, 0xbfb8aa3b, v152
	v_add_f32_e32 v35, 1.0, v35
	v_exp_f32_e32 v175, v153
	v_exp_f32_e32 v176, v152
	v_rcp_f32_e32 v152, v35
	v_add_f32_e32 v35, 1.0, v161
	v_rcp_f32_e32 v153, v35
	v_add_f32_e32 v35, 1.0, v172
	v_add_f32_e32 v32, 1.0, v32
	v_rcp_f32_e32 v154, v35
	v_add_f32_e32 v35, 1.0, v173
	v_rcp_f32_e32 v32, v32
	v_rcp_f32_e32 v155, v35
	v_add_f32_e32 v35, 1.0, v174
	v_rcp_f32_e32 v172, v35
	v_add_f32_e32 v35, 1.0, v175
	v_rcp_f32_e32 v173, v35
	v_mov_b32_e32 v174, v121
	v_mov_b32_e32 v175, v122
	v_pk_mul_f32 v[152:153], v[174:175], v[152:153]
	v_pk_mov_b32 v[174:175], v[122:123], v[116:117] op_sel:[1,0]
	v_add_f32_e32 v35, 1.0, v176
	v_fma_mixlo_f16 v32, v120, v32, 0
	v_cvt_pk_f16_f32 v153, v152, v153
	v_pk_mul_f32 v[154:155], v[174:175], v[154:155]
	v_rcp_f32_e32 v35, v35
	v_pack_b32_f16 v152, v32, v153
	v_cvt_pk_f16_f32 v32, v154, v155
	v_mov_b32_e32 v154, v117
	v_mov_b32_e32 v155, v118
	v_pk_mul_f32 v[154:155], v[154:155], v[172:173]
	v_alignbit_b32 v153, v32, v153, 16
	v_cvt_pk_f16_f32 v155, v154, v155
	v_alignbit_b32 v154, v155, v32, 16
	v_lshrrev_b32_e32 v155, 16, v155
	v_fma_mixhi_f16 v155, v119, v35, 0
	v_cvt_f32_f16_e32 v32, v148
	v_cvt_f32_f16_sdwa v35, v148 dst_sel:DWORD dst_unused:UNUSED_PAD src0_sel:WORD_1
	v_cvt_f32_f16_e32 v148, v149
	v_cvt_f32_f16_sdwa v149, v149 dst_sel:DWORD dst_unused:UNUSED_PAD src0_sel:WORD_1
	v_lshl_add_u64 v[170:171], s[14:15], 0, v[170:171]
	v_lshl_add_u64 v[170:171], v[170:171], 0, v[166:167]
	v_max_f32_e32 v148, 0xc1f00000, v148
	v_mul_f32_e32 v148, 0xbfb8aa3b, v148
	global_store_dwordx4 v[170:171], v[152:155], off
	v_max_f32_e32 v35, 0xc1f00000, v35
	v_mul_f32_e32 v35, 0xbfb8aa3b, v35
	v_exp_f32_e32 v152, v148
	v_max_f32_e32 v148, 0xc1f00000, v149
	v_mul_f32_e32 v148, 0xbfb8aa3b, v148
	v_cvt_f32_f16_e32 v149, v150
	v_exp_f32_e32 v153, v148
	v_cvt_f32_f16_sdwa v148, v150 dst_sel:DWORD dst_unused:UNUSED_PAD src0_sel:WORD_1
	v_exp_f32_e32 v35, v35
	v_max_f32_e32 v149, 0xc1f00000, v149
	v_mul_f32_e32 v149, 0xbfb8aa3b, v149
	v_max_f32_e32 v148, 0xc1f00000, v148
	v_mul_f32_e32 v148, 0xbfb8aa3b, v148
	v_exp_f32_e32 v154, v149
	v_cvt_f32_f16_e32 v149, v151
	v_exp_f32_e32 v155, v148
	v_cvt_f32_f16_sdwa v148, v151 dst_sel:DWORD dst_unused:UNUSED_PAD src0_sel:WORD_1
	v_max_f32_e32 v32, 0xc1f00000, v32
	v_mul_f32_e32 v32, 0xbfb8aa3b, v32
	v_exp_f32_e32 v32, v32
	v_max_f32_e32 v149, 0xc1f00000, v149
	v_max_f32_e32 v148, 0xc1f00000, v148
	v_mul_f32_e32 v149, 0xbfb8aa3b, v149
	v_mul_f32_e32 v148, 0xbfb8aa3b, v148
	v_add_f32_e32 v35, 1.0, v35
	v_exp_f32_e32 v161, v149
	v_exp_f32_e32 v172, v148
	v_rcp_f32_e32 v148, v35
	v_add_f32_e32 v35, 1.0, v152
	v_rcp_f32_e32 v149, v35
	v_add_f32_e32 v35, 1.0, v153
	v_add_f32_e32 v32, 1.0, v32
	v_rcp_f32_e32 v150, v35
	v_add_f32_e32 v35, 1.0, v154
	v_rcp_f32_e32 v32, v32
	v_rcp_f32_e32 v151, v35
	v_add_f32_e32 v35, 1.0, v155
	v_rcp_f32_e32 v152, v35
	v_add_f32_e32 v35, 1.0, v161
	v_rcp_f32_e32 v153, v35
	v_mov_b32_e32 v154, v89
	v_mov_b32_e32 v155, v90
	v_pk_mul_f32 v[148:149], v[154:155], v[148:149]
	v_pk_mov_b32 v[154:155], v[90:91], v[84:85] op_sel:[1,0]
	v_add_f32_e32 v35, 1.0, v172
	v_fma_mixlo_f16 v32, v88, v32, 0
	v_cvt_pk_f16_f32 v149, v148, v149
	v_pk_mul_f32 v[150:151], v[154:155], v[150:151]
	v_rcp_f32_e32 v35, v35
	v_pack_b32_f16 v148, v32, v149
	v_cvt_pk_f16_f32 v32, v150, v151
	v_mov_b32_e32 v150, v85
	v_mov_b32_e32 v151, v86
	v_pk_mul_f32 v[150:151], v[150:151], v[152:153]
	v_alignbit_b32 v149, v32, v149, 16
	v_cvt_pk_f16_f32 v151, v150, v151
	v_alignbit_b32 v150, v151, v32, 16
	v_lshrrev_b32_e32 v151, 16, v151
	v_fma_mixhi_f16 v151, v87, v35, 0
	v_cvt_f32_f16_e32 v32, v144
	v_cvt_f32_f16_sdwa v35, v144 dst_sel:DWORD dst_unused:UNUSED_PAD src0_sel:WORD_1
	v_cvt_f32_f16_e32 v144, v145
	v_cvt_f32_f16_sdwa v145, v145 dst_sel:DWORD dst_unused:UNUSED_PAD src0_sel:WORD_1
	global_store_dwordx4 v[170:171], v[148:151], off offset:256
	v_max_f32_e32 v35, 0xc1f00000, v35
	v_max_f32_e32 v144, 0xc1f00000, v144
	v_mul_f32_e32 v144, 0xbfb8aa3b, v144
	v_exp_f32_e32 v150, v144
	v_max_f32_e32 v144, 0xc1f00000, v145
	v_mul_f32_e32 v144, 0xbfb8aa3b, v144
	v_cvt_f32_f16_e32 v145, v146
	v_exp_f32_e32 v151, v144
	v_cvt_f32_f16_sdwa v144, v146 dst_sel:DWORD dst_unused:UNUSED_PAD src0_sel:WORD_1
	v_mul_f32_e32 v35, 0xbfb8aa3b, v35
	v_max_f32_e32 v145, 0xc1f00000, v145
	v_mul_f32_e32 v145, 0xbfb8aa3b, v145
	v_max_f32_e32 v144, 0xc1f00000, v144
	v_mul_f32_e32 v144, 0xbfb8aa3b, v144
	v_exp_f32_e32 v152, v145
	v_cvt_f32_f16_e32 v145, v147
	v_exp_f32_e32 v153, v144
	v_cvt_f32_f16_sdwa v144, v147 dst_sel:DWORD dst_unused:UNUSED_PAD src0_sel:WORD_1
	v_exp_f32_e32 v35, v35
	v_max_f32_e32 v32, 0xc1f00000, v32
	v_mul_f32_e32 v32, 0xbfb8aa3b, v32
	v_exp_f32_e32 v32, v32
	v_max_f32_e32 v145, 0xc1f00000, v145
	v_max_f32_e32 v144, 0xc1f00000, v144
	v_mul_f32_e32 v145, 0xbfb8aa3b, v145
	v_mul_f32_e32 v144, 0xbfb8aa3b, v144
	v_add_f32_e32 v35, 1.0, v35
	v_exp_f32_e32 v154, v145
	v_exp_f32_e32 v155, v144
	v_rcp_f32_e32 v144, v35
	v_add_f32_e32 v35, 1.0, v150
	v_rcp_f32_e32 v145, v35
	v_add_f32_e32 v35, 1.0, v151
	v_add_f32_e32 v32, 1.0, v32
	v_rcp_f32_e32 v146, v35
	v_add_f32_e32 v35, 1.0, v152
	v_rcp_f32_e32 v32, v32
	v_rcp_f32_e32 v147, v35
	v_add_f32_e32 v35, 1.0, v153
	v_rcp_f32_e32 v150, v35
	v_add_f32_e32 v35, 1.0, v154
	v_rcp_f32_e32 v151, v35
	v_mov_b32_e32 v152, v113
	v_mov_b32_e32 v153, v114
	v_pk_mul_f32 v[144:145], v[152:153], v[144:145]
	v_pk_mov_b32 v[152:153], v[114:115], v[108:109] op_sel:[1,0]
	v_add_f32_e32 v35, 1.0, v155
	v_fma_mixlo_f16 v32, v112, v32, 0
	v_cvt_pk_f16_f32 v145, v144, v145
	v_pk_mul_f32 v[146:147], v[152:153], v[146:147]
	v_rcp_f32_e32 v35, v35
	v_pack_b32_f16 v144, v32, v145
	v_cvt_pk_f16_f32 v32, v146, v147
	v_mov_b32_e32 v146, v109
	v_mov_b32_e32 v147, v110
	v_pk_mul_f32 v[146:147], v[146:147], v[150:151]
	v_alignbit_b32 v145, v32, v145, 16
	v_cvt_pk_f16_f32 v147, v146, v147
	v_alignbit_b32 v146, v147, v32, 16
	v_lshrrev_b32_e32 v147, 16, v147
	v_fma_mixhi_f16 v147, v111, v35, 0
	v_cvt_f32_f16_e32 v32, v140
	v_cvt_f32_f16_sdwa v35, v140 dst_sel:DWORD dst_unused:UNUSED_PAD src0_sel:WORD_1
	v_cvt_f32_f16_e32 v140, v141
	v_cvt_f32_f16_sdwa v141, v141 dst_sel:DWORD dst_unused:UNUSED_PAD src0_sel:WORD_1
	v_lshlrev_b64 v[148:149], 11, v[162:163]
	v_lshl_add_u64 v[148:149], s[14:15], 0, v[148:149]
	v_max_f32_e32 v140, 0xc1f00000, v140
	v_lshl_add_u64 v[148:149], v[148:149], 0, v[166:167]
	v_mul_f32_e32 v140, 0xbfb8aa3b, v140
	global_store_dwordx4 v[148:149], v[144:147], off
	v_max_f32_e32 v35, 0xc1f00000, v35
	v_mul_f32_e32 v35, 0xbfb8aa3b, v35
	v_exp_f32_e32 v144, v140
	v_max_f32_e32 v140, 0xc1f00000, v141
	v_mul_f32_e32 v140, 0xbfb8aa3b, v140
	v_cvt_f32_f16_e32 v141, v142
	v_exp_f32_e32 v145, v140
	v_cvt_f32_f16_sdwa v140, v142 dst_sel:DWORD dst_unused:UNUSED_PAD src0_sel:WORD_1
	v_exp_f32_e32 v35, v35
	v_max_f32_e32 v141, 0xc1f00000, v141
	v_mul_f32_e32 v141, 0xbfb8aa3b, v141
	v_max_f32_e32 v140, 0xc1f00000, v140
	v_mul_f32_e32 v140, 0xbfb8aa3b, v140
	v_exp_f32_e32 v146, v141
	v_cvt_f32_f16_e32 v141, v143
	v_exp_f32_e32 v147, v140
	v_cvt_f32_f16_sdwa v140, v143 dst_sel:DWORD dst_unused:UNUSED_PAD src0_sel:WORD_1
	v_max_f32_e32 v32, 0xc1f00000, v32
	v_mul_f32_e32 v32, 0xbfb8aa3b, v32
	v_exp_f32_e32 v32, v32
	v_max_f32_e32 v141, 0xc1f00000, v141
	v_max_f32_e32 v140, 0xc1f00000, v140
	v_mul_f32_e32 v141, 0xbfb8aa3b, v141
	v_mul_f32_e32 v140, 0xbfb8aa3b, v140
	v_add_f32_e32 v35, 1.0, v35
	v_exp_f32_e32 v150, v141
	v_exp_f32_e32 v151, v140
	v_rcp_f32_e32 v140, v35
	v_add_f32_e32 v35, 1.0, v144
	v_rcp_f32_e32 v141, v35
	v_add_f32_e32 v35, 1.0, v145
	v_add_f32_e32 v32, 1.0, v32
	v_rcp_f32_e32 v142, v35
	v_add_f32_e32 v35, 1.0, v146
	v_rcp_f32_e32 v32, v32
	v_rcp_f32_e32 v143, v35
	v_add_f32_e32 v35, 1.0, v147
	v_rcp_f32_e32 v144, v35
	v_add_f32_e32 v35, 1.0, v150
	v_rcp_f32_e32 v145, v35
	v_mov_b32_e32 v146, v81
	v_mov_b32_e32 v147, v82
	v_pk_mul_f32 v[140:141], v[146:147], v[140:141]
	v_pk_mov_b32 v[146:147], v[82:83], v[76:77] op_sel:[1,0]
	v_add_f32_e32 v35, 1.0, v151
	v_fma_mixlo_f16 v32, v80, v32, 0
	v_cvt_pk_f16_f32 v141, v140, v141
	v_pk_mul_f32 v[142:143], v[146:147], v[142:143]
	v_rcp_f32_e32 v35, v35
	v_pack_b32_f16 v140, v32, v141
	v_cvt_pk_f16_f32 v32, v142, v143
	v_mov_b32_e32 v142, v77
	v_mov_b32_e32 v143, v78
	v_pk_mul_f32 v[142:143], v[142:143], v[144:145]
	v_alignbit_b32 v141, v32, v141, 16
	v_cvt_pk_f16_f32 v143, v142, v143
	v_alignbit_b32 v142, v143, v32, 16
	v_lshrrev_b32_e32 v143, 16, v143
	v_fma_mixhi_f16 v143, v79, v35, 0
	v_cvt_f32_f16_e32 v32, v136
	v_cvt_f32_f16_sdwa v35, v136 dst_sel:DWORD dst_unused:UNUSED_PAD src0_sel:WORD_1
	v_cvt_f32_f16_e32 v136, v137
	v_cvt_f32_f16_sdwa v137, v137 dst_sel:DWORD dst_unused:UNUSED_PAD src0_sel:WORD_1
	global_store_dwordx4 v[148:149], v[140:143], off offset:256
	v_max_f32_e32 v35, 0xc1f00000, v35
	v_max_f32_e32 v136, 0xc1f00000, v136
	v_mul_f32_e32 v136, 0xbfb8aa3b, v136
	v_exp_f32_e32 v142, v136
	v_max_f32_e32 v136, 0xc1f00000, v137
	v_mul_f32_e32 v136, 0xbfb8aa3b, v136
	v_cvt_f32_f16_e32 v137, v138
	v_exp_f32_e32 v143, v136
	v_cvt_f32_f16_sdwa v136, v138 dst_sel:DWORD dst_unused:UNUSED_PAD src0_sel:WORD_1
	v_mul_f32_e32 v35, 0xbfb8aa3b, v35
	v_max_f32_e32 v137, 0xc1f00000, v137
	v_mul_f32_e32 v137, 0xbfb8aa3b, v137
	v_max_f32_e32 v136, 0xc1f00000, v136
	v_mul_f32_e32 v136, 0xbfb8aa3b, v136
	v_exp_f32_e32 v144, v137
	v_cvt_f32_f16_e32 v137, v139
	v_exp_f32_e32 v145, v136
	v_cvt_f32_f16_sdwa v136, v139 dst_sel:DWORD dst_unused:UNUSED_PAD src0_sel:WORD_1
	v_exp_f32_e32 v35, v35
	v_max_f32_e32 v32, 0xc1f00000, v32
	v_mul_f32_e32 v32, 0xbfb8aa3b, v32
	v_exp_f32_e32 v32, v32
	v_max_f32_e32 v137, 0xc1f00000, v137
	v_max_f32_e32 v136, 0xc1f00000, v136
	v_mul_f32_e32 v137, 0xbfb8aa3b, v137
	v_mul_f32_e32 v136, 0xbfb8aa3b, v136
	v_add_f32_e32 v35, 1.0, v35
	v_exp_f32_e32 v146, v137
	v_exp_f32_e32 v147, v136
	v_rcp_f32_e32 v136, v35
	v_add_f32_e32 v35, 1.0, v142
	v_rcp_f32_e32 v137, v35
	v_add_f32_e32 v35, 1.0, v143
	v_add_f32_e32 v32, 1.0, v32
	v_rcp_f32_e32 v138, v35
	v_add_f32_e32 v35, 1.0, v144
	v_rcp_f32_e32 v32, v32
	v_rcp_f32_e32 v139, v35
	v_add_f32_e32 v35, 1.0, v145
	v_rcp_f32_e32 v142, v35
	v_add_f32_e32 v35, 1.0, v146
	v_rcp_f32_e32 v143, v35
	v_mov_b32_e32 v144, v105
	v_mov_b32_e32 v145, v106
	v_pk_mul_f32 v[136:137], v[144:145], v[136:137]
	v_pk_mov_b32 v[144:145], v[106:107], v[100:101] op_sel:[1,0]
	v_add_f32_e32 v35, 1.0, v147
	v_fma_mixlo_f16 v32, v104, v32, 0
	v_cvt_pk_f16_f32 v137, v136, v137
	v_pk_mul_f32 v[138:139], v[144:145], v[138:139]
	v_rcp_f32_e32 v35, v35
	v_pack_b32_f16 v136, v32, v137
	v_cvt_pk_f16_f32 v32, v138, v139
	v_mov_b32_e32 v138, v101
	v_mov_b32_e32 v139, v102
	v_pk_mul_f32 v[138:139], v[138:139], v[142:143]
	v_alignbit_b32 v137, v32, v137, 16
	v_cvt_pk_f16_f32 v139, v138, v139
	v_alignbit_b32 v138, v139, v32, 16
	v_lshrrev_b32_e32 v139, 16, v139
	v_fma_mixhi_f16 v139, v103, v35, 0
	v_cvt_f32_f16_e32 v32, v132
	v_cvt_f32_f16_sdwa v35, v132 dst_sel:DWORD dst_unused:UNUSED_PAD src0_sel:WORD_1
	v_cvt_f32_f16_e32 v132, v133
	v_cvt_f32_f16_sdwa v133, v133 dst_sel:DWORD dst_unused:UNUSED_PAD src0_sel:WORD_1
	v_lshlrev_b64 v[140:141], 11, v[164:165]
	v_lshl_add_u64 v[140:141], s[14:15], 0, v[140:141]
	v_max_f32_e32 v132, 0xc1f00000, v132
	v_lshl_add_u64 v[140:141], v[140:141], 0, v[166:167]
	v_mul_f32_e32 v132, 0xbfb8aa3b, v132
	global_store_dwordx4 v[140:141], v[136:139], off
	v_max_f32_e32 v35, 0xc1f00000, v35
	v_mul_f32_e32 v35, 0xbfb8aa3b, v35
	v_exp_f32_e32 v136, v132
	v_max_f32_e32 v132, 0xc1f00000, v133
	v_mul_f32_e32 v132, 0xbfb8aa3b, v132
	v_cvt_f32_f16_e32 v133, v134
	v_exp_f32_e32 v137, v132
	v_cvt_f32_f16_sdwa v132, v134 dst_sel:DWORD dst_unused:UNUSED_PAD src0_sel:WORD_1
	v_exp_f32_e32 v35, v35
	v_max_f32_e32 v133, 0xc1f00000, v133
	v_mul_f32_e32 v133, 0xbfb8aa3b, v133
	v_max_f32_e32 v132, 0xc1f00000, v132
	v_mul_f32_e32 v132, 0xbfb8aa3b, v132
	v_exp_f32_e32 v138, v133
	v_cvt_f32_f16_e32 v133, v135
	v_exp_f32_e32 v139, v132
	v_cvt_f32_f16_sdwa v132, v135 dst_sel:DWORD dst_unused:UNUSED_PAD src0_sel:WORD_1
	v_max_f32_e32 v32, 0xc1f00000, v32
	v_mul_f32_e32 v32, 0xbfb8aa3b, v32
	v_exp_f32_e32 v32, v32
	v_max_f32_e32 v133, 0xc1f00000, v133
	v_max_f32_e32 v132, 0xc1f00000, v132
	v_mul_f32_e32 v133, 0xbfb8aa3b, v133
	v_mul_f32_e32 v132, 0xbfb8aa3b, v132
	v_add_f32_e32 v35, 1.0, v35
	v_exp_f32_e32 v142, v133
	v_exp_f32_e32 v143, v132
	v_rcp_f32_e32 v132, v35
	v_add_f32_e32 v35, 1.0, v136
	v_rcp_f32_e32 v133, v35
	v_add_f32_e32 v35, 1.0, v137
	v_add_f32_e32 v32, 1.0, v32
	v_rcp_f32_e32 v134, v35
	v_add_f32_e32 v35, 1.0, v138
	v_rcp_f32_e32 v32, v32
	v_rcp_f32_e32 v135, v35
	v_add_f32_e32 v35, 1.0, v139
	v_rcp_f32_e32 v136, v35
	v_add_f32_e32 v35, 1.0, v142
	v_rcp_f32_e32 v137, v35
	v_mov_b32_e32 v138, v73
	v_mov_b32_e32 v139, v74
	v_pk_mul_f32 v[132:133], v[138:139], v[132:133]
	v_pk_mov_b32 v[138:139], v[74:75], v[68:69] op_sel:[1,0]
	v_add_f32_e32 v35, 1.0, v143
	v_fma_mixlo_f16 v32, v72, v32, 0
	v_cvt_pk_f16_f32 v133, v132, v133
	v_pk_mul_f32 v[134:135], v[138:139], v[134:135]
	v_rcp_f32_e32 v35, v35
	v_pack_b32_f16 v132, v32, v133
	v_cvt_pk_f16_f32 v32, v134, v135
	v_mov_b32_e32 v134, v69
	v_mov_b32_e32 v135, v70
	v_pk_mul_f32 v[134:135], v[134:135], v[136:137]
	v_alignbit_b32 v133, v32, v133, 16
	v_cvt_pk_f16_f32 v135, v134, v135
	v_alignbit_b32 v134, v135, v32, 16
	v_lshrrev_b32_e32 v135, 16, v135
	v_fma_mixhi_f16 v135, v71, v35, 0
	global_store_dwordx4 v[140:141], v[132:135], off offset:256
	v_add_u32_e32 v184, 0x80, v34
	s_nop 0
	v_mad_i64_i32 v[132:133], s[12:13], v184, s33, v[168:169]
	v_lshl_add_u64 v[132:133], v[132:133], 0, v[166:167]
	v_add_u32_e32 v174, 0x90, v34
	v_lshl_add_u64 v[134:135], v[132:133], 0, s[16:17]
	v_mad_i64_i32 v[136:137], s[12:13], v174, s33, v[168:169]
	v_add_co_u32_e32 v132, vcc, s1, v132
	v_lshl_add_u64 v[136:137], v[136:137], 0, v[166:167]
	v_add_u32_e32 v172, 0xa0, v34
	v_addc_co_u32_e32 v133, vcc, 0, v133, vcc
	v_lshl_add_u64 v[138:139], v[136:137], 0, s[16:17]
	v_mad_i64_i32 v[140:141], s[12:13], v172, s33, v[168:169]
	v_add_co_u32_e32 v136, vcc, s1, v136
	v_lshl_add_u64 v[140:141], v[140:141], 0, v[166:167]
	v_add_u32_e32 v170, 0xb0, v34
	v_addc_co_u32_e32 v137, vcc, 0, v137, vcc
	v_mad_i64_i32 v[144:145], s[12:13], v170, s33, v[168:169]
	global_load_dwordx4 v[176:179], v[132:133], off offset:2048
	global_load_dwordx4 v[152:155], v[136:137], off offset:2048
	global_load_dwordx4 v[180:183], v[134:135], off offset:256
	global_load_dwordx4 v[148:151], v[138:139], off offset:256
	v_add_co_u32_e32 v132, vcc, s1, v140
	v_lshl_add_u64 v[144:145], v[144:145], 0, v[166:167]
	s_nop 0
	v_addc_co_u32_e32 v133, vcc, 0, v141, vcc
	v_add_co_u32_e32 v134, vcc, s1, v144
	v_lshl_add_u64 v[142:143], v[140:141], 0, s[16:17]
	s_nop 0
	v_addc_co_u32_e32 v135, vcc, 0, v145, vcc
	v_lshl_add_u64 v[168:169], v[144:145], 0, s[16:17]
	global_load_dwordx4 v[144:147], v[132:133], off offset:2048
	global_load_dwordx4 v[136:139], v[134:135], off offset:2048
	s_nop 0
	global_load_dwordx4 v[140:143], v[142:143], off offset:256
	s_nop 0
	global_load_dwordx4 v[132:135], v[168:169], off offset:256
	v_ashrrev_i32_e32 v185, 31, v184
	v_ashrrev_i32_e32 v175, 31, v174
	v_ashrrev_i32_e32 v173, 31, v172
	v_ashrrev_i32_e32 v171, 31, v170
	s_waitcnt vmcnt(0)
	v_cvt_f32_f16_e32 v32, v176
	v_cvt_f32_f16_sdwa v35, v176 dst_sel:DWORD dst_unused:UNUSED_PAD src0_sel:WORD_1
	v_cvt_f32_f16_sdwa v176, v178 dst_sel:DWORD dst_unused:UNUSED_PAD src0_sel:WORD_1
	v_cvt_f32_f16_e32 v161, v177
	v_cvt_f32_f16_sdwa v163, v177 dst_sel:DWORD dst_unused:UNUSED_PAD src0_sel:WORD_1
	v_cvt_f32_f16_e32 v165, v178
	v_max_f32_e32 v176, 0xc1f00000, v176
	v_max_f32_e32 v35, 0xc1f00000, v35
	v_mul_f32_e32 v176, 0xbfb8aa3b, v176
	v_lshlrev_b64 v[168:169], 11, v[184:185]
	v_mul_f32_e32 v35, 0xbfb8aa3b, v35
	v_max_f32_e32 v161, 0xc1f00000, v161
	v_cvt_f32_f16_e32 v177, v179
	v_exp_f32_e32 v184, v176
	v_cvt_f32_f16_sdwa v176, v179 dst_sel:DWORD dst_unused:UNUSED_PAD src0_sel:WORD_1
	v_exp_f32_e32 v35, v35
	v_mul_f32_e32 v161, 0xbfb8aa3b, v161
	v_max_f32_e32 v163, 0xc1f00000, v163
	v_max_f32_e32 v32, 0xc1f00000, v32
	v_exp_f32_e32 v161, v161
	v_mul_f32_e32 v163, 0xbfb8aa3b, v163
	v_max_f32_e32 v165, 0xc1f00000, v165
	v_mul_f32_e32 v32, 0xbfb8aa3b, v32
	v_exp_f32_e32 v163, v163
	v_mul_f32_e32 v165, 0xbfb8aa3b, v165
	v_exp_f32_e32 v32, v32
	v_exp_f32_e32 v165, v165
	v_max_f32_e32 v177, 0xc1f00000, v177
	v_max_f32_e32 v176, 0xc1f00000, v176
	v_mul_f32_e32 v177, 0xbfb8aa3b, v177
	v_mul_f32_e32 v176, 0xbfb8aa3b, v176
	v_add_f32_e32 v35, 1.0, v35
	v_exp_f32_e32 v185, v177
	v_exp_f32_e32 v186, v176
	v_rcp_f32_e32 v176, v35
	v_add_f32_e32 v35, 1.0, v161
	v_rcp_f32_e32 v177, v35
	v_add_f32_e32 v35, 1.0, v163
	v_add_f32_e32 v32, 1.0, v32
	v_rcp_f32_e32 v178, v35
	v_add_f32_e32 v35, 1.0, v165
	v_rcp_f32_e32 v32, v32
	v_rcp_f32_e32 v179, v35
	v_add_f32_e32 v35, 1.0, v184
	v_rcp_f32_e32 v184, v35
	v_add_f32_e32 v35, 1.0, v185
	v_rcp_f32_e32 v185, v35
	v_add_f32_e32 v35, 1.0, v186
	v_mov_b32_e32 v186, v65
	v_mov_b32_e32 v187, v66
	v_pk_mul_f32 v[176:177], v[186:187], v[176:177]
	v_pk_mov_b32 v[186:187], v[66:67], v[60:61] op_sel:[1,0]
	v_fma_mixlo_f16 v32, v64, v32, 0
	v_cvt_pk_f16_f32 v161, v176, v177
	v_pk_mul_f32 v[178:179], v[186:187], v[178:179]
	v_rcp_f32_e32 v35, v35
	v_pack_b32_f16 v176, v32, v161
	v_cvt_pk_f16_f32 v32, v178, v179
	v_mov_b32_e32 v178, v61
	v_mov_b32_e32 v179, v62
	v_pk_mul_f32 v[178:179], v[178:179], v[184:185]
	v_alignbit_b32 v177, v32, v161, 16
	v_cvt_pk_f16_f32 v161, v178, v179
	v_lshrrev_b32_e32 v179, 16, v161
	v_lshl_add_u64 v[168:169], s[14:15], 0, v[168:169]
	v_alignbit_b32 v178, v161, v32, 16
	v_fma_mixhi_f16 v179, v63, v35, 0
	v_lshl_add_u64 v[168:169], v[168:169], 0, v[166:167]
	global_store_dwordx4 v[168:169], v[176:179], off
	v_cvt_f32_f16_sdwa v35, v180 dst_sel:DWORD dst_unused:UNUSED_PAD src0_sel:WORD_1
	v_cvt_f32_f16_e32 v161, v181
	v_cvt_f32_f16_sdwa v176, v182 dst_sel:DWORD dst_unused:UNUSED_PAD src0_sel:WORD_1
	v_cvt_f32_f16_sdwa v163, v181 dst_sel:DWORD dst_unused:UNUSED_PAD src0_sel:WORD_1
	v_cvt_f32_f16_e32 v32, v180
	v_cvt_f32_f16_e32 v165, v182
	v_max_f32_e32 v176, 0xc1f00000, v176
	v_max_f32_e32 v35, 0xc1f00000, v35
	v_mul_f32_e32 v176, 0xbfb8aa3b, v176
	v_mul_f32_e32 v35, 0xbfb8aa3b, v35
	v_max_f32_e32 v161, 0xc1f00000, v161
	v_cvt_f32_f16_e32 v177, v183
	v_exp_f32_e32 v180, v176
	v_cvt_f32_f16_sdwa v176, v183 dst_sel:DWORD dst_unused:UNUSED_PAD src0_sel:WORD_1
	v_exp_f32_e32 v35, v35
	v_mul_f32_e32 v161, 0xbfb8aa3b, v161
	v_max_f32_e32 v163, 0xc1f00000, v163
	v_max_f32_e32 v32, 0xc1f00000, v32
	v_exp_f32_e32 v161, v161
	v_mul_f32_e32 v163, 0xbfb8aa3b, v163
	v_max_f32_e32 v165, 0xc1f00000, v165
	v_mul_f32_e32 v32, 0xbfb8aa3b, v32
	v_exp_f32_e32 v163, v163
	v_mul_f32_e32 v165, 0xbfb8aa3b, v165
	v_exp_f32_e32 v32, v32
	v_exp_f32_e32 v165, v165
	v_max_f32_e32 v177, 0xc1f00000, v177
	v_max_f32_e32 v176, 0xc1f00000, v176
	v_mul_f32_e32 v177, 0xbfb8aa3b, v177
	v_mul_f32_e32 v176, 0xbfb8aa3b, v176
	v_add_f32_e32 v35, 1.0, v35
	v_exp_f32_e32 v181, v177
	v_exp_f32_e32 v182, v176
	v_rcp_f32_e32 v176, v35
	v_add_f32_e32 v35, 1.0, v161
	v_rcp_f32_e32 v177, v35
	v_add_f32_e32 v35, 1.0, v163
	v_add_f32_e32 v32, 1.0, v32
	v_rcp_f32_e32 v178, v35
	v_add_f32_e32 v35, 1.0, v165
	v_rcp_f32_e32 v32, v32
	v_rcp_f32_e32 v179, v35
	v_add_f32_e32 v35, 1.0, v180
	v_rcp_f32_e32 v180, v35
	v_add_f32_e32 v35, 1.0, v181
	v_rcp_f32_e32 v181, v35
	v_add_f32_e32 v35, 1.0, v182
	v_mov_b32_e32 v182, v29
	v_mov_b32_e32 v183, v30
	v_pk_mul_f32 v[176:177], v[182:183], v[176:177]
	v_pk_mov_b32 v[182:183], v[30:31], v[24:25] op_sel:[1,0]
	v_fma_mixlo_f16 v32, v28, v32, 0
	v_cvt_pk_f16_f32 v161, v176, v177
	v_pk_mul_f32 v[178:179], v[182:183], v[178:179]
	v_rcp_f32_e32 v35, v35
	v_pack_b32_f16 v176, v32, v161
	v_cvt_pk_f16_f32 v32, v178, v179
	v_mov_b32_e32 v178, v25
	v_mov_b32_e32 v179, v26
	v_pk_mul_f32 v[178:179], v[178:179], v[180:181]
	v_alignbit_b32 v177, v32, v161, 16
	v_cvt_pk_f16_f32 v161, v178, v179
	v_lshrrev_b32_e32 v179, 16, v161
	v_alignbit_b32 v178, v161, v32, 16
	v_fma_mixhi_f16 v179, v27, v35, 0
	v_cvt_f32_f16_e32 v32, v152
	v_cvt_f32_f16_sdwa v35, v152 dst_sel:DWORD dst_unused:UNUSED_PAD src0_sel:WORD_1
	v_cvt_f32_f16_e32 v152, v153
	v_cvt_f32_f16_sdwa v153, v153 dst_sel:DWORD dst_unused:UNUSED_PAD src0_sel:WORD_1
	global_store_dwordx4 v[168:169], v[176:179], off offset:256
	v_max_f32_e32 v35, 0xc1f00000, v35
	v_max_f32_e32 v152, 0xc1f00000, v152
	v_mul_f32_e32 v152, 0xbfb8aa3b, v152
	v_exp_f32_e32 v161, v152
	v_max_f32_e32 v152, 0xc1f00000, v153
	v_mul_f32_e32 v152, 0xbfb8aa3b, v152
	v_cvt_f32_f16_e32 v153, v154
	v_exp_f32_e32 v163, v152
	v_cvt_f32_f16_sdwa v152, v154 dst_sel:DWORD dst_unused:UNUSED_PAD src0_sel:WORD_1
	v_lshlrev_b64 v[168:169], 11, v[174:175]
	v_max_f32_e32 v153, 0xc1f00000, v153
	v_mul_f32_e32 v153, 0xbfb8aa3b, v153
	v_max_f32_e32 v152, 0xc1f00000, v152
	v_mul_f32_e32 v152, 0xbfb8aa3b, v152
	v_mul_f32_e32 v35, 0xbfb8aa3b, v35
	v_exp_f32_e32 v165, v153
	v_cvt_f32_f16_e32 v153, v155
	v_exp_f32_e32 v174, v152
	v_cvt_f32_f16_sdwa v152, v155 dst_sel:DWORD dst_unused:UNUSED_PAD src0_sel:WORD_1
	v_exp_f32_e32 v35, v35
	v_max_f32_e32 v32, 0xc1f00000, v32
	v_mul_f32_e32 v32, 0xbfb8aa3b, v32
	v_exp_f32_e32 v32, v32
	v_max_f32_e32 v153, 0xc1f00000, v153
	v_max_f32_e32 v152, 0xc1f00000, v152
	v_mul_f32_e32 v153, 0xbfb8aa3b, v153
	v_mul_f32_e32 v152, 0xbfb8aa3b, v152
	v_add_f32_e32 v35, 1.0, v35
	v_exp_f32_e32 v175, v153
	v_exp_f32_e32 v176, v152
	v_rcp_f32_e32 v152, v35
	v_add_f32_e32 v35, 1.0, v161
	v_rcp_f32_e32 v153, v35
	v_add_f32_e32 v35, 1.0, v163
	v_add_f32_e32 v32, 1.0, v32
	v_rcp_f32_e32 v154, v35
	v_add_f32_e32 v35, 1.0, v165
	v_rcp_f32_e32 v32, v32
	v_rcp_f32_e32 v155, v35
	v_add_f32_e32 v35, 1.0, v174
	v_rcp_f32_e32 v174, v35
	v_add_f32_e32 v35, 1.0, v175
	v_rcp_f32_e32 v175, v35
	v_add_f32_e32 v35, 1.0, v176
	v_mov_b32_e32 v176, v57
	v_mov_b32_e32 v177, v58
	v_pk_mul_f32 v[152:153], v[176:177], v[152:153]
	v_pk_mov_b32 v[176:177], v[58:59], v[52:53] op_sel:[1,0]
	v_fma_mixlo_f16 v32, v56, v32, 0
	v_cvt_pk_f16_f32 v153, v152, v153
	v_pk_mul_f32 v[154:155], v[176:177], v[154:155]
	v_rcp_f32_e32 v35, v35
	v_pack_b32_f16 v152, v32, v153
	v_cvt_pk_f16_f32 v32, v154, v155
	v_mov_b32_e32 v154, v53
	v_mov_b32_e32 v155, v54
	v_pk_mul_f32 v[154:155], v[154:155], v[174:175]
	v_alignbit_b32 v153, v32, v153, 16
	v_cvt_pk_f16_f32 v155, v154, v155
	v_alignbit_b32 v154, v155, v32, 16
	v_lshrrev_b32_e32 v155, 16, v155
	v_fma_mixhi_f16 v155, v55, v35, 0
	v_cvt_f32_f16_e32 v32, v148
	v_cvt_f32_f16_sdwa v35, v148 dst_sel:DWORD dst_unused:UNUSED_PAD src0_sel:WORD_1
	v_cvt_f32_f16_e32 v148, v149
	v_cvt_f32_f16_sdwa v149, v149 dst_sel:DWORD dst_unused:UNUSED_PAD src0_sel:WORD_1
	v_lshl_add_u64 v[168:169], s[14:15], 0, v[168:169]
	v_lshl_add_u64 v[168:169], v[168:169], 0, v[166:167]
	v_max_f32_e32 v148, 0xc1f00000, v148
	v_mul_f32_e32 v148, 0xbfb8aa3b, v148
	global_store_dwordx4 v[168:169], v[152:155], off
	v_max_f32_e32 v35, 0xc1f00000, v35
	v_mul_f32_e32 v35, 0xbfb8aa3b, v35
	v_exp_f32_e32 v152, v148
	v_max_f32_e32 v148, 0xc1f00000, v149
	v_mul_f32_e32 v148, 0xbfb8aa3b, v148
	v_cvt_f32_f16_e32 v149, v150
	v_exp_f32_e32 v153, v148
	v_cvt_f32_f16_sdwa v148, v150 dst_sel:DWORD dst_unused:UNUSED_PAD src0_sel:WORD_1
	v_exp_f32_e32 v35, v35
	v_max_f32_e32 v149, 0xc1f00000, v149
	v_mul_f32_e32 v149, 0xbfb8aa3b, v149
	v_max_f32_e32 v148, 0xc1f00000, v148
	v_mul_f32_e32 v148, 0xbfb8aa3b, v148
	v_exp_f32_e32 v154, v149
	v_cvt_f32_f16_e32 v149, v151
	v_exp_f32_e32 v155, v148
	v_cvt_f32_f16_sdwa v148, v151 dst_sel:DWORD dst_unused:UNUSED_PAD src0_sel:WORD_1
	v_max_f32_e32 v32, 0xc1f00000, v32
	v_mul_f32_e32 v32, 0xbfb8aa3b, v32
	v_exp_f32_e32 v32, v32
	v_max_f32_e32 v149, 0xc1f00000, v149
	v_max_f32_e32 v148, 0xc1f00000, v148
	v_mul_f32_e32 v149, 0xbfb8aa3b, v149
	v_mul_f32_e32 v148, 0xbfb8aa3b, v148
	v_add_f32_e32 v35, 1.0, v35
	v_exp_f32_e32 v161, v149
	v_exp_f32_e32 v163, v148
	v_rcp_f32_e32 v148, v35
	v_add_f32_e32 v35, 1.0, v152
	v_rcp_f32_e32 v149, v35
	v_add_f32_e32 v35, 1.0, v153
	v_add_f32_e32 v32, 1.0, v32
	v_rcp_f32_e32 v150, v35
	v_add_f32_e32 v35, 1.0, v154
	v_rcp_f32_e32 v32, v32
	v_rcp_f32_e32 v151, v35
	v_add_f32_e32 v35, 1.0, v155
	v_rcp_f32_e32 v152, v35
	v_add_f32_e32 v35, 1.0, v161
	v_rcp_f32_e32 v153, v35
	v_mov_b32_e32 v154, v21
	v_mov_b32_e32 v155, v22
	v_pk_mul_f32 v[148:149], v[154:155], v[148:149]
	v_pk_mov_b32 v[154:155], v[22:23], v[16:17] op_sel:[1,0]
	v_add_f32_e32 v35, 1.0, v163
	v_fma_mixlo_f16 v32, v20, v32, 0
	v_cvt_pk_f16_f32 v149, v148, v149
	v_pk_mul_f32 v[150:151], v[154:155], v[150:151]
	v_rcp_f32_e32 v35, v35
	v_pack_b32_f16 v148, v32, v149
	v_cvt_pk_f16_f32 v32, v150, v151
	v_mov_b32_e32 v150, v17
	v_mov_b32_e32 v151, v18
	v_pk_mul_f32 v[150:151], v[150:151], v[152:153]
	v_alignbit_b32 v149, v32, v149, 16
	v_cvt_pk_f16_f32 v151, v150, v151
	v_alignbit_b32 v150, v151, v32, 16
	v_lshrrev_b32_e32 v151, 16, v151
	v_fma_mixhi_f16 v151, v19, v35, 0
	v_cvt_f32_f16_e32 v32, v144
	v_cvt_f32_f16_sdwa v35, v144 dst_sel:DWORD dst_unused:UNUSED_PAD src0_sel:WORD_1
	v_cvt_f32_f16_e32 v144, v145
	v_cvt_f32_f16_sdwa v145, v145 dst_sel:DWORD dst_unused:UNUSED_PAD src0_sel:WORD_1
	global_store_dwordx4 v[168:169], v[148:151], off offset:256
	v_max_f32_e32 v35, 0xc1f00000, v35
	v_max_f32_e32 v144, 0xc1f00000, v144
	v_mul_f32_e32 v144, 0xbfb8aa3b, v144
	v_exp_f32_e32 v150, v144
	v_max_f32_e32 v144, 0xc1f00000, v145
	v_mul_f32_e32 v144, 0xbfb8aa3b, v144
	v_cvt_f32_f16_e32 v145, v146
	v_exp_f32_e32 v151, v144
	v_cvt_f32_f16_sdwa v144, v146 dst_sel:DWORD dst_unused:UNUSED_PAD src0_sel:WORD_1
	v_mul_f32_e32 v35, 0xbfb8aa3b, v35
	v_max_f32_e32 v145, 0xc1f00000, v145
	v_mul_f32_e32 v145, 0xbfb8aa3b, v145
	v_max_f32_e32 v144, 0xc1f00000, v144
	v_mul_f32_e32 v144, 0xbfb8aa3b, v144
	v_exp_f32_e32 v152, v145
	v_cvt_f32_f16_e32 v145, v147
	v_exp_f32_e32 v153, v144
	v_cvt_f32_f16_sdwa v144, v147 dst_sel:DWORD dst_unused:UNUSED_PAD src0_sel:WORD_1
	v_exp_f32_e32 v35, v35
	v_max_f32_e32 v32, 0xc1f00000, v32
	v_mul_f32_e32 v32, 0xbfb8aa3b, v32
	v_exp_f32_e32 v32, v32
	v_max_f32_e32 v145, 0xc1f00000, v145
	v_max_f32_e32 v144, 0xc1f00000, v144
	v_mul_f32_e32 v145, 0xbfb8aa3b, v145
	v_mul_f32_e32 v144, 0xbfb8aa3b, v144
	v_add_f32_e32 v35, 1.0, v35
	v_exp_f32_e32 v154, v145
	v_exp_f32_e32 v155, v144
	v_rcp_f32_e32 v144, v35
	v_add_f32_e32 v35, 1.0, v150
	v_rcp_f32_e32 v145, v35
	v_add_f32_e32 v35, 1.0, v151
	v_add_f32_e32 v32, 1.0, v32
	v_rcp_f32_e32 v146, v35
	v_add_f32_e32 v35, 1.0, v152
	v_rcp_f32_e32 v32, v32
	v_rcp_f32_e32 v147, v35
	v_add_f32_e32 v35, 1.0, v153
	v_rcp_f32_e32 v150, v35
	v_add_f32_e32 v35, 1.0, v154
	v_rcp_f32_e32 v151, v35
	v_mov_b32_e32 v152, v49
	v_mov_b32_e32 v153, v50
	v_pk_mul_f32 v[144:145], v[152:153], v[144:145]
	v_pk_mov_b32 v[152:153], v[50:51], v[44:45] op_sel:[1,0]
	v_add_f32_e32 v35, 1.0, v155
	v_fma_mixlo_f16 v32, v48, v32, 0
	v_cvt_pk_f16_f32 v145, v144, v145
	v_pk_mul_f32 v[146:147], v[152:153], v[146:147]
	v_rcp_f32_e32 v35, v35
	v_pack_b32_f16 v144, v32, v145
	v_cvt_pk_f16_f32 v32, v146, v147
	v_mov_b32_e32 v146, v45
	v_mov_b32_e32 v147, v46
	v_pk_mul_f32 v[146:147], v[146:147], v[150:151]
	v_alignbit_b32 v145, v32, v145, 16
	v_cvt_pk_f16_f32 v147, v146, v147
	v_alignbit_b32 v146, v147, v32, 16
	v_lshrrev_b32_e32 v147, 16, v147
	v_fma_mixhi_f16 v147, v47, v35, 0
	v_cvt_f32_f16_e32 v32, v140
	v_cvt_f32_f16_sdwa v35, v140 dst_sel:DWORD dst_unused:UNUSED_PAD src0_sel:WORD_1
	v_cvt_f32_f16_e32 v140, v141
	v_cvt_f32_f16_sdwa v141, v141 dst_sel:DWORD dst_unused:UNUSED_PAD src0_sel:WORD_1
	v_lshlrev_b64 v[148:149], 11, v[172:173]
	v_lshl_add_u64 v[148:149], s[14:15], 0, v[148:149]
	v_max_f32_e32 v140, 0xc1f00000, v140
	v_lshl_add_u64 v[148:149], v[148:149], 0, v[166:167]
	v_mul_f32_e32 v140, 0xbfb8aa3b, v140
	global_store_dwordx4 v[148:149], v[144:147], off
	v_max_f32_e32 v35, 0xc1f00000, v35
	v_mul_f32_e32 v35, 0xbfb8aa3b, v35
	v_exp_f32_e32 v144, v140
	v_max_f32_e32 v140, 0xc1f00000, v141
	v_mul_f32_e32 v140, 0xbfb8aa3b, v140
	v_cvt_f32_f16_e32 v141, v142
	v_exp_f32_e32 v145, v140
	v_cvt_f32_f16_sdwa v140, v142 dst_sel:DWORD dst_unused:UNUSED_PAD src0_sel:WORD_1
	v_exp_f32_e32 v35, v35
	v_max_f32_e32 v141, 0xc1f00000, v141
	v_mul_f32_e32 v141, 0xbfb8aa3b, v141
	v_max_f32_e32 v140, 0xc1f00000, v140
	v_mul_f32_e32 v140, 0xbfb8aa3b, v140
	v_exp_f32_e32 v146, v141
	v_cvt_f32_f16_e32 v141, v143
	v_exp_f32_e32 v147, v140
	v_cvt_f32_f16_sdwa v140, v143 dst_sel:DWORD dst_unused:UNUSED_PAD src0_sel:WORD_1
	v_max_f32_e32 v32, 0xc1f00000, v32
	v_mul_f32_e32 v32, 0xbfb8aa3b, v32
	v_exp_f32_e32 v32, v32
	v_max_f32_e32 v141, 0xc1f00000, v141
	v_max_f32_e32 v140, 0xc1f00000, v140
	v_mul_f32_e32 v141, 0xbfb8aa3b, v141
	v_mul_f32_e32 v140, 0xbfb8aa3b, v140
	v_add_f32_e32 v35, 1.0, v35
	v_exp_f32_e32 v150, v141
	v_exp_f32_e32 v151, v140
	v_rcp_f32_e32 v140, v35
	v_add_f32_e32 v35, 1.0, v144
	v_rcp_f32_e32 v141, v35
	v_add_f32_e32 v35, 1.0, v145
	v_add_f32_e32 v32, 1.0, v32
	v_rcp_f32_e32 v142, v35
	v_add_f32_e32 v35, 1.0, v146
	v_rcp_f32_e32 v32, v32
	v_rcp_f32_e32 v143, v35
	v_add_f32_e32 v35, 1.0, v147
	v_rcp_f32_e32 v144, v35
	v_add_f32_e32 v35, 1.0, v150
	v_rcp_f32_e32 v145, v35
	v_mov_b32_e32 v146, v13
	v_mov_b32_e32 v147, v14
	v_pk_mul_f32 v[140:141], v[146:147], v[140:141]
	v_pk_mov_b32 v[146:147], v[14:15], v[8:9] op_sel:[1,0]
	v_add_f32_e32 v35, 1.0, v151
	v_fma_mixlo_f16 v32, v12, v32, 0
	v_cvt_pk_f16_f32 v141, v140, v141
	v_pk_mul_f32 v[142:143], v[146:147], v[142:143]
	v_rcp_f32_e32 v35, v35
	v_pack_b32_f16 v140, v32, v141
	v_cvt_pk_f16_f32 v32, v142, v143
	v_mov_b32_e32 v142, v9
	v_mov_b32_e32 v143, v10
	v_pk_mul_f32 v[142:143], v[142:143], v[144:145]
	v_alignbit_b32 v141, v32, v141, 16
	v_cvt_pk_f16_f32 v143, v142, v143
	v_alignbit_b32 v142, v143, v32, 16
	v_lshrrev_b32_e32 v143, 16, v143
	v_fma_mixhi_f16 v143, v11, v35, 0
	v_cvt_f32_f16_e32 v32, v136
	v_cvt_f32_f16_sdwa v35, v136 dst_sel:DWORD dst_unused:UNUSED_PAD src0_sel:WORD_1
	v_cvt_f32_f16_e32 v136, v137
	v_cvt_f32_f16_sdwa v137, v137 dst_sel:DWORD dst_unused:UNUSED_PAD src0_sel:WORD_1
	global_store_dwordx4 v[148:149], v[140:143], off offset:256
	v_max_f32_e32 v35, 0xc1f00000, v35
	v_max_f32_e32 v136, 0xc1f00000, v136
	v_mul_f32_e32 v136, 0xbfb8aa3b, v136
	v_exp_f32_e32 v142, v136
	v_max_f32_e32 v136, 0xc1f00000, v137
	v_mul_f32_e32 v136, 0xbfb8aa3b, v136
	v_cvt_f32_f16_e32 v137, v138
	v_exp_f32_e32 v143, v136
	v_cvt_f32_f16_sdwa v136, v138 dst_sel:DWORD dst_unused:UNUSED_PAD src0_sel:WORD_1
	v_mul_f32_e32 v35, 0xbfb8aa3b, v35
	v_max_f32_e32 v137, 0xc1f00000, v137
	v_mul_f32_e32 v137, 0xbfb8aa3b, v137
	v_max_f32_e32 v136, 0xc1f00000, v136
	v_mul_f32_e32 v136, 0xbfb8aa3b, v136
	v_exp_f32_e32 v144, v137
	v_cvt_f32_f16_e32 v137, v139
	v_exp_f32_e32 v145, v136
	v_cvt_f32_f16_sdwa v136, v139 dst_sel:DWORD dst_unused:UNUSED_PAD src0_sel:WORD_1
	v_exp_f32_e32 v35, v35
	v_max_f32_e32 v32, 0xc1f00000, v32
	v_mul_f32_e32 v32, 0xbfb8aa3b, v32
	v_exp_f32_e32 v32, v32
	v_max_f32_e32 v137, 0xc1f00000, v137
	v_max_f32_e32 v136, 0xc1f00000, v136
	v_mul_f32_e32 v137, 0xbfb8aa3b, v137
	v_mul_f32_e32 v136, 0xbfb8aa3b, v136
	v_add_f32_e32 v35, 1.0, v35
	v_exp_f32_e32 v146, v137
	v_exp_f32_e32 v147, v136
	v_rcp_f32_e32 v136, v35
	v_add_f32_e32 v35, 1.0, v142
	v_rcp_f32_e32 v137, v35
	v_add_f32_e32 v35, 1.0, v143
	v_add_f32_e32 v32, 1.0, v32
	v_rcp_f32_e32 v138, v35
	v_add_f32_e32 v35, 1.0, v144
	v_rcp_f32_e32 v32, v32
	v_rcp_f32_e32 v139, v35
	v_add_f32_e32 v35, 1.0, v145
	v_rcp_f32_e32 v142, v35
	v_add_f32_e32 v35, 1.0, v146
	v_rcp_f32_e32 v143, v35
	v_mov_b32_e32 v144, v41
	v_mov_b32_e32 v145, v42
	v_pk_mul_f32 v[136:137], v[144:145], v[136:137]
	v_pk_mov_b32 v[144:145], v[42:43], v[36:37] op_sel:[1,0]
	v_add_f32_e32 v35, 1.0, v147
	v_fma_mixlo_f16 v32, v40, v32, 0
	v_cvt_pk_f16_f32 v137, v136, v137
	v_pk_mul_f32 v[138:139], v[144:145], v[138:139]
	v_rcp_f32_e32 v35, v35
	v_pack_b32_f16 v136, v32, v137
	v_cvt_pk_f16_f32 v32, v138, v139
	v_mov_b32_e32 v138, v37
	v_mov_b32_e32 v139, v38
	v_pk_mul_f32 v[138:139], v[138:139], v[142:143]
	v_alignbit_b32 v137, v32, v137, 16
	v_cvt_pk_f16_f32 v139, v138, v139
	v_alignbit_b32 v138, v139, v32, 16
	v_lshrrev_b32_e32 v139, 16, v139
	v_fma_mixhi_f16 v139, v39, v35, 0
	v_cvt_f32_f16_e32 v32, v132
	v_cvt_f32_f16_sdwa v35, v132 dst_sel:DWORD dst_unused:UNUSED_PAD src0_sel:WORD_1
	v_cvt_f32_f16_e32 v132, v133
	v_cvt_f32_f16_sdwa v133, v133 dst_sel:DWORD dst_unused:UNUSED_PAD src0_sel:WORD_1
	v_lshlrev_b64 v[140:141], 11, v[170:171]
	v_lshl_add_u64 v[140:141], s[14:15], 0, v[140:141]
	v_max_f32_e32 v132, 0xc1f00000, v132
	v_lshl_add_u64 v[140:141], v[140:141], 0, v[166:167]
	v_mul_f32_e32 v132, 0xbfb8aa3b, v132
	global_store_dwordx4 v[140:141], v[136:139], off
	v_max_f32_e32 v35, 0xc1f00000, v35
	v_mul_f32_e32 v35, 0xbfb8aa3b, v35
	v_exp_f32_e32 v136, v132
	v_max_f32_e32 v132, 0xc1f00000, v133
	v_mul_f32_e32 v132, 0xbfb8aa3b, v132
	v_cvt_f32_f16_e32 v133, v134
	v_exp_f32_e32 v137, v132
	v_cvt_f32_f16_sdwa v132, v134 dst_sel:DWORD dst_unused:UNUSED_PAD src0_sel:WORD_1
	v_exp_f32_e32 v35, v35
	v_max_f32_e32 v133, 0xc1f00000, v133
	v_mul_f32_e32 v133, 0xbfb8aa3b, v133
	v_max_f32_e32 v132, 0xc1f00000, v132
	v_mul_f32_e32 v132, 0xbfb8aa3b, v132
	v_exp_f32_e32 v138, v133
	v_cvt_f32_f16_e32 v133, v135
	v_exp_f32_e32 v139, v132
	v_cvt_f32_f16_sdwa v132, v135 dst_sel:DWORD dst_unused:UNUSED_PAD src0_sel:WORD_1
	v_max_f32_e32 v32, 0xc1f00000, v32
	v_mul_f32_e32 v32, 0xbfb8aa3b, v32
	v_exp_f32_e32 v32, v32
	v_max_f32_e32 v133, 0xc1f00000, v133
	v_max_f32_e32 v132, 0xc1f00000, v132
	v_mul_f32_e32 v133, 0xbfb8aa3b, v133
	v_mul_f32_e32 v132, 0xbfb8aa3b, v132
	v_add_f32_e32 v35, 1.0, v35
	v_exp_f32_e32 v142, v133
	v_exp_f32_e32 v143, v132
	v_rcp_f32_e32 v132, v35
	v_add_f32_e32 v35, 1.0, v136
	v_rcp_f32_e32 v133, v35
	v_add_f32_e32 v35, 1.0, v137
	v_add_f32_e32 v32, 1.0, v32
	v_rcp_f32_e32 v134, v35
	v_add_f32_e32 v35, 1.0, v138
	v_rcp_f32_e32 v32, v32
	v_rcp_f32_e32 v135, v35
	v_add_f32_e32 v35, 1.0, v139
	v_rcp_f32_e32 v136, v35
	v_add_f32_e32 v35, 1.0, v142
	v_rcp_f32_e32 v137, v35
	v_mov_b32_e32 v138, v5
	v_mov_b32_e32 v139, v6
	v_pk_mul_f32 v[132:133], v[138:139], v[132:133]
	v_pk_mov_b32 v[138:139], v[6:7], v[0:1] op_sel:[1,0]
	v_add_f32_e32 v35, 1.0, v143
	v_fma_mixlo_f16 v32, v4, v32, 0
	v_cvt_pk_f16_f32 v133, v132, v133
	v_pk_mul_f32 v[134:135], v[138:139], v[134:135]
	v_rcp_f32_e32 v35, v35
	v_pack_b32_f16 v132, v32, v133
	v_cvt_pk_f16_f32 v32, v134, v135
	v_mov_b32_e32 v134, v1
	v_mov_b32_e32 v135, v2
	v_pk_mul_f32 v[134:135], v[134:135], v[136:137]
	v_alignbit_b32 v133, v32, v133, 16
	v_cvt_pk_f16_f32 v135, v134, v135
	v_alignbit_b32 v134, v135, v32, 16
	v_lshrrev_b32_e32 v135, 16, v135
	v_fma_mixhi_f16 v135, v3, v35, 0
	global_store_dwordx4 v[140:141], v[132:135], off offset:256
	s_cbranch_execnz .LBB0_944

.LBB0_958:
	s_add_u32 s12, s10, 0x100
	s_addc_u32 s13, s11, 0
	s_add_i32 s38, 0, 0x10000
	v_add_u32_e32 v142, s38, v196
	ds_read_b128 v[122:125], v142
	ds_read_b128 v[138:141], v142 offset:2048
	ds_read_b128 v[130:133], v142 offset:1024
	ds_read_b128 v[142:145], v142 offset:3072
	s_cmp_eq_u32 s37, 12
	s_cselect_b32 s17, s7, s13
	s_cselect_b32 s16, s6, s12
	s_cselect_b32 s15, s9, s36
	s_cselect_b32 s14, s8, s35
	v_lshl_add_u64 v[230:231], s[10:11], 0, v[188:189]
	s_add_i32 m0, s21, 0xc000
	ds_read_b128 v[146:149], v198
	ds_read_b128 v[192:195], v198 offset:2048
	ds_read_b128 v[204:207], v198 offset:4096
	ds_read_b128 v[212:215], v198 offset:6144
	ds_read_b128 v[150:153], v198 offset:1024
	ds_read_b128 v[200:203], v198 offset:3072
	ds_read_b128 v[208:211], v198 offset:5120
	ds_read_b128 v[216:219], v198 offset:7168
	global_load_lds_dwordx4 v[230:231], off
	v_lshl_add_u64 v[230:231], s[10:11], 0, v[190:191]
	s_add_i32 m0, s21, 0xe000
	s_nop 0
	global_load_lds_dwordx4 v[230:231], off
	s_waitcnt lgkmcnt(8)
	s_barrier
	s_waitcnt lgkmcnt(7)
	v_mfma_f32_16x16x32_f16 v[134:137], v[122:125], v[146:149], v[134:137]
	v_mfma_f32_16x16x32_f16 v[126:129], v[138:141], v[146:149], v[126:129]
	s_waitcnt lgkmcnt(6)
	v_mfma_f32_16x16x32_f16 v[110:113], v[122:125], v[192:195], v[110:113]
	v_mfma_f32_16x16x32_f16 v[106:109], v[138:141], v[192:195], v[106:109]
	s_waitcnt lgkmcnt(5)
	v_mfma_f32_16x16x32_f16 v[94:97], v[122:125], v[204:207], v[94:97]
	v_mfma_f32_16x16x32_f16 v[90:93], v[138:141], v[204:207], v[90:93]
	s_waitcnt lgkmcnt(4)
	v_mfma_f32_16x16x32_f16 v[78:81], v[122:125], v[212:215], v[78:81]
	v_mfma_f32_16x16x32_f16 v[74:77], v[138:141], v[212:215], v[74:77]
	s_waitcnt lgkmcnt(3)
	v_mfma_f32_16x16x32_f16 v[134:137], v[130:133], v[150:153], v[134:137]
	v_mfma_f32_16x16x32_f16 v[126:129], v[142:145], v[150:153], v[126:129]
	s_waitcnt lgkmcnt(2)
	v_mfma_f32_16x16x32_f16 v[110:113], v[130:133], v[200:203], v[110:113]
	v_mfma_f32_16x16x32_f16 v[106:109], v[142:145], v[200:203], v[106:109]
	s_waitcnt lgkmcnt(1)
	v_mfma_f32_16x16x32_f16 v[94:97], v[130:133], v[208:211], v[94:97]
	v_mfma_f32_16x16x32_f16 v[90:93], v[142:145], v[208:211], v[90:93]
	s_waitcnt lgkmcnt(0)
	v_mfma_f32_16x16x32_f16 v[78:81], v[130:133], v[216:219], v[78:81]
	v_mfma_f32_16x16x32_f16 v[74:77], v[142:145], v[216:219], v[74:77]
	s_barrier
	s_add_i32 s39, 0, 0x14000
	s_add_i32 s10, s38, s20
	v_add_u32_e32 v199, s39, v196
	v_lshl_add_u64 v[246:247], s[14:15], 0, v[32:33]
	s_mov_b32 m0, s10
	ds_read_b128 v[230:233], v199
	ds_read_b128 v[238:241], v199 offset:2048
	ds_read_b128 v[234:237], v199 offset:1024
	ds_read_b128 v[242:245], v199 offset:3072
	global_load_lds_dwordx4 v[246:247], off
	v_lshl_add_u64 v[248:249], s[14:15], 0, v[154:155]
	s_add_i32 m0, s10, 0x2000
	s_nop 0
	global_load_lds_dwordx4 v[248:249], off
	s_barrier
	s_waitcnt lgkmcnt(2)
	v_mfma_f32_16x16x32_f16 v[118:121], v[230:233], v[146:149], v[118:121]
	v_mfma_f32_16x16x32_f16 v[114:117], v[238:241], v[146:149], v[114:117]
	v_mfma_f32_16x16x32_f16 v[102:105], v[230:233], v[192:195], v[102:105]
	v_mfma_f32_16x16x32_f16 v[98:101], v[238:241], v[192:195], v[98:101]
	v_mfma_f32_16x16x32_f16 v[86:89], v[230:233], v[204:207], v[86:89]
	v_mfma_f32_16x16x32_f16 v[82:85], v[238:241], v[204:207], v[82:85]
	v_mfma_f32_16x16x32_f16 v[70:73], v[230:233], v[212:215], v[70:73]
	v_mfma_f32_16x16x32_f16 v[66:69], v[238:241], v[212:215], v[66:69]
	s_waitcnt lgkmcnt(0)
	v_mfma_f32_16x16x32_f16 v[118:121], v[234:237], v[150:153], v[118:121]
	v_mfma_f32_16x16x32_f16 v[114:117], v[242:245], v[150:153], v[114:117]
	v_mfma_f32_16x16x32_f16 v[102:105], v[234:237], v[200:203], v[102:105]
	v_mfma_f32_16x16x32_f16 v[98:101], v[242:245], v[200:203], v[98:101]
	v_mfma_f32_16x16x32_f16 v[86:89], v[234:237], v[208:211], v[86:89]
	v_mfma_f32_16x16x32_f16 v[82:85], v[242:245], v[208:211], v[82:85]
	v_mfma_f32_16x16x32_f16 v[70:73], v[234:237], v[216:219], v[70:73]
	v_mfma_f32_16x16x32_f16 v[66:69], v[242:245], v[216:219], v[66:69]
	s_mov_b32 m0, s21
	v_lshl_add_u64 v[228:229], s[16:17], 0, v[32:33]
	s_barrier
	ds_read_b128 v[146:149], v198 offset:16384
	ds_read_b128 v[192:195], v198 offset:18432
	ds_read_b128 v[204:207], v198 offset:20480
	ds_read_b128 v[212:215], v198 offset:22528
	ds_read_b128 v[150:153], v198 offset:17408
	ds_read_b128 v[200:203], v198 offset:19456
	ds_read_b128 v[208:211], v198 offset:21504
	ds_read_b128 v[216:219], v198 offset:23552
	global_load_lds_dwordx4 v[228:229], off
	v_lshl_add_u64 v[222:223], s[16:17], 0, v[154:155]
	s_mov_b32 m0, s22
	s_nop 0
	global_load_lds_dwordx4 v[222:223], off
	s_barrier
	s_waitcnt lgkmcnt(7)
	v_mfma_f32_16x16x32_f16 v[62:65], v[122:125], v[146:149], v[62:65]
	v_mfma_f32_16x16x32_f16 v[58:61], v[138:141], v[146:149], v[58:61]
	s_waitcnt lgkmcnt(6)
	v_mfma_f32_16x16x32_f16 v[46:49], v[122:125], v[192:195], v[46:49]
	v_mfma_f32_16x16x32_f16 v[42:45], v[138:141], v[192:195], v[42:45]
	s_waitcnt lgkmcnt(5)
	v_mfma_f32_16x16x32_f16 v[28:31], v[122:125], v[204:207], v[28:31]
	v_mfma_f32_16x16x32_f16 v[24:27], v[138:141], v[204:207], v[24:27]
	s_waitcnt lgkmcnt(4)
	v_mfma_f32_16x16x32_f16 v[12:15], v[122:125], v[212:215], v[12:15]
	v_mfma_f32_16x16x32_f16 v[8:11], v[138:141], v[212:215], v[8:11]
	s_waitcnt lgkmcnt(3)
	v_mfma_f32_16x16x32_f16 v[62:65], v[130:133], v[150:153], v[62:65]
	v_mfma_f32_16x16x32_f16 v[58:61], v[142:145], v[150:153], v[58:61]
	s_waitcnt lgkmcnt(2)
	v_mfma_f32_16x16x32_f16 v[46:49], v[130:133], v[200:203], v[46:49]
	v_mfma_f32_16x16x32_f16 v[42:45], v[142:145], v[200:203], v[42:45]
	s_waitcnt lgkmcnt(1)
	v_mfma_f32_16x16x32_f16 v[28:31], v[130:133], v[208:211], v[28:31]
	v_mfma_f32_16x16x32_f16 v[24:27], v[142:145], v[208:211], v[24:27]
	s_waitcnt lgkmcnt(0)
	v_mfma_f32_16x16x32_f16 v[12:15], v[130:133], v[216:219], v[12:15]
	v_mfma_f32_16x16x32_f16 v[8:11], v[142:145], v[216:219], v[8:11]
	s_barrier
	s_add_u32 s10, s14, 0x40000
	s_addc_u32 s11, s15, 0
	s_add_i32 s38, s39, s20
	v_lshl_add_u64 v[122:123], s[10:11], 0, v[32:33]
	s_mov_b32 m0, s38
	s_nop 0
	global_load_lds_dwordx4 v[122:123], off
	v_lshl_add_u64 v[122:123], s[10:11], 0, v[154:155]
	s_add_i32 m0, s38, 0x2000
	s_nop 0
	global_load_lds_dwordx4 v[122:123], off
	s_waitcnt vmcnt(6)
	s_barrier
	v_mfma_f32_16x16x32_f16 v[54:57], v[230:233], v[146:149], v[54:57]
	v_mfma_f32_16x16x32_f16 v[50:53], v[238:241], v[146:149], v[50:53]
	v_mfma_f32_16x16x32_f16 v[38:41], v[230:233], v[192:195], v[38:41]
	v_mfma_f32_16x16x32_f16 v[34:37], v[238:241], v[192:195], v[34:37]
	v_mfma_f32_16x16x32_f16 v[20:23], v[230:233], v[204:207], v[20:23]
	v_mfma_f32_16x16x32_f16 v[16:19], v[238:241], v[204:207], v[16:19]
	v_mfma_f32_16x16x32_f16 v[4:7], v[230:233], v[212:215], v[4:7]
	v_mfma_f32_16x16x32_f16 v[0:3], v[238:241], v[212:215], v[0:3]
	v_mfma_f32_16x16x32_f16 v[54:57], v[234:237], v[150:153], v[54:57]
	v_mfma_f32_16x16x32_f16 v[50:53], v[242:245], v[150:153], v[50:53]
	v_mfma_f32_16x16x32_f16 v[38:41], v[234:237], v[200:203], v[38:41]
	v_mfma_f32_16x16x32_f16 v[34:37], v[242:245], v[200:203], v[34:37]
	v_mfma_f32_16x16x32_f16 v[20:23], v[234:237], v[208:211], v[20:23]
	v_mfma_f32_16x16x32_f16 v[16:19], v[242:245], v[208:211], v[16:19]
	v_mfma_f32_16x16x32_f16 v[4:7], v[234:237], v[216:219], v[4:7]
	v_mfma_f32_16x16x32_f16 v[0:3], v[242:245], v[216:219], v[0:3]
	s_add_i32 s38, 0, 0x18000
	v_add_u32_e32 v142, s38, v196
	s_barrier
	ds_read_b128 v[122:125], v142
	ds_read_b128 v[138:141], v142 offset:2048
	ds_read_b128 v[130:133], v142 offset:1024
	ds_read_b128 v[142:145], v142 offset:3072
	s_add_u32 s10, s16, 0x40000
	s_addc_u32 s11, s17, 0
	s_mov_b32 m0, s23
	v_lshl_add_u64 v[230:231], s[10:11], 0, v[32:33]
	ds_read_b128 v[146:149], v198 offset:32768
	ds_read_b128 v[192:195], v198 offset:34816
	ds_read_b128 v[204:207], v198 offset:36864
	ds_read_b128 v[212:215], v198 offset:38912
	ds_read_b128 v[150:153], v198 offset:33792
	ds_read_b128 v[200:203], v198 offset:35840
	ds_read_b128 v[208:211], v198 offset:37888
	ds_read_b128 v[216:219], v198 offset:39936
	global_load_lds_dwordx4 v[230:231], off
	v_lshl_add_u64 v[230:231], s[10:11], 0, v[154:155]
	s_mov_b32 m0, s24
	s_nop 0
	global_load_lds_dwordx4 v[230:231], off
	s_waitcnt lgkmcnt(8)
	s_barrier
	s_waitcnt lgkmcnt(7)
	v_mfma_f32_16x16x32_f16 v[134:137], v[122:125], v[146:149], v[134:137]
	v_mfma_f32_16x16x32_f16 v[126:129], v[138:141], v[146:149], v[126:129]
	s_waitcnt lgkmcnt(6)
	v_mfma_f32_16x16x32_f16 v[110:113], v[122:125], v[192:195], v[110:113]
	v_mfma_f32_16x16x32_f16 v[106:109], v[138:141], v[192:195], v[106:109]
	s_waitcnt lgkmcnt(5)
	v_mfma_f32_16x16x32_f16 v[94:97], v[122:125], v[204:207], v[94:97]
	v_mfma_f32_16x16x32_f16 v[90:93], v[138:141], v[204:207], v[90:93]
	s_waitcnt lgkmcnt(4)
	v_mfma_f32_16x16x32_f16 v[78:81], v[122:125], v[212:215], v[78:81]
	v_mfma_f32_16x16x32_f16 v[74:77], v[138:141], v[212:215], v[74:77]
	s_waitcnt lgkmcnt(3)
	v_mfma_f32_16x16x32_f16 v[134:137], v[130:133], v[150:153], v[134:137]
	v_mfma_f32_16x16x32_f16 v[126:129], v[142:145], v[150:153], v[126:129]
	s_waitcnt lgkmcnt(2)
	v_mfma_f32_16x16x32_f16 v[110:113], v[130:133], v[200:203], v[110:113]
	v_mfma_f32_16x16x32_f16 v[106:109], v[142:145], v[200:203], v[106:109]
	s_waitcnt lgkmcnt(1)
	v_mfma_f32_16x16x32_f16 v[94:97], v[130:133], v[208:211], v[94:97]
	v_mfma_f32_16x16x32_f16 v[90:93], v[142:145], v[208:211], v[90:93]
	s_waitcnt lgkmcnt(0)
	v_mfma_f32_16x16x32_f16 v[78:81], v[130:133], v[216:219], v[78:81]
	v_mfma_f32_16x16x32_f16 v[74:77], v[142:145], v[216:219], v[74:77]
	s_barrier
	s_add_i32 s16, 0, 0x1c000
	s_add_i32 s10, s38, s20
	v_add_u32_e32 v199, s16, v196
	v_lshl_add_u64 v[246:247], v[246:247], 0, s[84:85]
	s_mov_b32 m0, s10
	ds_read_b128 v[230:233], v199
	ds_read_b128 v[238:241], v199 offset:2048
	ds_read_b128 v[234:237], v199 offset:1024
	ds_read_b128 v[242:245], v199 offset:3072
	global_load_lds_dwordx4 v[246:247], off
	v_lshl_add_u64 v[246:247], v[248:249], 0, s[84:85]
	s_add_i32 m0, s10, 0x2000
	s_nop 0
	global_load_lds_dwordx4 v[246:247], off
	s_barrier
	s_waitcnt lgkmcnt(2)
	v_mfma_f32_16x16x32_f16 v[118:121], v[230:233], v[146:149], v[118:121]
	v_mfma_f32_16x16x32_f16 v[114:117], v[238:241], v[146:149], v[114:117]
	v_mfma_f32_16x16x32_f16 v[102:105], v[230:233], v[192:195], v[102:105]
	v_mfma_f32_16x16x32_f16 v[98:101], v[238:241], v[192:195], v[98:101]
	v_mfma_f32_16x16x32_f16 v[86:89], v[230:233], v[204:207], v[86:89]
	v_mfma_f32_16x16x32_f16 v[82:85], v[238:241], v[204:207], v[82:85]
	v_mfma_f32_16x16x32_f16 v[70:73], v[230:233], v[212:215], v[70:73]
	v_mfma_f32_16x16x32_f16 v[66:69], v[238:241], v[212:215], v[66:69]
	s_waitcnt lgkmcnt(0)
	v_mfma_f32_16x16x32_f16 v[118:121], v[234:237], v[150:153], v[118:121]
	v_mfma_f32_16x16x32_f16 v[114:117], v[242:245], v[150:153], v[114:117]
	v_mfma_f32_16x16x32_f16 v[102:105], v[234:237], v[200:203], v[102:105]
	v_mfma_f32_16x16x32_f16 v[98:101], v[242:245], v[200:203], v[98:101]
	v_mfma_f32_16x16x32_f16 v[86:89], v[234:237], v[208:211], v[86:89]
	v_mfma_f32_16x16x32_f16 v[82:85], v[242:245], v[208:211], v[82:85]
	v_mfma_f32_16x16x32_f16 v[70:73], v[234:237], v[216:219], v[70:73]
	v_mfma_f32_16x16x32_f16 v[66:69], v[242:245], v[216:219], v[66:69]
	s_mov_b32 m0, s25
	v_lshl_add_u64 v[228:229], v[228:229], 0, s[84:85]
	s_barrier
	ds_read_b128 v[146:149], v198 offset:49152
	ds_read_b128 v[192:195], v198 offset:51200
	ds_read_b128 v[204:207], v198 offset:53248
	ds_read_b128 v[212:215], v198 offset:55296
	ds_read_b128 v[150:153], v198 offset:50176
	ds_read_b128 v[200:203], v198 offset:52224
	ds_read_b128 v[208:211], v198 offset:54272
	ds_read_b128 v[216:219], v198 offset:56320
	global_load_lds_dwordx4 v[228:229], off
	v_lshl_add_u64 v[222:223], v[222:223], 0, s[84:85]
	s_mov_b32 m0, s27
	s_nop 0
	global_load_lds_dwordx4 v[222:223], off
	s_barrier
	s_waitcnt lgkmcnt(7)
	v_mfma_f32_16x16x32_f16 v[62:65], v[122:125], v[146:149], v[62:65]
	v_mfma_f32_16x16x32_f16 v[58:61], v[138:141], v[146:149], v[58:61]
	s_waitcnt lgkmcnt(6)
	v_mfma_f32_16x16x32_f16 v[46:49], v[122:125], v[192:195], v[46:49]
	v_mfma_f32_16x16x32_f16 v[42:45], v[138:141], v[192:195], v[42:45]
	s_waitcnt lgkmcnt(5)
	v_mfma_f32_16x16x32_f16 v[28:31], v[122:125], v[204:207], v[28:31]
	v_mfma_f32_16x16x32_f16 v[24:27], v[138:141], v[204:207], v[24:27]
	s_waitcnt lgkmcnt(4)
	v_mfma_f32_16x16x32_f16 v[12:15], v[122:125], v[212:215], v[12:15]
	v_mfma_f32_16x16x32_f16 v[8:11], v[138:141], v[212:215], v[8:11]
	s_waitcnt lgkmcnt(3)
	v_mfma_f32_16x16x32_f16 v[62:65], v[130:133], v[150:153], v[62:65]
	v_mfma_f32_16x16x32_f16 v[58:61], v[142:145], v[150:153], v[58:61]
	s_waitcnt lgkmcnt(2)
	v_mfma_f32_16x16x32_f16 v[46:49], v[130:133], v[200:203], v[46:49]
	v_mfma_f32_16x16x32_f16 v[42:45], v[142:145], v[200:203], v[42:45]
	s_waitcnt lgkmcnt(1)
	v_mfma_f32_16x16x32_f16 v[28:31], v[130:133], v[208:211], v[28:31]
	v_mfma_f32_16x16x32_f16 v[24:27], v[142:145], v[208:211], v[24:27]
	s_waitcnt lgkmcnt(0)
	v_mfma_f32_16x16x32_f16 v[12:15], v[130:133], v[216:219], v[12:15]
	v_mfma_f32_16x16x32_f16 v[8:11], v[142:145], v[216:219], v[8:11]
	s_barrier
	s_add_u32 s10, s14, 0x40080
	s_addc_u32 s11, s15, 0
	s_add_i32 s14, s16, s20
	v_lshl_add_u64 v[122:123], s[10:11], 0, v[32:33]
	s_mov_b32 m0, s14
	s_nop 0
	global_load_lds_dwordx4 v[122:123], off
	v_lshl_add_u64 v[122:123], s[10:11], 0, v[154:155]
	s_add_i32 m0, s14, 0x2000
	s_nop 0
	global_load_lds_dwordx4 v[122:123], off
	s_waitcnt vmcnt(6)
	s_barrier
	v_mfma_f32_16x16x32_f16 v[54:57], v[230:233], v[146:149], v[54:57]
	v_mfma_f32_16x16x32_f16 v[50:53], v[238:241], v[146:149], v[50:53]
	v_mfma_f32_16x16x32_f16 v[38:41], v[230:233], v[192:195], v[38:41]
	v_mfma_f32_16x16x32_f16 v[34:37], v[238:241], v[192:195], v[34:37]
	v_mfma_f32_16x16x32_f16 v[20:23], v[230:233], v[204:207], v[20:23]
	v_mfma_f32_16x16x32_f16 v[16:19], v[238:241], v[204:207], v[16:19]
	v_mfma_f32_16x16x32_f16 v[4:7], v[230:233], v[212:215], v[4:7]
	v_mfma_f32_16x16x32_f16 v[0:3], v[238:241], v[212:215], v[0:3]
	v_mfma_f32_16x16x32_f16 v[54:57], v[234:237], v[150:153], v[54:57]
	v_mfma_f32_16x16x32_f16 v[50:53], v[242:245], v[150:153], v[50:53]
	v_mfma_f32_16x16x32_f16 v[38:41], v[234:237], v[200:203], v[38:41]
	v_mfma_f32_16x16x32_f16 v[34:37], v[242:245], v[200:203], v[34:37]
	v_mfma_f32_16x16x32_f16 v[20:23], v[234:237], v[208:211], v[20:23]
	v_mfma_f32_16x16x32_f16 v[16:19], v[242:245], v[208:211], v[16:19]
	v_mfma_f32_16x16x32_f16 v[4:7], v[234:237], v[216:219], v[4:7]
	v_mfma_f32_16x16x32_f16 v[0:3], v[242:245], v[216:219], v[0:3]
	s_add_i32 s37, s37, 2
	s_add_u32 s35, s35, 0x100
	s_addc_u32 s36, s36, 0
	s_cmp_gt_u32 s37, 13
	s_mov_b64 s[10:11], s[12:13]
	s_barrier
	s_cbranch_scc0 .LBB0_958
	s_cmp_eq_u32 s34, 2
	s_movk_i32 s6, 0x2800
	v_lshl_or_b32 v122, s31, 8, v197
	s_cselect_b32 s6, 0x2000, s6
	s_mov_b32 s7, 0x23a3c000
	s_cselect_b32 s8, s7, 0x23abc000
	s_add_u32 s6, s70, s6
	v_ashrrev_i32_e32 v123, 31, v122
	s_addc_u32 s7, s71, 0
	v_lshlrev_b64 v[192:193], 1, v[122:123]
	v_lshl_add_u64 v[194:195], s[6:7], 0, v[192:193]
	v_lshl_add_u64 v[122:123], v[194:195], 0, v[156:157]
	v_lshl_add_u64 v[124:125], v[194:195], 0, v[158:159]
	v_lshl_add_u64 v[130:131], v[194:195], 0, v[160:161]
	v_lshl_add_u64 v[208:209], v[194:195], 0, v[162:163]
	global_load_dwordx4 v[200:203], v[122:123], off
	global_load_dwordx4 v[204:207], v[122:123], off offset:256
	global_load_dwordx4 v[150:153], v[124:125], off
	global_load_dwordx4 v[146:149], v[124:125], off offset:256
	global_load_dwordx4 v[142:145], v[130:131], off
	global_load_dwordx4 v[138:141], v[130:131], off offset:256
	s_nop 0
	global_load_dwordx4 v[130:133], v[208:209], off
	global_load_dwordx4 v[122:125], v[208:209], off offset:256
	v_readlane_b32 s36, v252, 26
	v_readlane_b32 s42, v252, 32
	v_readlane_b32 s43, v252, 33
	s_add_u32 s6, s42, s8
	s_addc_u32 s7, s43, 0
	v_readlane_b32 s37, v252, 27
	v_readlane_b32 s38, v252, 28
	v_readlane_b32 s39, v252, 29
	v_readlane_b32 s40, v252, 30
	v_readlane_b32 s41, v252, 31
	v_lshl_add_u64 v[192:193], s[6:7], 0, v[192:193]
	s_waitcnt vmcnt(0)
	v_cvt_f32_f16_e32 v199, v200
	v_cvt_f32_f16_sdwa v200, v200 dst_sel:DWORD dst_unused:UNUSED_PAD src0_sel:WORD_1
	v_cvt_f32_f16_e32 v210, v201
	v_lshl_add_u64 v[208:209], v[192:193], 0, v[164:165]
	v_max_f32_e32 v199, 0xc1f00000, v199
	v_mul_f32_e32 v199, 0xbfb8aa3b, v199
	v_exp_f32_e32 v199, v199
	v_max_f32_e32 v200, 0xc1f00000, v200
	v_max_f32_e32 v210, 0xc1f00000, v210
	v_mul_f32_e32 v200, 0xbfb8aa3b, v200
	v_add_f32_e32 v199, 1.0, v199
	v_rcp_f32_e32 v199, v199
	v_exp_f32_e32 v200, v200
	v_mul_f32_e32 v210, 0xbfb8aa3b, v210
	v_exp_f32_e32 v211, v210
	v_fma_mixlo_f16 v199, v134, v199, 0
	v_add_f32_e32 v134, 1.0, v200
	v_rcp_f32_e32 v210, v134
	v_add_f32_e32 v134, 1.0, v211
	v_cvt_f32_f16_sdwa v200, v201 dst_sel:DWORD dst_unused:UNUSED_PAD src0_sel:WORD_1
	v_rcp_f32_e32 v211, v134
	v_mov_b32_e32 v134, v135
	v_mov_b32_e32 v135, v136
	v_cvt_f32_f16_e32 v136, v202
	v_max_f32_e32 v200, 0xc1f00000, v200
	v_mul_f32_e32 v200, 0xbfb8aa3b, v200
	v_exp_f32_e32 v200, v200
	v_max_f32_e32 v136, 0xc1f00000, v136
	v_mul_f32_e32 v136, 0xbfb8aa3b, v136
	v_exp_f32_e32 v136, v136
	v_pk_mul_f32 v[134:135], v[134:135], v[210:211]
	s_nop 0
	v_cvt_pk_f16_f32 v135, v134, v135
	v_add_f32_e32 v134, 1.0, v200
	v_rcp_f32_e32 v200, v134
	v_add_f32_e32 v134, 1.0, v136
	v_rcp_f32_e32 v201, v134
	v_pk_mov_b32 v[136:137], v[136:137], v[126:127] op_sel:[1,0]
	v_cvt_f32_f16_sdwa v126, v202 dst_sel:DWORD dst_unused:UNUSED_PAD src0_sel:WORD_1
	v_pack_b32_f16 v134, v199, v135
	v_pk_mul_f32 v[136:137], v[136:137], v[200:201]
	v_cvt_f32_f16_sdwa v200, v203 dst_sel:DWORD dst_unused:UNUSED_PAD src0_sel:WORD_1
	v_cvt_pk_f16_f32 v199, v136, v137
	v_cvt_f32_f16_e32 v136, v203
	v_max_f32_e32 v126, 0xc1f00000, v126
	v_mul_f32_e32 v126, 0xbfb8aa3b, v126
	v_exp_f32_e32 v126, v126
	v_max_f32_e32 v136, 0xc1f00000, v136
	v_mul_f32_e32 v136, 0xbfb8aa3b, v136
	v_exp_f32_e32 v137, v136
	v_add_f32_e32 v126, 1.0, v126
	v_rcp_f32_e32 v136, v126
	v_alignbit_b32 v135, v199, v135, 16
	v_add_f32_e32 v126, 1.0, v137
	v_rcp_f32_e32 v137, v126
	v_mov_b32_e32 v126, v127
	v_mov_b32_e32 v127, v128
	v_cvt_f32_f16_e32 v128, v204
	v_pk_mul_f32 v[126:127], v[126:127], v[136:137]
	s_nop 0
	v_cvt_pk_f16_f32 v126, v126, v127
	v_max_f32_e32 v127, 0xc1f00000, v200
	v_mul_f32_e32 v127, 0xbfb8aa3b, v127
	v_exp_f32_e32 v127, v127
	v_alignbit_b32 v136, v126, v199, 16
	v_lshrrev_b32_e32 v137, 16, v126
	v_add_f32_e32 v126, 1.0, v127
	v_rcp_f32_e32 v126, v126
	v_max_f32_e32 v127, 0xc1f00000, v128
	v_mul_f32_e32 v127, 0xbfb8aa3b, v127
	v_exp_f32_e32 v127, v127
	v_fma_mixhi_f16 v137, v129, v126, 0
	v_cvt_f32_f16_sdwa v126, v204 dst_sel:DWORD dst_unused:UNUSED_PAD src0_sel:WORD_1
	v_cvt_f32_f16_e32 v128, v205
	v_add_f32_e32 v127, 1.0, v127
	v_rcp_f32_e32 v127, v127
	v_max_f32_e32 v126, 0xc1f00000, v126
	v_mul_f32_e32 v126, 0xbfb8aa3b, v126
	v_max_f32_e32 v128, 0xc1f00000, v128
	v_exp_f32_e32 v126, v126
	v_mul_f32_e32 v128, 0xbfb8aa3b, v128
	v_exp_f32_e32 v128, v128
	v_fma_mixlo_f16 v129, v118, v127, 0
	v_add_f32_e32 v118, 1.0, v126
	v_rcp_f32_e32 v126, v118
	v_add_f32_e32 v118, 1.0, v128
	v_rcp_f32_e32 v127, v118
	v_cvt_f32_f16_sdwa v128, v205 dst_sel:DWORD dst_unused:UNUSED_PAD src0_sel:WORD_1
	v_mov_b32_e32 v118, v119
	v_mov_b32_e32 v119, v120
	v_cvt_f32_f16_e32 v120, v206
	v_max_f32_e32 v128, 0xc1f00000, v128
	v_mul_f32_e32 v128, 0xbfb8aa3b, v128
	v_exp_f32_e32 v128, v128
	v_max_f32_e32 v120, 0xc1f00000, v120
	v_mul_f32_e32 v120, 0xbfb8aa3b, v120
	v_exp_f32_e32 v120, v120
	v_pk_mul_f32 v[118:119], v[118:119], v[126:127]
	v_add_f32_e32 v126, 1.0, v128
	v_rcp_f32_e32 v126, v126
	v_add_f32_e32 v120, 1.0, v120
	v_rcp_f32_e32 v127, v120
	v_pk_mov_b32 v[120:121], v[120:121], v[114:115] op_sel:[1,0]
	v_cvt_f32_f16_sdwa v114, v206 dst_sel:DWORD dst_unused:UNUSED_PAD src0_sel:WORD_1
	v_cvt_pk_f16_f32 v119, v118, v119
	v_pk_mul_f32 v[120:121], v[120:121], v[126:127]
	v_cvt_f32_f16_sdwa v127, v207 dst_sel:DWORD dst_unused:UNUSED_PAD src0_sel:WORD_1
	v_cvt_pk_f16_f32 v126, v120, v121
	v_cvt_f32_f16_e32 v120, v207
	v_max_f32_e32 v114, 0xc1f00000, v114
	v_mul_f32_e32 v114, 0xbfb8aa3b, v114
	v_exp_f32_e32 v114, v114
	v_max_f32_e32 v120, 0xc1f00000, v120
	v_mul_f32_e32 v120, 0xbfb8aa3b, v120
	v_exp_f32_e32 v121, v120
	v_add_f32_e32 v114, 1.0, v114
	v_rcp_f32_e32 v120, v114
	v_pack_b32_f16 v118, v129, v119
	v_add_f32_e32 v114, 1.0, v121
	v_rcp_f32_e32 v121, v114
	v_mov_b32_e32 v114, v115
	v_max_f32_e32 v115, 0xc1f00000, v127
	v_mul_f32_e32 v115, 0xbfb8aa3b, v115
	v_exp_f32_e32 v127, v115
	v_mov_b32_e32 v115, v116
	v_pk_mul_f32 v[114:115], v[114:115], v[120:121]
	v_cvt_f32_f16_e32 v116, v150
	v_cvt_pk_f16_f32 v114, v114, v115
	v_add_f32_e32 v115, 1.0, v127
	v_rcp_f32_e32 v115, v115
	v_alignbit_b32 v120, v114, v126, 16
	v_lshrrev_b32_e32 v121, 16, v114
	v_max_f32_e32 v114, 0xc1f00000, v116
	v_alignbit_b32 v119, v126, v119, 16
	v_fma_mixhi_f16 v121, v117, v115, 0
	v_mul_f32_e32 v114, 0xbfb8aa3b, v114
	v_cvt_f32_f16_sdwa v117, v150 dst_sel:DWORD dst_unused:UNUSED_PAD src0_sel:WORD_1
	v_exp_f32_e32 v116, v114
	global_store_dwordx4 v[208:209], v[118:121], off offset:256
	v_lshl_add_u64 v[114:115], v[192:193], 0, v[166:167]
	v_max_f32_e32 v117, 0xc1f00000, v117
	v_cvt_f32_f16_e32 v118, v151
	v_add_f32_e32 v116, 1.0, v116
	v_mul_f32_e32 v117, 0xbfb8aa3b, v117
	v_rcp_f32_e32 v116, v116
	v_max_f32_e32 v118, 0xc1f00000, v118
	v_exp_f32_e32 v117, v117
	v_mul_f32_e32 v118, 0xbfb8aa3b, v118
	v_exp_f32_e32 v118, v118
	v_fma_mixlo_f16 v119, v110, v116, 0
	v_add_f32_e32 v110, 1.0, v117
	v_rcp_f32_e32 v116, v110
	v_add_f32_e32 v110, 1.0, v118
	v_rcp_f32_e32 v117, v110
	v_cvt_f32_f16_sdwa v118, v151 dst_sel:DWORD dst_unused:UNUSED_PAD src0_sel:WORD_1
	v_mov_b32_e32 v110, v111
	v_mov_b32_e32 v111, v112
	v_cvt_f32_f16_e32 v112, v152
	v_pk_mul_f32 v[110:111], v[110:111], v[116:117]
	v_max_f32_e32 v116, 0xc1f00000, v118
	v_mul_f32_e32 v116, 0xbfb8aa3b, v116
	v_max_f32_e32 v112, 0xc1f00000, v112
	v_exp_f32_e32 v116, v116
	v_mul_f32_e32 v112, 0xbfb8aa3b, v112
	v_exp_f32_e32 v112, v112
	v_cvt_pk_f16_f32 v111, v110, v111
	v_add_f32_e32 v110, 1.0, v116
	v_rcp_f32_e32 v116, v110
	v_add_f32_e32 v110, 1.0, v112
	v_rcp_f32_e32 v117, v110
	v_pk_mov_b32 v[112:113], v[112:113], v[106:107] op_sel:[1,0]
	v_cvt_f32_f16_sdwa v106, v152 dst_sel:DWORD dst_unused:UNUSED_PAD src0_sel:WORD_1
	v_pack_b32_f16 v110, v119, v111
	v_pk_mul_f32 v[112:113], v[112:113], v[116:117]
	v_cvt_f32_f16_sdwa v117, v153 dst_sel:DWORD dst_unused:UNUSED_PAD src0_sel:WORD_1
	v_cvt_pk_f16_f32 v116, v112, v113
	v_cvt_f32_f16_e32 v112, v153
	v_max_f32_e32 v106, 0xc1f00000, v106
	v_mul_f32_e32 v106, 0xbfb8aa3b, v106
	v_exp_f32_e32 v106, v106
	v_max_f32_e32 v112, 0xc1f00000, v112
	v_mul_f32_e32 v112, 0xbfb8aa3b, v112
	v_exp_f32_e32 v113, v112
	v_add_f32_e32 v106, 1.0, v106
	v_rcp_f32_e32 v112, v106
	v_alignbit_b32 v111, v116, v111, 16
	v_add_f32_e32 v106, 1.0, v113
	v_rcp_f32_e32 v113, v106
	v_mov_b32_e32 v106, v107
	v_mov_b32_e32 v107, v108
	v_cvt_f32_f16_e32 v108, v146
	v_pk_mul_f32 v[106:107], v[106:107], v[112:113]
	global_store_dwordx4 v[208:209], v[134:137], off
	v_cvt_pk_f16_f32 v106, v106, v107
	v_max_f32_e32 v107, 0xc1f00000, v117
	v_mul_f32_e32 v107, 0xbfb8aa3b, v107
	v_exp_f32_e32 v107, v107
	v_alignbit_b32 v112, v106, v116, 16
	v_lshrrev_b32_e32 v113, 16, v106
	v_add_f32_e32 v106, 1.0, v107
	v_rcp_f32_e32 v106, v106
	v_max_f32_e32 v107, 0xc1f00000, v108
	v_mul_f32_e32 v107, 0xbfb8aa3b, v107
	v_exp_f32_e32 v107, v107
	v_fma_mixhi_f16 v113, v109, v106, 0
	v_cvt_f32_f16_sdwa v106, v146 dst_sel:DWORD dst_unused:UNUSED_PAD src0_sel:WORD_1
	v_cvt_f32_f16_e32 v108, v147
	v_add_f32_e32 v107, 1.0, v107
	v_rcp_f32_e32 v107, v107
	v_max_f32_e32 v106, 0xc1f00000, v106
	v_mul_f32_e32 v106, 0xbfb8aa3b, v106
	v_max_f32_e32 v108, 0xc1f00000, v108
	v_exp_f32_e32 v106, v106
	v_mul_f32_e32 v108, 0xbfb8aa3b, v108
	v_exp_f32_e32 v108, v108
	v_fma_mixlo_f16 v109, v102, v107, 0
	v_add_f32_e32 v102, 1.0, v106
	v_rcp_f32_e32 v106, v102
	v_add_f32_e32 v102, 1.0, v108
	v_rcp_f32_e32 v107, v102
	v_cvt_f32_f16_sdwa v108, v147 dst_sel:DWORD dst_unused:UNUSED_PAD src0_sel:WORD_1
	v_mov_b32_e32 v102, v103
	v_mov_b32_e32 v103, v104
	v_cvt_f32_f16_e32 v104, v148
	v_max_f32_e32 v108, 0xc1f00000, v108
	v_mul_f32_e32 v108, 0xbfb8aa3b, v108
	v_exp_f32_e32 v108, v108
	v_max_f32_e32 v104, 0xc1f00000, v104
	v_mul_f32_e32 v104, 0xbfb8aa3b, v104
	v_exp_f32_e32 v104, v104
	v_pk_mul_f32 v[102:103], v[102:103], v[106:107]
	v_add_f32_e32 v106, 1.0, v108
	v_rcp_f32_e32 v106, v106
	v_add_f32_e32 v104, 1.0, v104
	v_rcp_f32_e32 v107, v104
	v_pk_mov_b32 v[104:105], v[104:105], v[98:99] op_sel:[1,0]
	v_cvt_f32_f16_sdwa v98, v148 dst_sel:DWORD dst_unused:UNUSED_PAD src0_sel:WORD_1
	v_cvt_pk_f16_f32 v103, v102, v103
	v_pk_mul_f32 v[104:105], v[104:105], v[106:107]
	v_cvt_f32_f16_sdwa v107, v149 dst_sel:DWORD dst_unused:UNUSED_PAD src0_sel:WORD_1
	v_cvt_pk_f16_f32 v106, v104, v105
	v_cvt_f32_f16_e32 v104, v149
	v_max_f32_e32 v98, 0xc1f00000, v98
	v_mul_f32_e32 v98, 0xbfb8aa3b, v98
	v_exp_f32_e32 v98, v98
	v_max_f32_e32 v104, 0xc1f00000, v104
	v_mul_f32_e32 v104, 0xbfb8aa3b, v104
	v_exp_f32_e32 v105, v104
	v_add_f32_e32 v98, 1.0, v98
	v_rcp_f32_e32 v104, v98
	v_pack_b32_f16 v102, v109, v103
	v_add_f32_e32 v98, 1.0, v105
	v_rcp_f32_e32 v105, v98
	v_mov_b32_e32 v98, v99
	v_max_f32_e32 v99, 0xc1f00000, v107
	v_mul_f32_e32 v99, 0xbfb8aa3b, v99
	v_exp_f32_e32 v107, v99
	v_mov_b32_e32 v99, v100
	v_pk_mul_f32 v[98:99], v[98:99], v[104:105]
	v_cvt_f32_f16_e32 v100, v142
	v_cvt_pk_f16_f32 v98, v98, v99
	v_add_f32_e32 v99, 1.0, v107
	v_rcp_f32_e32 v99, v99
	v_alignbit_b32 v104, v98, v106, 16
	v_lshrrev_b32_e32 v105, 16, v98
	v_max_f32_e32 v98, 0xc1f00000, v100
	v_alignbit_b32 v103, v106, v103, 16
	v_fma_mixhi_f16 v105, v101, v99, 0
	v_mul_f32_e32 v98, 0xbfb8aa3b, v98
	v_cvt_f32_f16_sdwa v101, v142 dst_sel:DWORD dst_unused:UNUSED_PAD src0_sel:WORD_1
	v_exp_f32_e32 v100, v98
	global_store_dwordx4 v[114:115], v[102:105], off offset:256
	v_lshl_add_u64 v[98:99], v[192:193], 0, v[168:169]
	v_max_f32_e32 v101, 0xc1f00000, v101
	v_cvt_f32_f16_e32 v102, v143
	v_add_f32_e32 v100, 1.0, v100
	v_mul_f32_e32 v101, 0xbfb8aa3b, v101
	v_rcp_f32_e32 v100, v100
	v_max_f32_e32 v102, 0xc1f00000, v102
	v_exp_f32_e32 v101, v101
	v_mul_f32_e32 v102, 0xbfb8aa3b, v102
	v_exp_f32_e32 v102, v102
	v_fma_mixlo_f16 v103, v94, v100, 0
	v_add_f32_e32 v94, 1.0, v101
	v_rcp_f32_e32 v100, v94
	v_add_f32_e32 v94, 1.0, v102
	v_rcp_f32_e32 v101, v94
	v_cvt_f32_f16_sdwa v102, v143 dst_sel:DWORD dst_unused:UNUSED_PAD src0_sel:WORD_1
	v_mov_b32_e32 v94, v95
	v_mov_b32_e32 v95, v96
	v_cvt_f32_f16_e32 v96, v144
	v_pk_mul_f32 v[94:95], v[94:95], v[100:101]
	v_max_f32_e32 v100, 0xc1f00000, v102
	v_mul_f32_e32 v100, 0xbfb8aa3b, v100
	v_max_f32_e32 v96, 0xc1f00000, v96
	v_exp_f32_e32 v100, v100
	v_mul_f32_e32 v96, 0xbfb8aa3b, v96
	v_exp_f32_e32 v96, v96
	v_cvt_pk_f16_f32 v95, v94, v95
	v_add_f32_e32 v94, 1.0, v100
	v_rcp_f32_e32 v100, v94
	v_add_f32_e32 v94, 1.0, v96
	v_rcp_f32_e32 v101, v94
	v_pk_mov_b32 v[96:97], v[96:97], v[90:91] op_sel:[1,0]
	v_cvt_f32_f16_sdwa v90, v144 dst_sel:DWORD dst_unused:UNUSED_PAD src0_sel:WORD_1
	v_pack_b32_f16 v94, v103, v95
	v_pk_mul_f32 v[96:97], v[96:97], v[100:101]
	v_cvt_f32_f16_sdwa v101, v145 dst_sel:DWORD dst_unused:UNUSED_PAD src0_sel:WORD_1
	v_cvt_pk_f16_f32 v100, v96, v97
	v_cvt_f32_f16_e32 v96, v145
	v_max_f32_e32 v90, 0xc1f00000, v90
	v_mul_f32_e32 v90, 0xbfb8aa3b, v90
	v_exp_f32_e32 v90, v90
	v_max_f32_e32 v96, 0xc1f00000, v96
	v_mul_f32_e32 v96, 0xbfb8aa3b, v96
	v_exp_f32_e32 v97, v96
	v_add_f32_e32 v90, 1.0, v90
	v_rcp_f32_e32 v96, v90
	v_alignbit_b32 v95, v100, v95, 16
	v_add_f32_e32 v90, 1.0, v97
	v_rcp_f32_e32 v97, v90
	v_mov_b32_e32 v90, v91
	v_mov_b32_e32 v91, v92
	v_cvt_f32_f16_e32 v92, v138
	v_pk_mul_f32 v[90:91], v[90:91], v[96:97]
	global_store_dwordx4 v[114:115], v[110:113], off
	v_cvt_pk_f16_f32 v90, v90, v91
	v_max_f32_e32 v91, 0xc1f00000, v101
	v_mul_f32_e32 v91, 0xbfb8aa3b, v91
	v_exp_f32_e32 v91, v91
	v_alignbit_b32 v96, v90, v100, 16
	v_lshrrev_b32_e32 v97, 16, v90
	v_add_f32_e32 v90, 1.0, v91
	v_rcp_f32_e32 v90, v90
	v_max_f32_e32 v91, 0xc1f00000, v92
	v_mul_f32_e32 v91, 0xbfb8aa3b, v91
	v_exp_f32_e32 v91, v91
	v_fma_mixhi_f16 v97, v93, v90, 0
	v_cvt_f32_f16_sdwa v90, v138 dst_sel:DWORD dst_unused:UNUSED_PAD src0_sel:WORD_1
	v_cvt_f32_f16_e32 v92, v139
	v_add_f32_e32 v91, 1.0, v91
	v_rcp_f32_e32 v91, v91
	v_max_f32_e32 v90, 0xc1f00000, v90
	v_mul_f32_e32 v90, 0xbfb8aa3b, v90
	v_max_f32_e32 v92, 0xc1f00000, v92
	v_exp_f32_e32 v90, v90
	v_mul_f32_e32 v92, 0xbfb8aa3b, v92
	v_exp_f32_e32 v92, v92
	v_fma_mixlo_f16 v93, v86, v91, 0
	v_add_f32_e32 v86, 1.0, v90
	v_rcp_f32_e32 v90, v86
	v_add_f32_e32 v86, 1.0, v92
	v_rcp_f32_e32 v91, v86
	v_cvt_f32_f16_sdwa v92, v139 dst_sel:DWORD dst_unused:UNUSED_PAD src0_sel:WORD_1
	v_mov_b32_e32 v86, v87
	v_mov_b32_e32 v87, v88
	v_cvt_f32_f16_e32 v88, v140
	v_max_f32_e32 v92, 0xc1f00000, v92
	v_mul_f32_e32 v92, 0xbfb8aa3b, v92
	v_exp_f32_e32 v92, v92
	v_max_f32_e32 v88, 0xc1f00000, v88
	v_mul_f32_e32 v88, 0xbfb8aa3b, v88
	v_exp_f32_e32 v88, v88
	v_pk_mul_f32 v[86:87], v[86:87], v[90:91]
	v_add_f32_e32 v90, 1.0, v92
	v_rcp_f32_e32 v90, v90
	v_add_f32_e32 v88, 1.0, v88
	v_rcp_f32_e32 v91, v88
	v_pk_mov_b32 v[88:89], v[88:89], v[82:83] op_sel:[1,0]
	v_cvt_f32_f16_sdwa v82, v140 dst_sel:DWORD dst_unused:UNUSED_PAD src0_sel:WORD_1
	v_cvt_pk_f16_f32 v87, v86, v87
	v_pk_mul_f32 v[88:89], v[88:89], v[90:91]
	v_cvt_f32_f16_sdwa v91, v141 dst_sel:DWORD dst_unused:UNUSED_PAD src0_sel:WORD_1
	v_cvt_pk_f16_f32 v90, v88, v89
	v_cvt_f32_f16_e32 v88, v141
	v_max_f32_e32 v82, 0xc1f00000, v82
	v_mul_f32_e32 v82, 0xbfb8aa3b, v82
	v_exp_f32_e32 v82, v82
	v_max_f32_e32 v88, 0xc1f00000, v88
	v_mul_f32_e32 v88, 0xbfb8aa3b, v88
	v_exp_f32_e32 v89, v88
	v_add_f32_e32 v82, 1.0, v82
	v_rcp_f32_e32 v88, v82
	v_pack_b32_f16 v86, v93, v87
	v_add_f32_e32 v82, 1.0, v89
	v_rcp_f32_e32 v89, v82
	v_mov_b32_e32 v82, v83
	v_max_f32_e32 v83, 0xc1f00000, v91
	v_mul_f32_e32 v83, 0xbfb8aa3b, v83
	v_exp_f32_e32 v91, v83
	v_mov_b32_e32 v83, v84
	v_pk_mul_f32 v[82:83], v[82:83], v[88:89]
	v_cvt_f32_f16_e32 v84, v130
	v_cvt_pk_f16_f32 v82, v82, v83
	v_add_f32_e32 v83, 1.0, v91
	v_rcp_f32_e32 v83, v83
	v_alignbit_b32 v88, v82, v90, 16
	v_lshrrev_b32_e32 v89, 16, v82
	v_max_f32_e32 v82, 0xc1f00000, v84
	v_alignbit_b32 v87, v90, v87, 16
	v_fma_mixhi_f16 v89, v85, v83, 0
	v_mul_f32_e32 v82, 0xbfb8aa3b, v82
	v_cvt_f32_f16_sdwa v85, v130 dst_sel:DWORD dst_unused:UNUSED_PAD src0_sel:WORD_1
	v_exp_f32_e32 v84, v82
	global_store_dwordx4 v[98:99], v[86:89], off offset:256
	v_lshl_add_u64 v[82:83], v[192:193], 0, v[170:171]
	v_max_f32_e32 v85, 0xc1f00000, v85
	v_cvt_f32_f16_e32 v86, v131
	v_add_f32_e32 v84, 1.0, v84
	v_mul_f32_e32 v85, 0xbfb8aa3b, v85
	v_rcp_f32_e32 v84, v84
	v_max_f32_e32 v86, 0xc1f00000, v86
	v_exp_f32_e32 v85, v85
	v_mul_f32_e32 v86, 0xbfb8aa3b, v86
	v_exp_f32_e32 v86, v86
	v_fma_mixlo_f16 v87, v78, v84, 0
	v_add_f32_e32 v78, 1.0, v85
	v_rcp_f32_e32 v84, v78
	v_add_f32_e32 v78, 1.0, v86
	v_rcp_f32_e32 v85, v78
	v_cvt_f32_f16_sdwa v86, v131 dst_sel:DWORD dst_unused:UNUSED_PAD src0_sel:WORD_1
	v_mov_b32_e32 v78, v79
	v_mov_b32_e32 v79, v80
	v_cvt_f32_f16_e32 v80, v132
	v_pk_mul_f32 v[78:79], v[78:79], v[84:85]
	v_max_f32_e32 v84, 0xc1f00000, v86
	v_mul_f32_e32 v84, 0xbfb8aa3b, v84
	v_max_f32_e32 v80, 0xc1f00000, v80
	v_exp_f32_e32 v84, v84
	v_mul_f32_e32 v80, 0xbfb8aa3b, v80
	v_exp_f32_e32 v80, v80
	v_cvt_pk_f16_f32 v79, v78, v79
	v_add_f32_e32 v78, 1.0, v84
	v_rcp_f32_e32 v84, v78
	v_add_f32_e32 v78, 1.0, v80
	v_rcp_f32_e32 v85, v78
	v_pk_mov_b32 v[80:81], v[80:81], v[74:75] op_sel:[1,0]
	v_cvt_f32_f16_sdwa v74, v132 dst_sel:DWORD dst_unused:UNUSED_PAD src0_sel:WORD_1
	v_pack_b32_f16 v78, v87, v79
	v_pk_mul_f32 v[80:81], v[80:81], v[84:85]
	v_cvt_f32_f16_sdwa v85, v133 dst_sel:DWORD dst_unused:UNUSED_PAD src0_sel:WORD_1
	v_cvt_pk_f16_f32 v84, v80, v81
	v_cvt_f32_f16_e32 v80, v133
	v_max_f32_e32 v74, 0xc1f00000, v74
	v_mul_f32_e32 v74, 0xbfb8aa3b, v74
	v_exp_f32_e32 v74, v74
	v_max_f32_e32 v80, 0xc1f00000, v80
	v_mul_f32_e32 v80, 0xbfb8aa3b, v80
	v_exp_f32_e32 v81, v80
	v_add_f32_e32 v74, 1.0, v74
	v_rcp_f32_e32 v80, v74
	v_alignbit_b32 v79, v84, v79, 16
	v_add_f32_e32 v74, 1.0, v81
	v_rcp_f32_e32 v81, v74
	v_mov_b32_e32 v74, v75
	v_mov_b32_e32 v75, v76
	v_cvt_f32_f16_e32 v76, v122
	v_pk_mul_f32 v[74:75], v[74:75], v[80:81]
	global_store_dwordx4 v[98:99], v[94:97], off
	v_cvt_pk_f16_f32 v74, v74, v75
	v_max_f32_e32 v75, 0xc1f00000, v85
	v_mul_f32_e32 v75, 0xbfb8aa3b, v75
	v_exp_f32_e32 v75, v75
	v_alignbit_b32 v80, v74, v84, 16
	v_lshrrev_b32_e32 v81, 16, v74
	v_add_f32_e32 v74, 1.0, v75
	v_rcp_f32_e32 v74, v74
	v_max_f32_e32 v75, 0xc1f00000, v76
	v_mul_f32_e32 v75, 0xbfb8aa3b, v75
	v_exp_f32_e32 v75, v75
	v_fma_mixhi_f16 v81, v77, v74, 0
	v_cvt_f32_f16_sdwa v74, v122 dst_sel:DWORD dst_unused:UNUSED_PAD src0_sel:WORD_1
	v_cvt_f32_f16_e32 v76, v123
	v_add_f32_e32 v75, 1.0, v75
	v_rcp_f32_e32 v75, v75
	v_max_f32_e32 v74, 0xc1f00000, v74
	v_mul_f32_e32 v74, 0xbfb8aa3b, v74
	v_max_f32_e32 v76, 0xc1f00000, v76
	v_exp_f32_e32 v74, v74
	v_mul_f32_e32 v76, 0xbfb8aa3b, v76
	v_exp_f32_e32 v76, v76
	v_fma_mixlo_f16 v77, v70, v75, 0
	v_add_f32_e32 v70, 1.0, v74
	v_rcp_f32_e32 v74, v70
	v_add_f32_e32 v70, 1.0, v76
	v_rcp_f32_e32 v75, v70
	v_cvt_f32_f16_sdwa v76, v123 dst_sel:DWORD dst_unused:UNUSED_PAD src0_sel:WORD_1
	v_mov_b32_e32 v70, v71
	v_mov_b32_e32 v71, v72
	v_cvt_f32_f16_e32 v72, v124
	v_max_f32_e32 v76, 0xc1f00000, v76
	v_mul_f32_e32 v76, 0xbfb8aa3b, v76
	v_exp_f32_e32 v76, v76
	v_max_f32_e32 v72, 0xc1f00000, v72
	v_mul_f32_e32 v72, 0xbfb8aa3b, v72
	v_exp_f32_e32 v72, v72
	v_pk_mul_f32 v[70:71], v[70:71], v[74:75]
	v_add_f32_e32 v74, 1.0, v76
	v_rcp_f32_e32 v74, v74
	v_add_f32_e32 v72, 1.0, v72
	v_rcp_f32_e32 v75, v72
	v_pk_mov_b32 v[72:73], v[72:73], v[66:67] op_sel:[1,0]
	v_cvt_f32_f16_sdwa v66, v124 dst_sel:DWORD dst_unused:UNUSED_PAD src0_sel:WORD_1
	v_cvt_pk_f16_f32 v71, v70, v71
	v_pk_mul_f32 v[72:73], v[72:73], v[74:75]
	v_cvt_f32_f16_sdwa v75, v125 dst_sel:DWORD dst_unused:UNUSED_PAD src0_sel:WORD_1
	v_cvt_pk_f16_f32 v74, v72, v73
	v_cvt_f32_f16_e32 v72, v125
	v_max_f32_e32 v66, 0xc1f00000, v66
	v_mul_f32_e32 v66, 0xbfb8aa3b, v66
	v_exp_f32_e32 v66, v66
	v_max_f32_e32 v72, 0xc1f00000, v72
	v_mul_f32_e32 v72, 0xbfb8aa3b, v72
	v_exp_f32_e32 v73, v72
	v_add_f32_e32 v66, 1.0, v66
	v_rcp_f32_e32 v72, v66
	v_pack_b32_f16 v70, v77, v71
	v_add_f32_e32 v66, 1.0, v73
	v_rcp_f32_e32 v73, v66
	v_max_f32_e32 v66, 0xc1f00000, v75
	v_mul_f32_e32 v66, 0xbfb8aa3b, v66
	v_exp_f32_e32 v75, v66
	v_mov_b32_e32 v66, v67
	v_mov_b32_e32 v67, v68
	v_pk_mul_f32 v[66:67], v[66:67], v[72:73]
	v_add_f32_e32 v68, 1.0, v75
	v_rcp_f32_e32 v68, v68
	v_cvt_pk_f16_f32 v66, v66, v67
	v_lshrrev_b32_e32 v73, 16, v66
	v_alignbit_b32 v71, v74, v71, 16
	v_alignbit_b32 v72, v66, v74, 16
	v_fma_mixhi_f16 v73, v69, v68, 0
	global_store_dwordx4 v[82:83], v[78:81], off
	global_store_dwordx4 v[82:83], v[70:73], off offset:256
	v_lshl_add_u64 v[66:67], v[194:195], 0, v[172:173]
	v_lshl_add_u64 v[68:69], v[194:195], 0, v[174:175]
	v_lshl_add_u64 v[70:71], v[194:195], 0, v[176:177]
	v_lshl_add_u64 v[98:99], v[194:195], 0, v[178:179]
	global_load_dwordx4 v[90:93], v[66:67], off
	global_load_dwordx4 v[94:97], v[66:67], off offset:256
	global_load_dwordx4 v[86:89], v[68:69], off
	global_load_dwordx4 v[82:85], v[68:69], off offset:256
	global_load_dwordx4 v[78:81], v[70:71], off
	global_load_dwordx4 v[74:77], v[70:71], off offset:256
	s_nop 0
	global_load_dwordx4 v[70:73], v[98:99], off
	global_load_dwordx4 v[66:69], v[98:99], off offset:256
	s_waitcnt vmcnt(0)
	v_cvt_f32_f16_e32 v100, v90
	v_cvt_f32_f16_sdwa v90, v90 dst_sel:DWORD dst_unused:UNUSED_PAD src0_sel:WORD_1
	v_cvt_f32_f16_e32 v101, v91
	v_lshl_add_u64 v[98:99], v[192:193], 0, v[180:181]
	v_max_f32_e32 v100, 0xc1f00000, v100
	v_mul_f32_e32 v100, 0xbfb8aa3b, v100
	v_exp_f32_e32 v100, v100
	v_max_f32_e32 v90, 0xc1f00000, v90
	v_max_f32_e32 v101, 0xc1f00000, v101
	v_mul_f32_e32 v90, 0xbfb8aa3b, v90
	v_add_f32_e32 v100, 1.0, v100
	v_rcp_f32_e32 v100, v100
	v_exp_f32_e32 v90, v90
	v_mul_f32_e32 v101, 0xbfb8aa3b, v101
	v_exp_f32_e32 v101, v101
	v_fma_mixlo_f16 v102, v62, v100, 0
	v_add_f32_e32 v62, 1.0, v90
	v_rcp_f32_e32 v100, v62
	v_add_f32_e32 v62, 1.0, v101
	v_cvt_f32_f16_sdwa v90, v91 dst_sel:DWORD dst_unused:UNUSED_PAD src0_sel:WORD_1
	v_rcp_f32_e32 v101, v62
	v_mov_b32_e32 v62, v63
	v_mov_b32_e32 v63, v64
	v_cvt_f32_f16_e32 v64, v92
	v_max_f32_e32 v90, 0xc1f00000, v90
	v_mul_f32_e32 v90, 0xbfb8aa3b, v90
	v_exp_f32_e32 v90, v90
	v_max_f32_e32 v64, 0xc1f00000, v64
	v_mul_f32_e32 v64, 0xbfb8aa3b, v64
	v_exp_f32_e32 v64, v64
	v_pk_mul_f32 v[62:63], v[62:63], v[100:101]
	s_nop 0
	v_cvt_pk_f16_f32 v63, v62, v63
	v_add_f32_e32 v62, 1.0, v90
	v_rcp_f32_e32 v90, v62
	v_add_f32_e32 v62, 1.0, v64
	v_rcp_f32_e32 v91, v62
	v_pk_mov_b32 v[64:65], v[64:65], v[58:59] op_sel:[1,0]
	v_cvt_f32_f16_sdwa v58, v92 dst_sel:DWORD dst_unused:UNUSED_PAD src0_sel:WORD_1
	v_pack_b32_f16 v62, v102, v63
	v_pk_mul_f32 v[64:65], v[64:65], v[90:91]
	v_cvt_f32_f16_sdwa v91, v93 dst_sel:DWORD dst_unused:UNUSED_PAD src0_sel:WORD_1
	v_cvt_pk_f16_f32 v90, v64, v65
	v_cvt_f32_f16_e32 v64, v93
	v_max_f32_e32 v58, 0xc1f00000, v58
	v_mul_f32_e32 v58, 0xbfb8aa3b, v58
	v_exp_f32_e32 v58, v58
	v_max_f32_e32 v64, 0xc1f00000, v64
	v_mul_f32_e32 v64, 0xbfb8aa3b, v64
	v_exp_f32_e32 v65, v64
	v_add_f32_e32 v58, 1.0, v58
	v_rcp_f32_e32 v64, v58
	v_alignbit_b32 v63, v90, v63, 16
	v_add_f32_e32 v58, 1.0, v65
	v_rcp_f32_e32 v65, v58
	v_mov_b32_e32 v58, v59
	v_mov_b32_e32 v59, v60
	v_cvt_f32_f16_e32 v60, v94
	v_pk_mul_f32 v[58:59], v[58:59], v[64:65]
	s_nop 0
	v_cvt_pk_f16_f32 v58, v58, v59
	v_max_f32_e32 v59, 0xc1f00000, v91
	v_mul_f32_e32 v59, 0xbfb8aa3b, v59
	v_exp_f32_e32 v59, v59
	v_alignbit_b32 v64, v58, v90, 16
	v_lshrrev_b32_e32 v65, 16, v58
	v_add_f32_e32 v58, 1.0, v59
	v_rcp_f32_e32 v58, v58
	v_max_f32_e32 v59, 0xc1f00000, v60
	v_mul_f32_e32 v59, 0xbfb8aa3b, v59
	v_exp_f32_e32 v59, v59
	v_fma_mixhi_f16 v65, v61, v58, 0
	v_cvt_f32_f16_sdwa v58, v94 dst_sel:DWORD dst_unused:UNUSED_PAD src0_sel:WORD_1
	v_cvt_f32_f16_e32 v60, v95
	v_add_f32_e32 v59, 1.0, v59
	v_rcp_f32_e32 v59, v59
	v_max_f32_e32 v58, 0xc1f00000, v58
	v_mul_f32_e32 v58, 0xbfb8aa3b, v58
	v_max_f32_e32 v60, 0xc1f00000, v60
	v_exp_f32_e32 v58, v58
	v_mul_f32_e32 v60, 0xbfb8aa3b, v60
	v_exp_f32_e32 v60, v60
	v_fma_mixlo_f16 v61, v54, v59, 0
	v_add_f32_e32 v54, 1.0, v58
	v_rcp_f32_e32 v58, v54
	v_add_f32_e32 v54, 1.0, v60
	v_rcp_f32_e32 v59, v54
	v_cvt_f32_f16_sdwa v60, v95 dst_sel:DWORD dst_unused:UNUSED_PAD src0_sel:WORD_1
	v_mov_b32_e32 v54, v55
	v_mov_b32_e32 v55, v56
	v_cvt_f32_f16_e32 v56, v96
	v_max_f32_e32 v60, 0xc1f00000, v60
	v_mul_f32_e32 v60, 0xbfb8aa3b, v60
	v_exp_f32_e32 v60, v60
	v_max_f32_e32 v56, 0xc1f00000, v56
	v_mul_f32_e32 v56, 0xbfb8aa3b, v56
	v_exp_f32_e32 v56, v56
	v_pk_mul_f32 v[54:55], v[54:55], v[58:59]
	v_add_f32_e32 v58, 1.0, v60
	v_rcp_f32_e32 v58, v58
	v_add_f32_e32 v56, 1.0, v56
	v_rcp_f32_e32 v59, v56
	v_pk_mov_b32 v[56:57], v[56:57], v[50:51] op_sel:[1,0]
	v_cvt_f32_f16_sdwa v50, v96 dst_sel:DWORD dst_unused:UNUSED_PAD src0_sel:WORD_1
	v_cvt_pk_f16_f32 v55, v54, v55
	v_pk_mul_f32 v[56:57], v[56:57], v[58:59]
	v_cvt_f32_f16_sdwa v59, v97 dst_sel:DWORD dst_unused:UNUSED_PAD src0_sel:WORD_1
	v_cvt_pk_f16_f32 v58, v56, v57
	v_cvt_f32_f16_e32 v56, v97
	v_max_f32_e32 v50, 0xc1f00000, v50
	v_mul_f32_e32 v50, 0xbfb8aa3b, v50
	v_exp_f32_e32 v50, v50
	v_max_f32_e32 v56, 0xc1f00000, v56
	v_mul_f32_e32 v56, 0xbfb8aa3b, v56
	v_exp_f32_e32 v57, v56
	v_add_f32_e32 v50, 1.0, v50
	v_rcp_f32_e32 v56, v50
	v_pack_b32_f16 v54, v61, v55
	v_add_f32_e32 v50, 1.0, v57
	v_rcp_f32_e32 v57, v50
	v_mov_b32_e32 v50, v51
	v_max_f32_e32 v51, 0xc1f00000, v59
	v_mul_f32_e32 v51, 0xbfb8aa3b, v51
	v_exp_f32_e32 v59, v51
	v_mov_b32_e32 v51, v52
	v_pk_mul_f32 v[50:51], v[50:51], v[56:57]
	v_cvt_f32_f16_e32 v52, v86
	v_cvt_pk_f16_f32 v50, v50, v51
	v_add_f32_e32 v51, 1.0, v59
	v_rcp_f32_e32 v51, v51
	v_alignbit_b32 v56, v50, v58, 16
	v_lshrrev_b32_e32 v57, 16, v50
	v_max_f32_e32 v50, 0xc1f00000, v52
	v_alignbit_b32 v55, v58, v55, 16
	v_fma_mixhi_f16 v57, v53, v51, 0
	v_mul_f32_e32 v50, 0xbfb8aa3b, v50
	v_cvt_f32_f16_sdwa v53, v86 dst_sel:DWORD dst_unused:UNUSED_PAD src0_sel:WORD_1
	v_exp_f32_e32 v52, v50
	global_store_dwordx4 v[98:99], v[54:57], off offset:256
	v_lshl_add_u64 v[50:51], v[192:193], 0, v[182:183]
	v_max_f32_e32 v53, 0xc1f00000, v53
	v_cvt_f32_f16_e32 v54, v87
	v_add_f32_e32 v52, 1.0, v52
	v_mul_f32_e32 v53, 0xbfb8aa3b, v53
	v_rcp_f32_e32 v52, v52
	v_max_f32_e32 v54, 0xc1f00000, v54
	v_exp_f32_e32 v53, v53
	v_mul_f32_e32 v54, 0xbfb8aa3b, v54
	v_exp_f32_e32 v54, v54
	v_fma_mixlo_f16 v55, v46, v52, 0
	v_add_f32_e32 v46, 1.0, v53
	v_rcp_f32_e32 v52, v46
	v_add_f32_e32 v46, 1.0, v54
	v_rcp_f32_e32 v53, v46
	v_cvt_f32_f16_sdwa v54, v87 dst_sel:DWORD dst_unused:UNUSED_PAD src0_sel:WORD_1
	v_mov_b32_e32 v46, v47
	v_mov_b32_e32 v47, v48
	v_cvt_f32_f16_e32 v48, v88
	v_pk_mul_f32 v[46:47], v[46:47], v[52:53]
	v_max_f32_e32 v52, 0xc1f00000, v54
	v_mul_f32_e32 v52, 0xbfb8aa3b, v52
	v_max_f32_e32 v48, 0xc1f00000, v48
	v_exp_f32_e32 v52, v52
	v_mul_f32_e32 v48, 0xbfb8aa3b, v48
	v_exp_f32_e32 v48, v48
	v_cvt_pk_f16_f32 v47, v46, v47
	v_add_f32_e32 v46, 1.0, v52
	v_rcp_f32_e32 v52, v46
	v_add_f32_e32 v46, 1.0, v48
	v_rcp_f32_e32 v53, v46
	v_pk_mov_b32 v[48:49], v[48:49], v[42:43] op_sel:[1,0]
	v_cvt_f32_f16_sdwa v42, v88 dst_sel:DWORD dst_unused:UNUSED_PAD src0_sel:WORD_1
	v_pack_b32_f16 v46, v55, v47
	v_pk_mul_f32 v[48:49], v[48:49], v[52:53]
	v_cvt_f32_f16_sdwa v53, v89 dst_sel:DWORD dst_unused:UNUSED_PAD src0_sel:WORD_1
	v_cvt_pk_f16_f32 v52, v48, v49
	v_cvt_f32_f16_e32 v48, v89
	v_max_f32_e32 v42, 0xc1f00000, v42
	v_mul_f32_e32 v42, 0xbfb8aa3b, v42
	v_exp_f32_e32 v42, v42
	v_max_f32_e32 v48, 0xc1f00000, v48
	v_mul_f32_e32 v48, 0xbfb8aa3b, v48
	v_exp_f32_e32 v49, v48
	v_add_f32_e32 v42, 1.0, v42
	v_rcp_f32_e32 v48, v42
	v_alignbit_b32 v47, v52, v47, 16
	v_add_f32_e32 v42, 1.0, v49
	v_rcp_f32_e32 v49, v42
	v_mov_b32_e32 v42, v43
	v_mov_b32_e32 v43, v44
	v_cvt_f32_f16_e32 v44, v82
	v_pk_mul_f32 v[42:43], v[42:43], v[48:49]
	global_store_dwordx4 v[98:99], v[62:65], off
	v_cvt_pk_f16_f32 v42, v42, v43
	v_max_f32_e32 v43, 0xc1f00000, v53
	v_mul_f32_e32 v43, 0xbfb8aa3b, v43
	v_exp_f32_e32 v43, v43
	v_alignbit_b32 v48, v42, v52, 16
	v_lshrrev_b32_e32 v49, 16, v42
	v_add_f32_e32 v42, 1.0, v43
	v_rcp_f32_e32 v42, v42
	v_max_f32_e32 v43, 0xc1f00000, v44
	v_mul_f32_e32 v43, 0xbfb8aa3b, v43
	v_exp_f32_e32 v43, v43
	v_fma_mixhi_f16 v49, v45, v42, 0
	v_cvt_f32_f16_sdwa v42, v82 dst_sel:DWORD dst_unused:UNUSED_PAD src0_sel:WORD_1
	v_cvt_f32_f16_e32 v44, v83
	v_add_f32_e32 v43, 1.0, v43
	v_rcp_f32_e32 v43, v43
	v_max_f32_e32 v42, 0xc1f00000, v42
	v_mul_f32_e32 v42, 0xbfb8aa3b, v42
	v_max_f32_e32 v44, 0xc1f00000, v44
	v_exp_f32_e32 v42, v42
	v_mul_f32_e32 v44, 0xbfb8aa3b, v44
	v_exp_f32_e32 v44, v44
	v_fma_mixlo_f16 v45, v38, v43, 0
	v_add_f32_e32 v38, 1.0, v42
	v_rcp_f32_e32 v42, v38
	v_add_f32_e32 v38, 1.0, v44
	v_rcp_f32_e32 v43, v38
	v_cvt_f32_f16_sdwa v44, v83 dst_sel:DWORD dst_unused:UNUSED_PAD src0_sel:WORD_1
	v_mov_b32_e32 v38, v39
	v_mov_b32_e32 v39, v40
	v_cvt_f32_f16_e32 v40, v84
	v_max_f32_e32 v44, 0xc1f00000, v44
	v_mul_f32_e32 v44, 0xbfb8aa3b, v44
	v_exp_f32_e32 v44, v44
	v_max_f32_e32 v40, 0xc1f00000, v40
	v_mul_f32_e32 v40, 0xbfb8aa3b, v40
	v_exp_f32_e32 v40, v40
	v_pk_mul_f32 v[38:39], v[38:39], v[42:43]
	v_add_f32_e32 v42, 1.0, v44
	v_rcp_f32_e32 v42, v42
	v_add_f32_e32 v40, 1.0, v40
	v_rcp_f32_e32 v43, v40
	v_pk_mov_b32 v[40:41], v[40:41], v[34:35] op_sel:[1,0]
	v_cvt_f32_f16_sdwa v34, v84 dst_sel:DWORD dst_unused:UNUSED_PAD src0_sel:WORD_1
	v_cvt_pk_f16_f32 v39, v38, v39
	v_pk_mul_f32 v[40:41], v[40:41], v[42:43]
	v_cvt_f32_f16_sdwa v43, v85 dst_sel:DWORD dst_unused:UNUSED_PAD src0_sel:WORD_1
	v_cvt_pk_f16_f32 v42, v40, v41
	v_cvt_f32_f16_e32 v40, v85
	v_max_f32_e32 v34, 0xc1f00000, v34
	v_mul_f32_e32 v34, 0xbfb8aa3b, v34
	v_exp_f32_e32 v34, v34
	v_max_f32_e32 v40, 0xc1f00000, v40
	v_mul_f32_e32 v40, 0xbfb8aa3b, v40
	v_exp_f32_e32 v41, v40
	v_add_f32_e32 v34, 1.0, v34
	v_rcp_f32_e32 v40, v34
	v_pack_b32_f16 v38, v45, v39
	v_add_f32_e32 v34, 1.0, v41
	v_rcp_f32_e32 v41, v34
	v_mov_b32_e32 v34, v35
	v_max_f32_e32 v35, 0xc1f00000, v43
	v_mul_f32_e32 v35, 0xbfb8aa3b, v35
	v_exp_f32_e32 v43, v35
	v_mov_b32_e32 v35, v36
	v_pk_mul_f32 v[34:35], v[34:35], v[40:41]
	v_cvt_f32_f16_e32 v36, v78
	v_cvt_pk_f16_f32 v34, v34, v35
	v_add_f32_e32 v35, 1.0, v43
	v_rcp_f32_e32 v35, v35
	v_alignbit_b32 v40, v34, v42, 16
	v_lshrrev_b32_e32 v41, 16, v34
	v_max_f32_e32 v34, 0xc1f00000, v36
	v_alignbit_b32 v39, v42, v39, 16
	v_fma_mixhi_f16 v41, v37, v35, 0
	v_mul_f32_e32 v34, 0xbfb8aa3b, v34
	v_cvt_f32_f16_sdwa v37, v78 dst_sel:DWORD dst_unused:UNUSED_PAD src0_sel:WORD_1
	v_exp_f32_e32 v36, v34
	global_store_dwordx4 v[50:51], v[38:41], off offset:256
	v_lshl_add_u64 v[34:35], v[192:193], 0, v[184:185]
	v_max_f32_e32 v37, 0xc1f00000, v37
	v_cvt_f32_f16_e32 v38, v79
	v_add_f32_e32 v36, 1.0, v36
	v_mul_f32_e32 v37, 0xbfb8aa3b, v37
	v_rcp_f32_e32 v36, v36
	v_max_f32_e32 v38, 0xc1f00000, v38
	v_exp_f32_e32 v37, v37
	v_mul_f32_e32 v38, 0xbfb8aa3b, v38
	v_exp_f32_e32 v38, v38
	v_fma_mixlo_f16 v39, v28, v36, 0
	v_add_f32_e32 v28, 1.0, v37
	v_rcp_f32_e32 v36, v28
	v_add_f32_e32 v28, 1.0, v38
	v_rcp_f32_e32 v37, v28
	v_cvt_f32_f16_sdwa v38, v79 dst_sel:DWORD dst_unused:UNUSED_PAD src0_sel:WORD_1
	v_mov_b32_e32 v28, v29
	v_mov_b32_e32 v29, v30
	v_cvt_f32_f16_e32 v30, v80
	v_pk_mul_f32 v[28:29], v[28:29], v[36:37]
	v_max_f32_e32 v36, 0xc1f00000, v38
	v_mul_f32_e32 v36, 0xbfb8aa3b, v36
	v_max_f32_e32 v30, 0xc1f00000, v30
	v_exp_f32_e32 v36, v36
	v_mul_f32_e32 v30, 0xbfb8aa3b, v30
	v_exp_f32_e32 v30, v30
	v_cvt_pk_f16_f32 v29, v28, v29
	v_add_f32_e32 v28, 1.0, v36
	v_rcp_f32_e32 v36, v28
	v_add_f32_e32 v28, 1.0, v30
	v_rcp_f32_e32 v37, v28
	v_pk_mov_b32 v[30:31], v[30:31], v[24:25] op_sel:[1,0]
	v_cvt_f32_f16_sdwa v24, v80 dst_sel:DWORD dst_unused:UNUSED_PAD src0_sel:WORD_1
	v_pack_b32_f16 v28, v39, v29
	v_pk_mul_f32 v[30:31], v[30:31], v[36:37]
	v_cvt_f32_f16_sdwa v37, v81 dst_sel:DWORD dst_unused:UNUSED_PAD src0_sel:WORD_1
	v_cvt_pk_f16_f32 v36, v30, v31
	v_cvt_f32_f16_e32 v30, v81
	v_max_f32_e32 v24, 0xc1f00000, v24
	v_mul_f32_e32 v24, 0xbfb8aa3b, v24
	v_exp_f32_e32 v24, v24
	v_max_f32_e32 v30, 0xc1f00000, v30
	v_mul_f32_e32 v30, 0xbfb8aa3b, v30
	v_exp_f32_e32 v31, v30
	v_add_f32_e32 v24, 1.0, v24
	v_rcp_f32_e32 v30, v24
	v_alignbit_b32 v29, v36, v29, 16
	v_add_f32_e32 v24, 1.0, v31
	v_rcp_f32_e32 v31, v24
	v_mov_b32_e32 v24, v25
	v_mov_b32_e32 v25, v26
	v_cvt_f32_f16_e32 v26, v74
	v_pk_mul_f32 v[24:25], v[24:25], v[30:31]
	global_store_dwordx4 v[50:51], v[46:49], off
	v_cvt_pk_f16_f32 v24, v24, v25
	v_max_f32_e32 v25, 0xc1f00000, v37
	v_mul_f32_e32 v25, 0xbfb8aa3b, v25
	v_exp_f32_e32 v25, v25
	v_alignbit_b32 v30, v24, v36, 16
	v_lshrrev_b32_e32 v31, 16, v24
	v_add_f32_e32 v24, 1.0, v25
	v_rcp_f32_e32 v24, v24
	v_max_f32_e32 v25, 0xc1f00000, v26
	v_mul_f32_e32 v25, 0xbfb8aa3b, v25
	v_exp_f32_e32 v25, v25
	v_fma_mixhi_f16 v31, v27, v24, 0
	v_cvt_f32_f16_sdwa v24, v74 dst_sel:DWORD dst_unused:UNUSED_PAD src0_sel:WORD_1
	v_cvt_f32_f16_e32 v26, v75
	v_add_f32_e32 v25, 1.0, v25
	v_rcp_f32_e32 v25, v25
	v_max_f32_e32 v24, 0xc1f00000, v24
	v_mul_f32_e32 v24, 0xbfb8aa3b, v24
	v_max_f32_e32 v26, 0xc1f00000, v26
	v_exp_f32_e32 v24, v24
	v_mul_f32_e32 v26, 0xbfb8aa3b, v26
	v_exp_f32_e32 v26, v26
	v_fma_mixlo_f16 v27, v20, v25, 0
	v_add_f32_e32 v20, 1.0, v24
	v_rcp_f32_e32 v24, v20
	v_add_f32_e32 v20, 1.0, v26
	v_rcp_f32_e32 v25, v20
	v_cvt_f32_f16_sdwa v26, v75 dst_sel:DWORD dst_unused:UNUSED_PAD src0_sel:WORD_1
	v_mov_b32_e32 v20, v21
	v_mov_b32_e32 v21, v22
	v_cvt_f32_f16_e32 v22, v76
	v_max_f32_e32 v26, 0xc1f00000, v26
	v_mul_f32_e32 v26, 0xbfb8aa3b, v26
	v_exp_f32_e32 v26, v26
	v_max_f32_e32 v22, 0xc1f00000, v22
	v_mul_f32_e32 v22, 0xbfb8aa3b, v22
	v_exp_f32_e32 v22, v22
	v_pk_mul_f32 v[20:21], v[20:21], v[24:25]
	v_add_f32_e32 v24, 1.0, v26
	v_rcp_f32_e32 v24, v24
	v_add_f32_e32 v22, 1.0, v22
	v_rcp_f32_e32 v25, v22
	v_pk_mov_b32 v[22:23], v[22:23], v[16:17] op_sel:[1,0]
	v_cvt_f32_f16_sdwa v16, v76 dst_sel:DWORD dst_unused:UNUSED_PAD src0_sel:WORD_1
	v_cvt_pk_f16_f32 v21, v20, v21
	v_pk_mul_f32 v[22:23], v[22:23], v[24:25]
	v_cvt_f32_f16_sdwa v25, v77 dst_sel:DWORD dst_unused:UNUSED_PAD src0_sel:WORD_1
	v_cvt_pk_f16_f32 v24, v22, v23
	v_cvt_f32_f16_e32 v22, v77
	v_max_f32_e32 v16, 0xc1f00000, v16
	v_mul_f32_e32 v16, 0xbfb8aa3b, v16
	v_exp_f32_e32 v16, v16
	v_max_f32_e32 v22, 0xc1f00000, v22
	v_mul_f32_e32 v22, 0xbfb8aa3b, v22
	v_exp_f32_e32 v23, v22
	v_add_f32_e32 v16, 1.0, v16
	v_rcp_f32_e32 v22, v16
	v_pack_b32_f16 v20, v27, v21
	v_add_f32_e32 v16, 1.0, v23
	v_rcp_f32_e32 v23, v16
	v_mov_b32_e32 v16, v17
	v_max_f32_e32 v17, 0xc1f00000, v25
	v_mul_f32_e32 v17, 0xbfb8aa3b, v17
	v_exp_f32_e32 v25, v17
	v_mov_b32_e32 v17, v18
	v_pk_mul_f32 v[16:17], v[16:17], v[22:23]
	v_cvt_f32_f16_e32 v18, v70
	v_cvt_pk_f16_f32 v16, v16, v17
	v_add_f32_e32 v17, 1.0, v25
	v_rcp_f32_e32 v17, v17
	v_alignbit_b32 v22, v16, v24, 16
	v_lshrrev_b32_e32 v23, 16, v16
	v_max_f32_e32 v16, 0xc1f00000, v18
	v_alignbit_b32 v21, v24, v21, 16
	v_fma_mixhi_f16 v23, v19, v17, 0
	v_mul_f32_e32 v16, 0xbfb8aa3b, v16
	v_cvt_f32_f16_sdwa v19, v70 dst_sel:DWORD dst_unused:UNUSED_PAD src0_sel:WORD_1
	v_exp_f32_e32 v18, v16
	global_store_dwordx4 v[34:35], v[20:23], off offset:256
	v_lshl_add_u64 v[16:17], v[192:193], 0, v[186:187]
	v_max_f32_e32 v19, 0xc1f00000, v19
	v_cvt_f32_f16_e32 v20, v71
	v_add_f32_e32 v18, 1.0, v18
	v_mul_f32_e32 v19, 0xbfb8aa3b, v19
	v_rcp_f32_e32 v18, v18
	v_max_f32_e32 v20, 0xc1f00000, v20
	v_exp_f32_e32 v19, v19
	v_mul_f32_e32 v20, 0xbfb8aa3b, v20
	v_exp_f32_e32 v20, v20
	v_fma_mixlo_f16 v21, v12, v18, 0
	v_add_f32_e32 v12, 1.0, v19
	v_rcp_f32_e32 v18, v12
	v_add_f32_e32 v12, 1.0, v20
	v_rcp_f32_e32 v19, v12
	v_cvt_f32_f16_sdwa v20, v71 dst_sel:DWORD dst_unused:UNUSED_PAD src0_sel:WORD_1
	v_mov_b32_e32 v12, v13
	v_mov_b32_e32 v13, v14
	v_cvt_f32_f16_e32 v14, v72
	v_pk_mul_f32 v[12:13], v[12:13], v[18:19]
	v_max_f32_e32 v18, 0xc1f00000, v20
	v_mul_f32_e32 v18, 0xbfb8aa3b, v18
	v_max_f32_e32 v14, 0xc1f00000, v14
	v_exp_f32_e32 v18, v18
	v_mul_f32_e32 v14, 0xbfb8aa3b, v14
	v_exp_f32_e32 v14, v14
	v_cvt_pk_f16_f32 v13, v12, v13
	v_add_f32_e32 v12, 1.0, v18
	v_rcp_f32_e32 v18, v12
	v_add_f32_e32 v12, 1.0, v14
	v_rcp_f32_e32 v19, v12
	v_pk_mov_b32 v[14:15], v[14:15], v[8:9] op_sel:[1,0]
	v_cvt_f32_f16_sdwa v8, v72 dst_sel:DWORD dst_unused:UNUSED_PAD src0_sel:WORD_1
	v_pack_b32_f16 v12, v21, v13
	v_pk_mul_f32 v[14:15], v[14:15], v[18:19]
	v_cvt_f32_f16_sdwa v19, v73 dst_sel:DWORD dst_unused:UNUSED_PAD src0_sel:WORD_1
	v_cvt_pk_f16_f32 v18, v14, v15
	v_cvt_f32_f16_e32 v14, v73
	v_max_f32_e32 v8, 0xc1f00000, v8
	v_mul_f32_e32 v8, 0xbfb8aa3b, v8
	v_exp_f32_e32 v8, v8
	v_max_f32_e32 v14, 0xc1f00000, v14
	v_mul_f32_e32 v14, 0xbfb8aa3b, v14
	v_exp_f32_e32 v15, v14
	v_add_f32_e32 v8, 1.0, v8
	v_rcp_f32_e32 v14, v8
	v_alignbit_b32 v13, v18, v13, 16
	v_add_f32_e32 v8, 1.0, v15
	v_rcp_f32_e32 v15, v8
	v_mov_b32_e32 v8, v9
	v_mov_b32_e32 v9, v10
	v_cvt_f32_f16_e32 v10, v66
	v_pk_mul_f32 v[8:9], v[8:9], v[14:15]
	global_store_dwordx4 v[34:35], v[28:31], off
	v_cvt_pk_f16_f32 v8, v8, v9
	v_max_f32_e32 v9, 0xc1f00000, v19
	v_mul_f32_e32 v9, 0xbfb8aa3b, v9
	v_exp_f32_e32 v9, v9
	v_alignbit_b32 v14, v8, v18, 16
	v_lshrrev_b32_e32 v15, 16, v8
	v_add_f32_e32 v8, 1.0, v9
	v_rcp_f32_e32 v8, v8
	v_max_f32_e32 v9, 0xc1f00000, v10
	v_mul_f32_e32 v9, 0xbfb8aa3b, v9
	v_exp_f32_e32 v9, v9
	v_fma_mixhi_f16 v15, v11, v8, 0
	v_cvt_f32_f16_sdwa v8, v66 dst_sel:DWORD dst_unused:UNUSED_PAD src0_sel:WORD_1
	v_cvt_f32_f16_e32 v10, v67
	v_add_f32_e32 v9, 1.0, v9
	v_rcp_f32_e32 v9, v9
	v_max_f32_e32 v8, 0xc1f00000, v8
	v_mul_f32_e32 v8, 0xbfb8aa3b, v8
	v_max_f32_e32 v10, 0xc1f00000, v10
	v_exp_f32_e32 v8, v8
	v_mul_f32_e32 v10, 0xbfb8aa3b, v10
	v_exp_f32_e32 v10, v10
	v_fma_mixlo_f16 v11, v4, v9, 0
	v_add_f32_e32 v4, 1.0, v8
	v_rcp_f32_e32 v8, v4
	v_add_f32_e32 v4, 1.0, v10
	v_rcp_f32_e32 v9, v4
	v_cvt_f32_f16_sdwa v10, v67 dst_sel:DWORD dst_unused:UNUSED_PAD src0_sel:WORD_1
	v_mov_b32_e32 v4, v5
	v_mov_b32_e32 v5, v6
	v_cvt_f32_f16_e32 v6, v68
	v_max_f32_e32 v10, 0xc1f00000, v10
	v_mul_f32_e32 v10, 0xbfb8aa3b, v10
	v_exp_f32_e32 v10, v10
	v_max_f32_e32 v6, 0xc1f00000, v6
	v_mul_f32_e32 v6, 0xbfb8aa3b, v6
	v_exp_f32_e32 v6, v6
	v_pk_mul_f32 v[4:5], v[4:5], v[8:9]
	v_add_f32_e32 v8, 1.0, v10
	v_rcp_f32_e32 v8, v8
	v_add_f32_e32 v6, 1.0, v6
	v_rcp_f32_e32 v9, v6
	v_pk_mov_b32 v[6:7], v[6:7], v[0:1] op_sel:[1,0]
	v_cvt_f32_f16_sdwa v0, v68 dst_sel:DWORD dst_unused:UNUSED_PAD src0_sel:WORD_1
	v_cvt_pk_f16_f32 v5, v4, v5
	v_pk_mul_f32 v[6:7], v[6:7], v[8:9]
	v_cvt_f32_f16_sdwa v9, v69 dst_sel:DWORD dst_unused:UNUSED_PAD src0_sel:WORD_1
	v_cvt_pk_f16_f32 v8, v6, v7
	v_cvt_f32_f16_e32 v6, v69
	v_max_f32_e32 v0, 0xc1f00000, v0
	v_mul_f32_e32 v0, 0xbfb8aa3b, v0
	v_exp_f32_e32 v0, v0
	v_max_f32_e32 v6, 0xc1f00000, v6
	v_mul_f32_e32 v6, 0xbfb8aa3b, v6
	v_exp_f32_e32 v7, v6
	v_add_f32_e32 v0, 1.0, v0
	v_rcp_f32_e32 v6, v0
	v_pack_b32_f16 v4, v11, v5
	v_add_f32_e32 v0, 1.0, v7
	v_rcp_f32_e32 v7, v0
	v_max_f32_e32 v0, 0xc1f00000, v9
	v_mul_f32_e32 v0, 0xbfb8aa3b, v0
	v_exp_f32_e32 v9, v0
	v_mov_b32_e32 v0, v1
	v_mov_b32_e32 v1, v2
	v_pk_mul_f32 v[0:1], v[0:1], v[6:7]
	v_add_f32_e32 v2, 1.0, v9
	v_rcp_f32_e32 v2, v2
	v_cvt_pk_f16_f32 v0, v0, v1
	v_lshrrev_b32_e32 v7, 16, v0
	v_alignbit_b32 v5, v8, v5, 16
	v_alignbit_b32 v6, v0, v8, 16
	v_fma_mixhi_f16 v7, v3, v2, 0
	global_store_dwordx4 v[16:17], v[12:15], off
	global_store_dwordx4 v[16:17], v[4:7], off offset:256
	s_and_b64 vcc, exec, s[4:5]
	s_mov_b32 s31, s30
	s_mov_b32 s34, s29
	s_mov_b64 s[12:13], s[0:1]
	s_mov_b64 s[10:11], s[2:3]
	s_cbranch_vccz .LBB0_955
	s_waitcnt vmcnt(0)
	s_cmpk_gt_u32 s19, 0xff
	s_cbranch_scc1 .LBB0_962
	s_barrier

.LBB0_1117:
	s_add_i32 s41, s22, 2
	s_add_u32 s20, s14, 0x100
	s_addc_u32 s21, s15, 0
	s_add_i32 s42, 0, 0x10000
	s_waitcnt vmcnt(0)
	v_add_u32_e32 v102, s42, v230
	ds_read_b128 v[78:81], v102
	ds_read_b128 v[94:97], v102 offset:2048
	ds_read_b128 v[86:89], v102 offset:1024
	ds_read_b128 v[102:105], v102 offset:3072
	s_cmp_eq_u32 s38, s22
	s_cselect_b32 s22, s18, s39
	s_cselect_b32 s25, s17, s21
	s_cselect_b32 s24, s16, s20
	s_cselect_b32 s23, s19, s40
	v_lshl_add_u64 v[178:179], s[14:15], 0, v[200:201]
	s_add_i32 m0, s28, 0xc000
	ds_read_b128 v[122:125], v232
	ds_read_b128 v[130:133], v232 offset:2048
	ds_read_b128 v[154:157], v232 offset:4096
	ds_read_b128 v[170:173], v232 offset:6144
	ds_read_b128 v[126:129], v232 offset:1024
	ds_read_b128 v[134:137], v232 offset:3072
	ds_read_b128 v[158:161], v232 offset:5120
	ds_read_b128 v[174:177], v232 offset:7168
	global_load_lds_dwordx4 v[178:179], off
	v_lshl_add_u64 v[178:179], s[14:15], 0, v[202:203]
	s_add_i32 m0, s28, 0xe000
	s_nop 0
	global_load_lds_dwordx4 v[178:179], off
	s_waitcnt lgkmcnt(8)
	s_barrier
	s_waitcnt lgkmcnt(7)
	v_mfma_f32_16x16x32_f16 v[166:169], v[78:81], v[122:125], v[166:169]
	v_mfma_f32_16x16x32_f16 v[162:165], v[94:97], v[122:125], v[162:165]
	s_waitcnt lgkmcnt(6)
	v_mfma_f32_16x16x32_f16 v[150:153], v[78:81], v[130:133], v[150:153]
	v_mfma_f32_16x16x32_f16 v[142:145], v[94:97], v[130:133], v[142:145]
	s_waitcnt lgkmcnt(5)
	v_mfma_f32_16x16x32_f16 v[110:113], v[78:81], v[154:157], v[110:113]
	v_mfma_f32_16x16x32_f16 v[106:109], v[94:97], v[154:157], v[106:109]
	s_waitcnt lgkmcnt(4)
	v_mfma_f32_16x16x32_f16 v[82:85], v[78:81], v[170:173], v[82:85]
	v_mfma_f32_16x16x32_f16 v[74:77], v[94:97], v[170:173], v[74:77]
	s_waitcnt lgkmcnt(3)
	v_mfma_f32_16x16x32_f16 v[166:169], v[86:89], v[126:129], v[166:169]
	v_mfma_f32_16x16x32_f16 v[162:165], v[102:105], v[126:129], v[162:165]
	s_waitcnt lgkmcnt(2)
	v_mfma_f32_16x16x32_f16 v[150:153], v[86:89], v[134:137], v[150:153]
	v_mfma_f32_16x16x32_f16 v[142:145], v[102:105], v[134:137], v[142:145]
	s_waitcnt lgkmcnt(1)
	v_mfma_f32_16x16x32_f16 v[110:113], v[86:89], v[158:161], v[110:113]
	v_mfma_f32_16x16x32_f16 v[106:109], v[102:105], v[158:161], v[106:109]
	s_waitcnt lgkmcnt(0)
	v_mfma_f32_16x16x32_f16 v[82:85], v[86:89], v[174:177], v[82:85]
	v_mfma_f32_16x16x32_f16 v[74:77], v[102:105], v[174:177], v[74:77]
	s_barrier
	s_add_i32 s43, 0, 0x14000
	s_add_i32 s14, s42, s13
	v_add_u32_e32 v190, s43, v230
	v_lshl_add_u64 v[204:205], s[22:23], 0, v[32:33]
	s_mov_b32 m0, s14
	ds_read_b128 v[178:181], v190
	ds_read_b128 v[186:189], v190 offset:2048
	ds_read_b128 v[182:185], v190 offset:1024
	ds_read_b128 v[190:193], v190 offset:3072
	global_load_lds_dwordx4 v[204:205], off
	v_lshl_add_u64 v[206:207], s[22:23], 0, v[198:199]
	s_add_i32 m0, s14, 0x2000
	s_nop 0
	global_load_lds_dwordx4 v[206:207], off
	s_barrier
	s_waitcnt lgkmcnt(3)
	v_mfma_f32_16x16x32_f16 v[146:149], v[178:181], v[122:125], v[146:149]
	v_mfma_f32_16x16x32_f16 v[118:121], v[178:181], v[130:133], v[118:121]
	s_waitcnt lgkmcnt(2)
	v_mfma_f32_16x16x32_f16 v[114:117], v[186:189], v[130:133], v[114:117]
	v_mfma_f32_16x16x32_f16 v[98:101], v[178:181], v[154:157], v[98:101]
	v_mfma_f32_16x16x32_f16 v[90:93], v[186:189], v[154:157], v[90:93]
	v_mfma_f32_16x16x32_f16 v[70:73], v[178:181], v[170:173], v[70:73]
	s_waitcnt lgkmcnt(1)
	v_mfma_f32_16x16x32_f16 v[66:69], v[186:189], v[170:173], v[66:69]
	v_mfma_f32_16x16x32_f16 v[146:149], v[182:185], v[126:129], v[146:149]
	v_mfma_f32_16x16x32_f16 v[122:125], v[186:189], v[122:125], v[138:141]
	v_mfma_f32_16x16x32_f16 v[118:121], v[182:185], v[134:137], v[118:121]
	s_waitcnt lgkmcnt(0)
	v_mfma_f32_16x16x32_f16 v[114:117], v[190:193], v[134:137], v[114:117]
	v_mfma_f32_16x16x32_f16 v[98:101], v[182:185], v[158:161], v[98:101]
	v_mfma_f32_16x16x32_f16 v[90:93], v[190:193], v[158:161], v[90:93]
	v_mfma_f32_16x16x32_f16 v[70:73], v[182:185], v[174:177], v[70:73]
	v_mfma_f32_16x16x32_f16 v[66:69], v[190:193], v[174:177], v[66:69]
	v_mfma_f32_16x16x32_f16 v[122:125], v[190:193], v[126:129], v[122:125]
	s_mov_b32 m0, s28
	v_lshl_add_u64 v[208:209], s[24:25], 0, v[32:33]
	s_barrier
	ds_read_b128 v[126:129], v232 offset:16384
	ds_read_b128 v[134:137], v232 offset:18432
	ds_read_b128 v[154:157], v232 offset:20480
	ds_read_b128 v[170:173], v232 offset:22528
	ds_read_b128 v[130:133], v232 offset:17408
	ds_read_b128 v[138:141], v232 offset:19456
	ds_read_b128 v[158:161], v232 offset:21504
	ds_read_b128 v[174:177], v232 offset:23552
	global_load_lds_dwordx4 v[208:209], off
	v_lshl_add_u64 v[210:211], s[24:25], 0, v[198:199]
	s_mov_b32 m0, s29
	s_nop 0
	global_load_lds_dwordx4 v[210:211], off
	s_barrier
	s_waitcnt lgkmcnt(7)
	v_mfma_f32_16x16x32_f16 v[62:65], v[78:81], v[126:129], v[62:65]
	v_mfma_f32_16x16x32_f16 v[58:61], v[94:97], v[126:129], v[58:61]
	s_waitcnt lgkmcnt(6)
	v_mfma_f32_16x16x32_f16 v[46:49], v[78:81], v[134:137], v[46:49]
	v_mfma_f32_16x16x32_f16 v[42:45], v[94:97], v[134:137], v[42:45]
	s_waitcnt lgkmcnt(5)
	v_mfma_f32_16x16x32_f16 v[28:31], v[78:81], v[154:157], v[28:31]
	v_mfma_f32_16x16x32_f16 v[24:27], v[94:97], v[154:157], v[24:27]
	s_waitcnt lgkmcnt(4)
	v_mfma_f32_16x16x32_f16 v[12:15], v[78:81], v[170:173], v[12:15]
	v_mfma_f32_16x16x32_f16 v[8:11], v[94:97], v[170:173], v[8:11]
	s_waitcnt lgkmcnt(3)
	v_mfma_f32_16x16x32_f16 v[62:65], v[86:89], v[130:133], v[62:65]
	v_mfma_f32_16x16x32_f16 v[58:61], v[102:105], v[130:133], v[58:61]
	s_waitcnt lgkmcnt(2)
	v_mfma_f32_16x16x32_f16 v[46:49], v[86:89], v[138:141], v[46:49]
	v_mfma_f32_16x16x32_f16 v[42:45], v[102:105], v[138:141], v[42:45]
	s_waitcnt lgkmcnt(1)
	v_mfma_f32_16x16x32_f16 v[28:31], v[86:89], v[158:161], v[28:31]
	v_mfma_f32_16x16x32_f16 v[24:27], v[102:105], v[158:161], v[24:27]
	s_waitcnt lgkmcnt(0)
	v_mfma_f32_16x16x32_f16 v[12:15], v[86:89], v[174:177], v[12:15]
	v_mfma_f32_16x16x32_f16 v[8:11], v[102:105], v[174:177], v[8:11]
	s_barrier
	s_add_u32 s14, s22, 0x40000
	s_addc_u32 s15, s23, 0
	s_add_i32 s42, s43, s13
	v_lshl_add_u64 v[78:79], s[14:15], 0, v[32:33]
	s_mov_b32 m0, s42
	s_nop 0
	global_load_lds_dwordx4 v[78:79], off
	v_lshl_add_u64 v[78:79], s[14:15], 0, v[198:199]
	s_add_i32 m0, s42, 0x2000
	s_nop 0
	global_load_lds_dwordx4 v[78:79], off
	s_waitcnt vmcnt(6)
	s_barrier
	v_mfma_f32_16x16x32_f16 v[54:57], v[178:181], v[126:129], v[54:57]
	v_mfma_f32_16x16x32_f16 v[50:53], v[186:189], v[126:129], v[50:53]
	v_mfma_f32_16x16x32_f16 v[38:41], v[178:181], v[134:137], v[38:41]
	v_mfma_f32_16x16x32_f16 v[34:37], v[186:189], v[134:137], v[34:37]
	v_mfma_f32_16x16x32_f16 v[20:23], v[178:181], v[154:157], v[20:23]
	v_mfma_f32_16x16x32_f16 v[16:19], v[186:189], v[154:157], v[16:19]
	v_mfma_f32_16x16x32_f16 v[4:7], v[178:181], v[170:173], v[4:7]
	v_mfma_f32_16x16x32_f16 v[0:3], v[186:189], v[170:173], v[0:3]
	v_mfma_f32_16x16x32_f16 v[54:57], v[182:185], v[130:133], v[54:57]
	v_mfma_f32_16x16x32_f16 v[50:53], v[190:193], v[130:133], v[50:53]
	v_mfma_f32_16x16x32_f16 v[38:41], v[182:185], v[138:141], v[38:41]
	v_mfma_f32_16x16x32_f16 v[34:37], v[190:193], v[138:141], v[34:37]
	v_mfma_f32_16x16x32_f16 v[20:23], v[182:185], v[158:161], v[20:23]
	v_mfma_f32_16x16x32_f16 v[16:19], v[190:193], v[158:161], v[16:19]
	v_mfma_f32_16x16x32_f16 v[4:7], v[182:185], v[174:177], v[4:7]
	v_mfma_f32_16x16x32_f16 v[0:3], v[190:193], v[174:177], v[0:3]
	s_add_i32 s42, 0, 0x18000
	v_add_u32_e32 v102, s42, v230
	s_barrier
	ds_read_b128 v[78:81], v102
	ds_read_b128 v[86:89], v102 offset:1024
	ds_read_b128 v[94:97], v102 offset:2048
	ds_read_b128 v[102:105], v102 offset:3072
	s_add_u32 s14, s24, 0x40000
	s_addc_u32 s15, s25, 0
	s_mov_b32 m0, s30
	v_lshl_add_u64 v[138:139], s[14:15], 0, v[32:33]
	ds_read_b128 v[126:129], v232 offset:32768
	ds_read_b128 v[130:133], v232 offset:33792
	ds_read_b128 v[134:137], v232 offset:34816
	ds_read_b128 v[154:157], v232 offset:35840
	ds_read_b128 v[158:161], v232 offset:36864
	ds_read_b128 v[174:177], v232 offset:38912
	ds_read_b128 v[170:173], v232 offset:37888
	ds_read_b128 v[178:181], v232 offset:39936
	global_load_lds_dwordx4 v[138:139], off
	v_lshl_add_u64 v[138:139], s[14:15], 0, v[198:199]
	s_mov_b32 m0, s31
	s_nop 0
	global_load_lds_dwordx4 v[138:139], off
	s_waitcnt lgkmcnt(8)
	s_barrier
	s_waitcnt lgkmcnt(6)
	v_mfma_f32_16x16x32_f16 v[138:141], v[78:81], v[126:129], v[166:169]
	v_mfma_f32_16x16x32_f16 v[166:169], v[86:89], v[130:133], v[138:141]
	v_mfma_f32_16x16x32_f16 v[138:141], v[94:97], v[126:129], v[162:165]
	v_mfma_f32_16x16x32_f16 v[162:165], v[102:105], v[130:133], v[138:141]
	s_waitcnt lgkmcnt(4)
	v_mfma_f32_16x16x32_f16 v[138:141], v[78:81], v[134:137], v[150:153]
	v_mfma_f32_16x16x32_f16 v[150:153], v[86:89], v[154:157], v[138:141]
	s_waitcnt lgkmcnt(3)
	v_mfma_f32_16x16x32_f16 v[138:141], v[94:97], v[134:137], v[142:145]
	v_mfma_f32_16x16x32_f16 v[110:113], v[78:81], v[158:161], v[110:113]
	s_waitcnt lgkmcnt(2)
	v_mfma_f32_16x16x32_f16 v[106:109], v[94:97], v[158:161], v[106:109]
	v_mfma_f32_16x16x32_f16 v[82:85], v[78:81], v[174:177], v[82:85]
	v_mfma_f32_16x16x32_f16 v[74:77], v[94:97], v[174:177], v[74:77]
	v_mfma_f32_16x16x32_f16 v[142:145], v[102:105], v[154:157], v[138:141]
	s_waitcnt lgkmcnt(1)
	v_mfma_f32_16x16x32_f16 v[110:113], v[86:89], v[170:173], v[110:113]
	v_mfma_f32_16x16x32_f16 v[106:109], v[102:105], v[170:173], v[106:109]
	s_waitcnt lgkmcnt(0)
	v_mfma_f32_16x16x32_f16 v[82:85], v[86:89], v[178:181], v[82:85]
	v_mfma_f32_16x16x32_f16 v[74:77], v[102:105], v[178:181], v[74:77]
	s_barrier
	s_add_i32 s24, 0, 0x1c000
	v_add_u32_e32 v138, s24, v230
	s_add_i32 s14, s42, s13
	ds_read_b128 v[182:185], v138
	ds_read_b128 v[190:193], v138 offset:2048
	ds_read_b128 v[186:189], v138 offset:1024
	ds_read_b128 v[194:197], v138 offset:3072
	v_lshl_add_u64 v[138:139], v[204:205], 0, s[84:85]
	s_mov_b32 m0, s14
	s_nop 0
	global_load_lds_dwordx4 v[138:139], off
	v_lshl_add_u64 v[138:139], v[206:207], 0, s[84:85]
	s_add_i32 m0, s14, 0x2000
	s_nop 0
	global_load_lds_dwordx4 v[138:139], off
	s_barrier
	s_waitcnt lgkmcnt(2)
	v_mfma_f32_16x16x32_f16 v[138:141], v[182:185], v[126:129], v[146:149]
	v_mfma_f32_16x16x32_f16 v[122:125], v[190:193], v[126:129], v[122:125]
	v_mfma_f32_16x16x32_f16 v[118:121], v[182:185], v[134:137], v[118:121]
	v_mfma_f32_16x16x32_f16 v[114:117], v[190:193], v[134:137], v[114:117]
	v_mfma_f32_16x16x32_f16 v[98:101], v[182:185], v[158:161], v[98:101]
	v_mfma_f32_16x16x32_f16 v[90:93], v[190:193], v[158:161], v[90:93]
	v_mfma_f32_16x16x32_f16 v[70:73], v[182:185], v[174:177], v[70:73]
	v_mfma_f32_16x16x32_f16 v[66:69], v[190:193], v[174:177], v[66:69]
	s_waitcnt lgkmcnt(0)
	v_mfma_f32_16x16x32_f16 v[146:149], v[186:189], v[130:133], v[138:141]
	v_mfma_f32_16x16x32_f16 v[138:141], v[194:197], v[130:133], v[122:125]
	v_mfma_f32_16x16x32_f16 v[118:121], v[186:189], v[154:157], v[118:121]
	v_mfma_f32_16x16x32_f16 v[114:117], v[194:197], v[154:157], v[114:117]
	v_mfma_f32_16x16x32_f16 v[98:101], v[186:189], v[170:173], v[98:101]
	v_mfma_f32_16x16x32_f16 v[90:93], v[194:197], v[170:173], v[90:93]
	v_mfma_f32_16x16x32_f16 v[70:73], v[186:189], v[178:181], v[70:73]
	v_mfma_f32_16x16x32_f16 v[66:69], v[194:197], v[178:181], v[66:69]
	s_mov_b32 m0, s34
	v_lshl_add_u64 v[178:179], v[208:209], 0, s[84:85]
	s_barrier
	ds_read_b128 v[122:125], v232 offset:49152
	ds_read_b128 v[130:133], v232 offset:51200
	ds_read_b128 v[154:157], v232 offset:53248
	ds_read_b128 v[170:173], v232 offset:55296
	ds_read_b128 v[126:129], v232 offset:50176
	ds_read_b128 v[134:137], v232 offset:52224
	ds_read_b128 v[158:161], v232 offset:54272
	ds_read_b128 v[174:177], v232 offset:56320
	global_load_lds_dwordx4 v[178:179], off
	v_lshl_add_u64 v[178:179], v[210:211], 0, s[84:85]
	s_mov_b32 m0, s35
	s_nop 0
	global_load_lds_dwordx4 v[178:179], off
	s_barrier
	s_waitcnt lgkmcnt(7)
	v_mfma_f32_16x16x32_f16 v[62:65], v[78:81], v[122:125], v[62:65]
	v_mfma_f32_16x16x32_f16 v[58:61], v[94:97], v[122:125], v[58:61]
	s_waitcnt lgkmcnt(6)
	v_mfma_f32_16x16x32_f16 v[46:49], v[78:81], v[130:133], v[46:49]
	v_mfma_f32_16x16x32_f16 v[42:45], v[94:97], v[130:133], v[42:45]
	s_waitcnt lgkmcnt(5)
	v_mfma_f32_16x16x32_f16 v[28:31], v[78:81], v[154:157], v[28:31]
	v_mfma_f32_16x16x32_f16 v[24:27], v[94:97], v[154:157], v[24:27]
	s_waitcnt lgkmcnt(4)
	v_mfma_f32_16x16x32_f16 v[12:15], v[78:81], v[170:173], v[12:15]
	v_mfma_f32_16x16x32_f16 v[8:11], v[94:97], v[170:173], v[8:11]
	s_waitcnt lgkmcnt(3)
	v_mfma_f32_16x16x32_f16 v[62:65], v[86:89], v[126:129], v[62:65]
	v_mfma_f32_16x16x32_f16 v[58:61], v[102:105], v[126:129], v[58:61]
	s_waitcnt lgkmcnt(2)
	v_mfma_f32_16x16x32_f16 v[46:49], v[86:89], v[134:137], v[46:49]
	v_mfma_f32_16x16x32_f16 v[42:45], v[102:105], v[134:137], v[42:45]
	s_waitcnt lgkmcnt(1)
	v_mfma_f32_16x16x32_f16 v[28:31], v[86:89], v[158:161], v[28:31]
	v_mfma_f32_16x16x32_f16 v[24:27], v[102:105], v[158:161], v[24:27]
	s_waitcnt lgkmcnt(0)
	v_mfma_f32_16x16x32_f16 v[12:15], v[86:89], v[174:177], v[12:15]
	v_mfma_f32_16x16x32_f16 v[8:11], v[102:105], v[174:177], v[8:11]
	s_barrier
	s_add_u32 s14, s22, 0x40080
	s_addc_u32 s15, s23, 0
	s_add_i32 s22, s24, s13
	v_lshl_add_u64 v[78:79], s[14:15], 0, v[32:33]
	s_mov_b32 m0, s22
	s_nop 0
	global_load_lds_dwordx4 v[78:79], off
	v_lshl_add_u64 v[78:79], s[14:15], 0, v[198:199]
	s_add_i32 m0, s22, 0x2000
	s_nop 0
	global_load_lds_dwordx4 v[78:79], off
	s_waitcnt vmcnt(6)
	s_barrier
	v_mfma_f32_16x16x32_f16 v[54:57], v[182:185], v[122:125], v[54:57]
	v_mfma_f32_16x16x32_f16 v[50:53], v[190:193], v[122:125], v[50:53]
	v_mfma_f32_16x16x32_f16 v[38:41], v[182:185], v[130:133], v[38:41]
	v_mfma_f32_16x16x32_f16 v[34:37], v[190:193], v[130:133], v[34:37]
	v_mfma_f32_16x16x32_f16 v[20:23], v[182:185], v[154:157], v[20:23]
	v_mfma_f32_16x16x32_f16 v[16:19], v[190:193], v[154:157], v[16:19]
	v_mfma_f32_16x16x32_f16 v[4:7], v[182:185], v[170:173], v[4:7]
	v_mfma_f32_16x16x32_f16 v[0:3], v[190:193], v[170:173], v[0:3]
	v_mfma_f32_16x16x32_f16 v[54:57], v[186:189], v[126:129], v[54:57]
	v_mfma_f32_16x16x32_f16 v[50:53], v[194:197], v[126:129], v[50:53]
	v_mfma_f32_16x16x32_f16 v[38:41], v[186:189], v[134:137], v[38:41]
	v_mfma_f32_16x16x32_f16 v[34:37], v[194:197], v[134:137], v[34:37]
	v_mfma_f32_16x16x32_f16 v[20:23], v[186:189], v[158:161], v[20:23]
	v_mfma_f32_16x16x32_f16 v[16:19], v[194:197], v[158:161], v[16:19]
	v_mfma_f32_16x16x32_f16 v[4:7], v[186:189], v[174:177], v[4:7]
	v_mfma_f32_16x16x32_f16 v[0:3], v[194:197], v[174:177], v[0:3]
	s_add_u32 s39, s39, 0x100
	s_addc_u32 s40, s40, 0
	s_cmp_ge_u32 s41, s37
	s_mov_b64 s[14:15], s[20:21]
	s_mov_b32 s22, s41
	s_barrier
	s_cbranch_scc0 .LBB0_1117
	v_lshl_or_b32 v124, s12, 8, v231
	s_cmp_eq_u32 s10, 0
	s_movk_i32 s12, 0x5000
	s_cselect_b32 s12, 0xe000, s12
	v_readlane_b32 s14, v252, 51
	s_add_u32 s14, s14, s12
	v_readlane_b32 s12, v252, 52
	s_addc_u32 s15, s12, 0
	v_ashrrev_i32_e32 v125, 31, v124
	v_lshl_add_u64 v[86:87], v[124:125], 2, s[14:15]
	global_load_dwordx4 v[94:97], v[86:87], off offset:16
	global_load_dwordx4 v[102:105], v[86:87], off
	global_load_dwordx4 v[78:81], v[86:87], off offset:528
	s_nop 0
	global_load_dwordx4 v[86:89], v[86:87], off offset:512
	v_lshl_add_u32 v130, s10, 8, v229
	v_or_b32_e32 v128, 16, v130
	v_or_b32_e32 v126, 32, v130
	v_or_b32_e32 v122, 48, v130
	s_cmp_eq_u32 s11, 0
	v_ashrrev_i32_e32 v131, 31, v130
	v_ashrrev_i32_e32 v129, 31, v128
	v_ashrrev_i32_e32 v127, 31, v126
	v_ashrrev_i32_e32 v123, 31, v122
	s_cbranch_scc1 .LBB0_1120
	s_add_i32 s96, s11, -1
	s_lshl_b64 s[10:11], s[96:97], 20
	v_readlane_b32 s14, v252, 11
	v_readlane_b32 s15, v252, 12
	s_add_u32 s10, s14, s10
	s_addc_u32 s11, s15, s11
	v_lshlrev_b64 v[132:133], 2, v[124:125]
	v_lshrrev_b32_e32 v134, 5, v220
	v_mul_u32_u24_e32 v134, 48, v134
	s_nop 0
	v_sub_co_u32_e32 v132, vcc, v132, v134
	s_nop 1
	v_subbrev_co_u32_e32 v133, vcc, 0, v133, vcc
	v_lshl_add_u64 v[132:133], s[10:11], 0, v[132:133]
	s_mov_b64 s[10:11], 0x80000
	v_lshlrev_b64 v[204:205], 12, v[130:131]
	v_lshl_add_u64 v[204:205], v[204:205], 0, v[132:133]
	v_lshl_add_u64 v[212:213], v[204:205], 0, s[10:11]
	v_lshlrev_b64 v[206:207], 12, v[128:129]
	v_lshl_add_u64 v[206:207], v[206:207], 0, v[132:133]
	v_lshl_add_u64 v[214:215], v[206:207], 0, s[10:11]
	v_lshlrev_b64 v[208:209], 12, v[126:127]
	v_lshl_add_u64 v[208:209], v[208:209], 0, v[132:133]
	v_lshl_add_u64 v[216:217], v[208:209], 0, s[10:11]
	v_lshlrev_b64 v[210:211], 12, v[122:123]
	v_lshl_add_u64 v[210:211], v[210:211], 0, v[132:133]
	v_lshl_add_u64 v[218:219], v[210:211], 0, s[10:11]
	s_waitcnt vmcnt(0)
	v_pk_mul_f32 v[172:173], v[166:167], v[102:103]
	v_pk_mul_f32 v[174:175], v[168:169], v[104:105]
	v_pk_mul_f32 v[176:177], v[162:163], v[94:95]
	v_pk_mul_f32 v[178:179], v[164:165], v[96:97]
	s_nop 1
	v_permlane32_swap_b32_e32 v172, v176
	v_permlane32_swap_b32_e32 v173, v177
	v_permlane32_swap_b32_e32 v174, v178
	v_permlane32_swap_b32_e32 v175, v179
	s_nop 0
	global_store_dwordx4 v[204:205], v[172:175], off
	global_store_dwordx4 v[204:205], v[176:179], off offset:64
	v_pk_mul_f32 v[180:181], v[146:147], v[86:87]
	v_pk_mul_f32 v[182:183], v[148:149], v[88:89]
	v_pk_mul_f32 v[184:185], v[138:139], v[78:79]
	v_pk_mul_f32 v[186:187], v[140:141], v[80:81]
	s_nop 1
	v_permlane32_swap_b32_e32 v180, v184
	v_permlane32_swap_b32_e32 v181, v185
	v_permlane32_swap_b32_e32 v182, v186
	v_permlane32_swap_b32_e32 v183, v187
	s_nop 0
	global_store_dwordx4 v[204:205], v[180:183], off offset:512
	global_store_dwordx4 v[204:205], v[184:187], off offset:576
	v_pk_mul_f32 v[188:189], v[150:151], v[102:103]
	v_pk_mul_f32 v[190:191], v[152:153], v[104:105]
	v_pk_mul_f32 v[192:193], v[142:143], v[94:95]
	v_pk_mul_f32 v[194:195], v[144:145], v[96:97]
	s_nop 1
	v_permlane32_swap_b32_e32 v188, v192
	v_permlane32_swap_b32_e32 v189, v193
	v_permlane32_swap_b32_e32 v190, v194
	v_permlane32_swap_b32_e32 v191, v195
	s_nop 0
	global_store_dwordx4 v[206:207], v[188:191], off
	global_store_dwordx4 v[206:207], v[192:195], off offset:64
	v_pk_mul_f32 v[154:155], v[118:119], v[86:87]
	v_pk_mul_f32 v[156:157], v[120:121], v[88:89]
	v_pk_mul_f32 v[158:159], v[114:115], v[78:79]
	v_pk_mul_f32 v[160:161], v[116:117], v[80:81]
	s_nop 1
	v_permlane32_swap_b32_e32 v154, v158
	v_permlane32_swap_b32_e32 v155, v159
	v_permlane32_swap_b32_e32 v156, v160
	v_permlane32_swap_b32_e32 v157, v161
	s_nop 0
	global_store_dwordx4 v[206:207], v[154:157], off offset:512
	global_store_dwordx4 v[206:207], v[158:161], off offset:576
	v_pk_mul_f32 v[172:173], v[110:111], v[102:103]
	v_pk_mul_f32 v[174:175], v[112:113], v[104:105]
	v_pk_mul_f32 v[176:177], v[106:107], v[94:95]
	v_pk_mul_f32 v[178:179], v[108:109], v[96:97]
	s_nop 1
	v_permlane32_swap_b32_e32 v172, v176
	v_permlane32_swap_b32_e32 v173, v177
	v_permlane32_swap_b32_e32 v174, v178
	v_permlane32_swap_b32_e32 v175, v179
	s_nop 0
	global_store_dwordx4 v[208:209], v[172:175], off
	global_store_dwordx4 v[208:209], v[176:179], off offset:64
	v_pk_mul_f32 v[180:181], v[98:99], v[86:87]
	v_pk_mul_f32 v[182:183], v[100:101], v[88:89]
	v_pk_mul_f32 v[184:185], v[90:91], v[78:79]
	v_pk_mul_f32 v[186:187], v[92:93], v[80:81]
	s_nop 1
	v_permlane32_swap_b32_e32 v180, v184
	v_permlane32_swap_b32_e32 v181, v185
	v_permlane32_swap_b32_e32 v182, v186
	v_permlane32_swap_b32_e32 v183, v187
	s_nop 0
	global_store_dwordx4 v[208:209], v[180:183], off offset:512
	global_store_dwordx4 v[208:209], v[184:187], off offset:576
	v_pk_mul_f32 v[188:189], v[82:83], v[102:103]
	v_pk_mul_f32 v[190:191], v[84:85], v[104:105]
	v_pk_mul_f32 v[192:193], v[74:75], v[94:95]
	v_pk_mul_f32 v[194:195], v[76:77], v[96:97]
	s_nop 1
	v_permlane32_swap_b32_e32 v188, v192
	v_permlane32_swap_b32_e32 v189, v193
	v_permlane32_swap_b32_e32 v190, v194
	v_permlane32_swap_b32_e32 v191, v195
	s_nop 0
	global_store_dwordx4 v[210:211], v[188:191], off
	global_store_dwordx4 v[210:211], v[192:195], off offset:64
	v_pk_mul_f32 v[154:155], v[70:71], v[86:87]
	v_pk_mul_f32 v[156:157], v[72:73], v[88:89]
	v_pk_mul_f32 v[158:159], v[66:67], v[78:79]
	v_pk_mul_f32 v[160:161], v[68:69], v[80:81]
	s_nop 1
	v_permlane32_swap_b32_e32 v154, v158
	v_permlane32_swap_b32_e32 v155, v159
	v_permlane32_swap_b32_e32 v156, v160
	v_permlane32_swap_b32_e32 v157, v161
	s_nop 0
	global_store_dwordx4 v[210:211], v[154:157], off offset:512
	global_store_dwordx4 v[210:211], v[158:161], off offset:576
	v_pk_mul_f32 v[172:173], v[62:63], v[102:103]
	v_pk_mul_f32 v[174:175], v[64:65], v[104:105]
	v_pk_mul_f32 v[176:177], v[58:59], v[94:95]
	v_pk_mul_f32 v[178:179], v[60:61], v[96:97]
	s_nop 1
	v_permlane32_swap_b32_e32 v172, v176
	v_permlane32_swap_b32_e32 v173, v177
	v_permlane32_swap_b32_e32 v174, v178
	v_permlane32_swap_b32_e32 v175, v179
	s_nop 0
	global_store_dwordx4 v[212:213], v[172:175], off
	global_store_dwordx4 v[212:213], v[176:179], off offset:64
	v_pk_mul_f32 v[180:181], v[54:55], v[86:87]
	v_pk_mul_f32 v[182:183], v[56:57], v[88:89]
	v_pk_mul_f32 v[184:185], v[50:51], v[78:79]
	v_pk_mul_f32 v[186:187], v[52:53], v[80:81]
	s_nop 1
	v_permlane32_swap_b32_e32 v180, v184
	v_permlane32_swap_b32_e32 v181, v185
	v_permlane32_swap_b32_e32 v182, v186
	v_permlane32_swap_b32_e32 v183, v187
	s_nop 0
	global_store_dwordx4 v[212:213], v[180:183], off offset:512
	global_store_dwordx4 v[212:213], v[184:187], off offset:576
	v_pk_mul_f32 v[188:189], v[46:47], v[102:103]
	v_pk_mul_f32 v[190:191], v[48:49], v[104:105]
	v_pk_mul_f32 v[192:193], v[42:43], v[94:95]
	v_pk_mul_f32 v[194:195], v[44:45], v[96:97]
	s_nop 1
	v_permlane32_swap_b32_e32 v188, v192
	v_permlane32_swap_b32_e32 v189, v193
	v_permlane32_swap_b32_e32 v190, v194
	v_permlane32_swap_b32_e32 v191, v195
	s_nop 0
	global_store_dwordx4 v[214:215], v[188:191], off
	global_store_dwordx4 v[214:215], v[192:195], off offset:64
	v_pk_mul_f32 v[154:155], v[38:39], v[86:87]
	v_pk_mul_f32 v[156:157], v[40:41], v[88:89]
	v_pk_mul_f32 v[158:159], v[34:35], v[78:79]
	v_pk_mul_f32 v[160:161], v[36:37], v[80:81]
	s_nop 1
	v_permlane32_swap_b32_e32 v154, v158
	v_permlane32_swap_b32_e32 v155, v159
	v_permlane32_swap_b32_e32 v156, v160
	v_permlane32_swap_b32_e32 v157, v161
	s_nop 0
	global_store_dwordx4 v[214:215], v[154:157], off offset:512
	global_store_dwordx4 v[214:215], v[158:161], off offset:576
	v_pk_mul_f32 v[172:173], v[28:29], v[102:103]
	v_pk_mul_f32 v[174:175], v[30:31], v[104:105]
	v_pk_mul_f32 v[176:177], v[24:25], v[94:95]
	v_pk_mul_f32 v[178:179], v[26:27], v[96:97]
	s_nop 1
	v_permlane32_swap_b32_e32 v172, v176
	v_permlane32_swap_b32_e32 v173, v177
	v_permlane32_swap_b32_e32 v174, v178
	v_permlane32_swap_b32_e32 v175, v179
	s_nop 0
	global_store_dwordx4 v[216:217], v[172:175], off
	global_store_dwordx4 v[216:217], v[176:179], off offset:64
	v_pk_mul_f32 v[180:181], v[20:21], v[86:87]
	v_pk_mul_f32 v[182:183], v[22:23], v[88:89]
	v_pk_mul_f32 v[184:185], v[16:17], v[78:79]
	v_pk_mul_f32 v[186:187], v[18:19], v[80:81]
	s_nop 1
	v_permlane32_swap_b32_e32 v180, v184
	v_permlane32_swap_b32_e32 v181, v185
	v_permlane32_swap_b32_e32 v182, v186
	v_permlane32_swap_b32_e32 v183, v187
	s_nop 0
	global_store_dwordx4 v[216:217], v[180:183], off offset:512
	global_store_dwordx4 v[216:217], v[184:187], off offset:576
	v_pk_mul_f32 v[188:189], v[12:13], v[102:103]
	v_pk_mul_f32 v[190:191], v[14:15], v[104:105]
	v_pk_mul_f32 v[192:193], v[8:9], v[94:95]
	v_pk_mul_f32 v[194:195], v[10:11], v[96:97]
	s_nop 1
	v_permlane32_swap_b32_e32 v188, v192
	v_permlane32_swap_b32_e32 v189, v193
	v_permlane32_swap_b32_e32 v190, v194
	v_permlane32_swap_b32_e32 v191, v195
	s_nop 0
	global_store_dwordx4 v[218:219], v[188:191], off
	global_store_dwordx4 v[218:219], v[192:195], off offset:64
	v_pk_mul_f32 v[154:155], v[4:5], v[86:87]
	v_pk_mul_f32 v[156:157], v[6:7], v[88:89]
	v_pk_mul_f32 v[158:159], v[0:1], v[78:79]
	v_pk_mul_f32 v[160:161], v[2:3], v[80:81]
	s_nop 1
	v_permlane32_swap_b32_e32 v154, v158
	v_permlane32_swap_b32_e32 v155, v159
	v_permlane32_swap_b32_e32 v156, v160
	v_permlane32_swap_b32_e32 v157, v161
	s_nop 0
	global_store_dwordx4 v[218:219], v[154:157], off offset:512
	global_store_dwordx4 v[218:219], v[158:161], off offset:576
	s_cbranch_execnz .LBB0_1104
	s_branch .LBB0_1103

.LBB0_1276:
	s_add_u32 s16, s14, 0x100
	s_addc_u32 s17, s15, 0
	s_add_i32 s39, 0, 0x10000
	v_add_u32_e32 v152, s39, v137
	ds_read_b128 v[140:143], v152
	ds_read_b128 v[148:151], v152 offset:2048
	ds_read_b128 v[144:147], v152 offset:1024
	ds_read_b128 v[152:155], v152 offset:3072
	s_cmp_eq_u32 s38, 12
	s_cselect_b32 s21, s11, s17
	s_cselect_b32 s20, s10, s16
	s_cselect_b32 s19, s13, s37
	s_cselect_b32 s18, s12, s3
	v_lshl_add_u64 v[188:189], s[14:15], 0, v[132:133]
	s_add_i32 m0, s9, 0xc000
	ds_read_b128 v[156:159], v139
	ds_read_b128 v[164:167], v139 offset:2048
	ds_read_b128 v[172:175], v139 offset:4096
	ds_read_b128 v[180:183], v139 offset:6144
	ds_read_b128 v[160:163], v139 offset:1024
	ds_read_b128 v[168:171], v139 offset:3072
	ds_read_b128 v[176:179], v139 offset:5120
	ds_read_b128 v[184:187], v139 offset:7168
	global_load_lds_dwordx4 v[188:189], off
	v_lshl_add_u64 v[188:189], s[14:15], 0, v[134:135]
	s_add_i32 m0, s9, 0xe000
	s_nop 0
	global_load_lds_dwordx4 v[188:189], off
	s_waitcnt lgkmcnt(8)
	s_barrier
	s_waitcnt lgkmcnt(7)
	v_mfma_f32_16x16x32_f16 v[126:129], v[140:143], v[156:159], v[126:129]
	v_mfma_f32_16x16x32_f16 v[122:125], v[148:151], v[156:159], v[122:125]
	s_waitcnt lgkmcnt(6)
	v_mfma_f32_16x16x32_f16 v[110:113], v[140:143], v[164:167], v[110:113]
	v_mfma_f32_16x16x32_f16 v[106:109], v[148:151], v[164:167], v[106:109]
	s_waitcnt lgkmcnt(5)
	v_mfma_f32_16x16x32_f16 v[94:97], v[140:143], v[172:175], v[94:97]
	v_mfma_f32_16x16x32_f16 v[90:93], v[148:151], v[172:175], v[90:93]
	s_waitcnt lgkmcnt(4)
	v_mfma_f32_16x16x32_f16 v[78:81], v[140:143], v[180:183], v[78:81]
	v_mfma_f32_16x16x32_f16 v[74:77], v[148:151], v[180:183], v[74:77]
	s_waitcnt lgkmcnt(3)
	v_mfma_f32_16x16x32_f16 v[126:129], v[144:147], v[160:163], v[126:129]
	v_mfma_f32_16x16x32_f16 v[122:125], v[152:155], v[160:163], v[122:125]
	s_waitcnt lgkmcnt(2)
	v_mfma_f32_16x16x32_f16 v[110:113], v[144:147], v[168:171], v[110:113]
	v_mfma_f32_16x16x32_f16 v[106:109], v[152:155], v[168:171], v[106:109]
	s_waitcnt lgkmcnt(1)
	v_mfma_f32_16x16x32_f16 v[94:97], v[144:147], v[176:179], v[94:97]
	v_mfma_f32_16x16x32_f16 v[90:93], v[152:155], v[176:179], v[90:93]
	s_waitcnt lgkmcnt(0)
	v_mfma_f32_16x16x32_f16 v[78:81], v[144:147], v[184:187], v[78:81]
	v_mfma_f32_16x16x32_f16 v[74:77], v[152:155], v[184:187], v[74:77]
	s_barrier
	s_add_i32 s40, 0, 0x14000
	s_add_i32 s14, s39, s26
	v_add_u32_e32 v200, s40, v137
	v_lshl_add_u64 v[204:205], s[18:19], 0, v[32:33]
	s_mov_b32 m0, s14
	ds_read_b128 v[188:191], v200
	ds_read_b128 v[196:199], v200 offset:2048
	ds_read_b128 v[192:195], v200 offset:1024
	ds_read_b128 v[200:203], v200 offset:3072
	global_load_lds_dwordx4 v[204:205], off
	v_lshl_add_u64 v[206:207], s[18:19], 0, v[130:131]
	s_add_i32 m0, s14, 0x2000
	s_nop 0
	global_load_lds_dwordx4 v[206:207], off
	s_barrier
	s_waitcnt lgkmcnt(2)
	v_mfma_f32_16x16x32_f16 v[118:121], v[188:191], v[156:159], v[118:121]
	v_mfma_f32_16x16x32_f16 v[114:117], v[196:199], v[156:159], v[114:117]
	v_mfma_f32_16x16x32_f16 v[102:105], v[188:191], v[164:167], v[102:105]
	v_mfma_f32_16x16x32_f16 v[98:101], v[196:199], v[164:167], v[98:101]
	v_mfma_f32_16x16x32_f16 v[86:89], v[188:191], v[172:175], v[86:89]
	v_mfma_f32_16x16x32_f16 v[82:85], v[196:199], v[172:175], v[82:85]
	v_mfma_f32_16x16x32_f16 v[70:73], v[188:191], v[180:183], v[70:73]
	v_mfma_f32_16x16x32_f16 v[66:69], v[196:199], v[180:183], v[66:69]
	s_waitcnt lgkmcnt(0)
	v_mfma_f32_16x16x32_f16 v[118:121], v[192:195], v[160:163], v[118:121]
	v_mfma_f32_16x16x32_f16 v[114:117], v[200:203], v[160:163], v[114:117]
	v_mfma_f32_16x16x32_f16 v[102:105], v[192:195], v[168:171], v[102:105]
	v_mfma_f32_16x16x32_f16 v[98:101], v[200:203], v[168:171], v[98:101]
	v_mfma_f32_16x16x32_f16 v[86:89], v[192:195], v[176:179], v[86:89]
	v_mfma_f32_16x16x32_f16 v[82:85], v[200:203], v[176:179], v[82:85]
	v_mfma_f32_16x16x32_f16 v[70:73], v[192:195], v[184:187], v[70:73]
	v_mfma_f32_16x16x32_f16 v[66:69], v[200:203], v[184:187], v[66:69]
	s_mov_b32 m0, s9
	v_lshl_add_u64 v[208:209], s[20:21], 0, v[32:33]
	s_barrier
	ds_read_b128 v[156:159], v139 offset:16384
	ds_read_b128 v[164:167], v139 offset:18432
	ds_read_b128 v[172:175], v139 offset:20480
	ds_read_b128 v[180:183], v139 offset:22528
	ds_read_b128 v[160:163], v139 offset:17408
	ds_read_b128 v[168:171], v139 offset:19456
	ds_read_b128 v[176:179], v139 offset:21504
	ds_read_b128 v[184:187], v139 offset:23552
	global_load_lds_dwordx4 v[208:209], off
	v_lshl_add_u64 v[210:211], s[20:21], 0, v[130:131]
	s_mov_b32 m0, s27
	s_nop 0
	global_load_lds_dwordx4 v[210:211], off
	s_barrier
	s_waitcnt lgkmcnt(7)
	v_mfma_f32_16x16x32_f16 v[62:65], v[140:143], v[156:159], v[62:65]
	v_mfma_f32_16x16x32_f16 v[58:61], v[148:151], v[156:159], v[58:61]
	s_waitcnt lgkmcnt(6)
	v_mfma_f32_16x16x32_f16 v[46:49], v[140:143], v[164:167], v[46:49]
	v_mfma_f32_16x16x32_f16 v[42:45], v[148:151], v[164:167], v[42:45]
	s_waitcnt lgkmcnt(5)
	v_mfma_f32_16x16x32_f16 v[28:31], v[140:143], v[172:175], v[28:31]
	v_mfma_f32_16x16x32_f16 v[24:27], v[148:151], v[172:175], v[24:27]
	s_waitcnt lgkmcnt(4)
	v_mfma_f32_16x16x32_f16 v[12:15], v[140:143], v[180:183], v[12:15]
	v_mfma_f32_16x16x32_f16 v[8:11], v[148:151], v[180:183], v[8:11]
	s_waitcnt lgkmcnt(3)
	v_mfma_f32_16x16x32_f16 v[62:65], v[144:147], v[160:163], v[62:65]
	v_mfma_f32_16x16x32_f16 v[58:61], v[152:155], v[160:163], v[58:61]
	s_waitcnt lgkmcnt(2)
	v_mfma_f32_16x16x32_f16 v[46:49], v[144:147], v[168:171], v[46:49]
	v_mfma_f32_16x16x32_f16 v[42:45], v[152:155], v[168:171], v[42:45]
	s_waitcnt lgkmcnt(1)
	v_mfma_f32_16x16x32_f16 v[28:31], v[144:147], v[176:179], v[28:31]
	v_mfma_f32_16x16x32_f16 v[24:27], v[152:155], v[176:179], v[24:27]
	s_waitcnt lgkmcnt(0)
	v_mfma_f32_16x16x32_f16 v[12:15], v[144:147], v[184:187], v[12:15]
	v_mfma_f32_16x16x32_f16 v[8:11], v[152:155], v[184:187], v[8:11]
	s_barrier
	s_add_u32 s14, s18, 0x40000
	s_addc_u32 s15, s19, 0
	s_add_i32 s39, s40, s26
	v_lshl_add_u64 v[140:141], s[14:15], 0, v[32:33]
	s_mov_b32 m0, s39
	s_nop 0
	global_load_lds_dwordx4 v[140:141], off
	v_lshl_add_u64 v[140:141], s[14:15], 0, v[130:131]
	s_add_i32 m0, s39, 0x2000
	s_nop 0
	global_load_lds_dwordx4 v[140:141], off
	s_waitcnt vmcnt(6)
	s_barrier
	v_mfma_f32_16x16x32_f16 v[54:57], v[188:191], v[156:159], v[54:57]
	v_mfma_f32_16x16x32_f16 v[50:53], v[196:199], v[156:159], v[50:53]
	v_mfma_f32_16x16x32_f16 v[38:41], v[188:191], v[164:167], v[38:41]
	v_mfma_f32_16x16x32_f16 v[34:37], v[196:199], v[164:167], v[34:37]
	v_mfma_f32_16x16x32_f16 v[20:23], v[188:191], v[172:175], v[20:23]
	v_mfma_f32_16x16x32_f16 v[16:19], v[196:199], v[172:175], v[16:19]
	v_mfma_f32_16x16x32_f16 v[4:7], v[188:191], v[180:183], v[4:7]
	v_mfma_f32_16x16x32_f16 v[0:3], v[196:199], v[180:183], v[0:3]
	v_mfma_f32_16x16x32_f16 v[54:57], v[192:195], v[160:163], v[54:57]
	v_mfma_f32_16x16x32_f16 v[50:53], v[200:203], v[160:163], v[50:53]
	v_mfma_f32_16x16x32_f16 v[38:41], v[192:195], v[168:171], v[38:41]
	v_mfma_f32_16x16x32_f16 v[34:37], v[200:203], v[168:171], v[34:37]
	v_mfma_f32_16x16x32_f16 v[20:23], v[192:195], v[176:179], v[20:23]
	v_mfma_f32_16x16x32_f16 v[16:19], v[200:203], v[176:179], v[16:19]
	v_mfma_f32_16x16x32_f16 v[4:7], v[192:195], v[184:187], v[4:7]
	v_mfma_f32_16x16x32_f16 v[0:3], v[200:203], v[184:187], v[0:3]
	s_add_i32 s39, 0, 0x18000
	v_add_u32_e32 v152, s39, v137
	s_barrier
	ds_read_b128 v[140:143], v152
	ds_read_b128 v[148:151], v152 offset:2048
	ds_read_b128 v[144:147], v152 offset:1024
	ds_read_b128 v[152:155], v152 offset:3072
	s_add_u32 s14, s20, 0x40000
	s_addc_u32 s15, s21, 0
	s_mov_b32 m0, s28
	v_lshl_add_u64 v[188:189], s[14:15], 0, v[32:33]
	ds_read_b128 v[156:159], v139 offset:32768
	ds_read_b128 v[164:167], v139 offset:34816
	ds_read_b128 v[172:175], v139 offset:36864
	ds_read_b128 v[180:183], v139 offset:38912
	ds_read_b128 v[160:163], v139 offset:33792
	ds_read_b128 v[168:171], v139 offset:35840
	ds_read_b128 v[176:179], v139 offset:37888
	ds_read_b128 v[184:187], v139 offset:39936
	global_load_lds_dwordx4 v[188:189], off
	v_lshl_add_u64 v[188:189], s[14:15], 0, v[130:131]
	s_mov_b32 m0, s29
	s_nop 0
	global_load_lds_dwordx4 v[188:189], off
	s_waitcnt lgkmcnt(8)
	s_barrier
	s_waitcnt lgkmcnt(7)
	v_mfma_f32_16x16x32_f16 v[126:129], v[140:143], v[156:159], v[126:129]
	v_mfma_f32_16x16x32_f16 v[122:125], v[148:151], v[156:159], v[122:125]
	s_waitcnt lgkmcnt(6)
	v_mfma_f32_16x16x32_f16 v[110:113], v[140:143], v[164:167], v[110:113]
	v_mfma_f32_16x16x32_f16 v[106:109], v[148:151], v[164:167], v[106:109]
	s_waitcnt lgkmcnt(5)
	v_mfma_f32_16x16x32_f16 v[94:97], v[140:143], v[172:175], v[94:97]
	v_mfma_f32_16x16x32_f16 v[90:93], v[148:151], v[172:175], v[90:93]
	s_waitcnt lgkmcnt(4)
	v_mfma_f32_16x16x32_f16 v[78:81], v[140:143], v[180:183], v[78:81]
	v_mfma_f32_16x16x32_f16 v[74:77], v[148:151], v[180:183], v[74:77]
	s_waitcnt lgkmcnt(3)
	v_mfma_f32_16x16x32_f16 v[126:129], v[144:147], v[160:163], v[126:129]
	v_mfma_f32_16x16x32_f16 v[122:125], v[152:155], v[160:163], v[122:125]
	s_waitcnt lgkmcnt(2)
	v_mfma_f32_16x16x32_f16 v[110:113], v[144:147], v[168:171], v[110:113]
	v_mfma_f32_16x16x32_f16 v[106:109], v[152:155], v[168:171], v[106:109]
	s_waitcnt lgkmcnt(1)
	v_mfma_f32_16x16x32_f16 v[94:97], v[144:147], v[176:179], v[94:97]
	v_mfma_f32_16x16x32_f16 v[90:93], v[152:155], v[176:179], v[90:93]
	s_waitcnt lgkmcnt(0)
	v_mfma_f32_16x16x32_f16 v[78:81], v[144:147], v[184:187], v[78:81]
	v_mfma_f32_16x16x32_f16 v[74:77], v[152:155], v[184:187], v[74:77]
	s_barrier
	s_add_i32 s20, 0, 0x1c000
	s_add_i32 s14, s39, s26
	v_add_u32_e32 v200, s20, v137
	v_lshl_add_u64 v[204:205], v[204:205], 0, s[84:85]
	s_mov_b32 m0, s14
	ds_read_b128 v[188:191], v200
	ds_read_b128 v[196:199], v200 offset:2048
	ds_read_b128 v[192:195], v200 offset:1024
	ds_read_b128 v[200:203], v200 offset:3072
	global_load_lds_dwordx4 v[204:205], off
	v_lshl_add_u64 v[204:205], v[206:207], 0, s[84:85]
	s_add_i32 m0, s14, 0x2000
	s_nop 0
	global_load_lds_dwordx4 v[204:205], off
	s_barrier
	s_waitcnt lgkmcnt(2)
	v_mfma_f32_16x16x32_f16 v[118:121], v[188:191], v[156:159], v[118:121]
	v_mfma_f32_16x16x32_f16 v[114:117], v[196:199], v[156:159], v[114:117]
	v_mfma_f32_16x16x32_f16 v[102:105], v[188:191], v[164:167], v[102:105]
	v_mfma_f32_16x16x32_f16 v[98:101], v[196:199], v[164:167], v[98:101]
	v_mfma_f32_16x16x32_f16 v[86:89], v[188:191], v[172:175], v[86:89]
	v_mfma_f32_16x16x32_f16 v[82:85], v[196:199], v[172:175], v[82:85]
	v_mfma_f32_16x16x32_f16 v[70:73], v[188:191], v[180:183], v[70:73]
	v_mfma_f32_16x16x32_f16 v[66:69], v[196:199], v[180:183], v[66:69]
	s_waitcnt lgkmcnt(0)
	v_mfma_f32_16x16x32_f16 v[118:121], v[192:195], v[160:163], v[118:121]
	v_mfma_f32_16x16x32_f16 v[114:117], v[200:203], v[160:163], v[114:117]
	v_mfma_f32_16x16x32_f16 v[102:105], v[192:195], v[168:171], v[102:105]
	v_mfma_f32_16x16x32_f16 v[98:101], v[200:203], v[168:171], v[98:101]
	v_mfma_f32_16x16x32_f16 v[86:89], v[192:195], v[176:179], v[86:89]
	v_mfma_f32_16x16x32_f16 v[82:85], v[200:203], v[176:179], v[82:85]
	v_mfma_f32_16x16x32_f16 v[70:73], v[192:195], v[184:187], v[70:73]
	v_mfma_f32_16x16x32_f16 v[66:69], v[200:203], v[184:187], v[66:69]
	s_mov_b32 m0, s30
	v_lshl_add_u64 v[204:205], v[208:209], 0, s[84:85]
	s_barrier
	ds_read_b128 v[156:159], v139 offset:49152
	ds_read_b128 v[164:167], v139 offset:51200
	ds_read_b128 v[172:175], v139 offset:53248
	ds_read_b128 v[180:183], v139 offset:55296
	ds_read_b128 v[160:163], v139 offset:50176
	ds_read_b128 v[168:171], v139 offset:52224
	ds_read_b128 v[176:179], v139 offset:54272
	ds_read_b128 v[184:187], v139 offset:56320
	global_load_lds_dwordx4 v[204:205], off
	v_lshl_add_u64 v[204:205], v[210:211], 0, s[84:85]
	s_mov_b32 m0, s31
	s_nop 0
	global_load_lds_dwordx4 v[204:205], off
	s_barrier
	s_waitcnt lgkmcnt(7)
	v_mfma_f32_16x16x32_f16 v[62:65], v[140:143], v[156:159], v[62:65]
	v_mfma_f32_16x16x32_f16 v[58:61], v[148:151], v[156:159], v[58:61]
	s_waitcnt lgkmcnt(6)
	v_mfma_f32_16x16x32_f16 v[46:49], v[140:143], v[164:167], v[46:49]
	v_mfma_f32_16x16x32_f16 v[42:45], v[148:151], v[164:167], v[42:45]
	s_waitcnt lgkmcnt(5)
	v_mfma_f32_16x16x32_f16 v[28:31], v[140:143], v[172:175], v[28:31]
	v_mfma_f32_16x16x32_f16 v[24:27], v[148:151], v[172:175], v[24:27]
	s_waitcnt lgkmcnt(4)
	v_mfma_f32_16x16x32_f16 v[12:15], v[140:143], v[180:183], v[12:15]
	v_mfma_f32_16x16x32_f16 v[8:11], v[148:151], v[180:183], v[8:11]
	s_waitcnt lgkmcnt(3)
	v_mfma_f32_16x16x32_f16 v[62:65], v[144:147], v[160:163], v[62:65]
	v_mfma_f32_16x16x32_f16 v[58:61], v[152:155], v[160:163], v[58:61]
	s_waitcnt lgkmcnt(2)
	v_mfma_f32_16x16x32_f16 v[46:49], v[144:147], v[168:171], v[46:49]
	v_mfma_f32_16x16x32_f16 v[42:45], v[152:155], v[168:171], v[42:45]
	s_waitcnt lgkmcnt(1)
	v_mfma_f32_16x16x32_f16 v[28:31], v[144:147], v[176:179], v[28:31]
	v_mfma_f32_16x16x32_f16 v[24:27], v[152:155], v[176:179], v[24:27]
	s_waitcnt lgkmcnt(0)
	v_mfma_f32_16x16x32_f16 v[12:15], v[144:147], v[184:187], v[12:15]
	v_mfma_f32_16x16x32_f16 v[8:11], v[152:155], v[184:187], v[8:11]
	s_barrier
	s_add_u32 s14, s18, 0x40080
	s_addc_u32 s15, s19, 0
	s_add_i32 s18, s20, s26
	v_lshl_add_u64 v[140:141], s[14:15], 0, v[32:33]
	s_mov_b32 m0, s18
	s_nop 0
	global_load_lds_dwordx4 v[140:141], off
	v_lshl_add_u64 v[140:141], s[14:15], 0, v[130:131]
	s_add_i32 m0, s18, 0x2000
	s_nop 0
	global_load_lds_dwordx4 v[140:141], off
	s_waitcnt vmcnt(6)
	s_barrier
	v_mfma_f32_16x16x32_f16 v[54:57], v[188:191], v[156:159], v[54:57]
	v_mfma_f32_16x16x32_f16 v[50:53], v[196:199], v[156:159], v[50:53]
	v_mfma_f32_16x16x32_f16 v[38:41], v[188:191], v[164:167], v[38:41]
	v_mfma_f32_16x16x32_f16 v[34:37], v[196:199], v[164:167], v[34:37]
	v_mfma_f32_16x16x32_f16 v[20:23], v[188:191], v[172:175], v[20:23]
	v_mfma_f32_16x16x32_f16 v[16:19], v[196:199], v[172:175], v[16:19]
	v_mfma_f32_16x16x32_f16 v[4:7], v[188:191], v[180:183], v[4:7]
	v_mfma_f32_16x16x32_f16 v[0:3], v[196:199], v[180:183], v[0:3]
	v_mfma_f32_16x16x32_f16 v[54:57], v[192:195], v[160:163], v[54:57]
	v_mfma_f32_16x16x32_f16 v[50:53], v[200:203], v[160:163], v[50:53]
	v_mfma_f32_16x16x32_f16 v[38:41], v[192:195], v[168:171], v[38:41]
	v_mfma_f32_16x16x32_f16 v[34:37], v[200:203], v[168:171], v[34:37]
	v_mfma_f32_16x16x32_f16 v[20:23], v[192:195], v[176:179], v[20:23]
	v_mfma_f32_16x16x32_f16 v[16:19], v[200:203], v[176:179], v[16:19]
	v_mfma_f32_16x16x32_f16 v[4:7], v[192:195], v[184:187], v[4:7]
	v_mfma_f32_16x16x32_f16 v[0:3], v[200:203], v[184:187], v[0:3]
	s_add_i32 s38, s38, 2
	s_add_u32 s3, s3, 0x100
	s_addc_u32 s37, s37, 0
	s_cmp_gt_u32 s38, 13
	s_mov_b64 s[14:15], s[16:17]
	s_barrier
	s_cbranch_scc0 .LBB0_1276
	v_mul_f32_e32 v144, 0xbfb8aa3b, v127
	v_mul_f32_e32 v141, 0xbfb8aa3b, v126
	v_exp_f32_e32 v145, v144
	v_mul_f32_e32 v144, 0xbfb8aa3b, v128
	v_exp_f32_e32 v141, v141
	v_exp_f32_e32 v146, v144
	v_mul_f32_e32 v144, 0xbfb8aa3b, v129
	v_exp_f32_e32 v147, v144
	v_mul_f32_e32 v144, 0xbfb8aa3b, v122
	v_exp_f32_e32 v148, v144
	v_mul_f32_e32 v144, 0xbfb8aa3b, v123
	v_exp_f32_e32 v149, v144
	v_mul_f32_e32 v144, 0xbfb8aa3b, v124
	v_exp_f32_e32 v150, v144
	v_mul_f32_e32 v144, 0xbfb8aa3b, v125
	v_add_f32_e32 v141, 1.0, v141
	v_exp_f32_e32 v151, v144
	v_rcp_f32_e32 v144, v141
	v_add_f32_e32 v141, 1.0, v145
	v_rcp_f32_e32 v145, v141
	v_add_f32_e32 v141, 1.0, v146
	v_rcp_f32_e32 v146, v141
	v_add_f32_e32 v141, 1.0, v147
	v_rcp_f32_e32 v147, v141
	v_add_f32_e32 v141, 1.0, v148
	v_rcp_f32_e32 v148, v141
	v_add_f32_e32 v141, 1.0, v149
	v_rcp_f32_e32 v149, v141
	v_add_f32_e32 v141, 1.0, v150
	v_rcp_f32_e32 v150, v141
	v_add_f32_e32 v141, 1.0, v151
	v_pk_mul_f32 v[126:127], v[126:127], v[144:145]
	v_rcp_f32_e32 v151, v141
	v_pk_mul_f32 v[118:119], v[126:127], v[118:119]
	v_pk_mul_f32 v[126:127], v[128:129], v[146:147]
	v_cvt_pk_f16_f32 v118, v118, v119
	v_pk_mul_f32 v[120:121], v[126:127], v[120:121]
	v_lshl_or_b32 v142, s36, 7, v138
	v_cvt_pk_f16_f32 v119, v120, v121
	v_pk_mul_f32 v[120:121], v[122:123], v[148:149]
	v_lshl_add_u32 v140, s8, 8, v136
	v_pk_mul_f32 v[114:115], v[120:121], v[114:115]
	v_ashrrev_i32_e32 v143, 31, v142
	v_cvt_pk_f16_f32 v120, v114, v115
	v_pk_mul_f32 v[114:115], v[124:125], v[150:151]
	s_movk_i32 s3, 0x1600
	v_pk_mul_f32 v[114:115], v[114:115], v[116:117]
	v_lshlrev_b64 v[116:117], 1, v[142:143]
	v_cvt_pk_f16_f32 v121, v114, v115
	v_mov_b64_e32 v[114:115], s[92:93]
	v_mad_i64_i32 v[122:123], s[10:11], v140, s3, v[114:115]
	v_lshl_add_u64 v[122:123], v[122:123], 0, v[116:117]
	global_store_dwordx4 v[122:123], v[118:121], off
	v_mul_f32_e32 v122, 0xbfb8aa3b, v106
	v_mul_f32_e32 v123, 0xbfb8aa3b, v107
	v_mul_f32_e32 v118, 0xbfb8aa3b, v110
	v_mul_f32_e32 v119, 0xbfb8aa3b, v111
	v_exp_f32_e32 v118, v118
	v_exp_f32_e32 v119, v119
	v_mul_f32_e32 v120, 0xbfb8aa3b, v112
	v_mul_f32_e32 v121, 0xbfb8aa3b, v113
	v_exp_f32_e32 v120, v120
	v_exp_f32_e32 v121, v121
	v_exp_f32_e32 v122, v122
	v_exp_f32_e32 v123, v123
	v_mul_f32_e32 v124, 0xbfb8aa3b, v108
	v_mul_f32_e32 v125, 0xbfb8aa3b, v109
	v_add_f32_e32 v118, 1.0, v118
	v_add_f32_e32 v119, 1.0, v119
	v_exp_f32_e32 v124, v124
	v_exp_f32_e32 v125, v125
	v_rcp_f32_e32 v118, v118
	v_rcp_f32_e32 v119, v119
	v_add_f32_e32 v120, 1.0, v120
	v_add_f32_e32 v121, 1.0, v121
	v_rcp_f32_e32 v120, v120
	v_rcp_f32_e32 v121, v121
	v_add_f32_e32 v122, 1.0, v122
	v_add_f32_e32 v123, 1.0, v123
	v_rcp_f32_e32 v122, v122
	v_rcp_f32_e32 v123, v123
	v_add_f32_e32 v124, 1.0, v124
	v_add_f32_e32 v125, 1.0, v125
	v_pk_mul_f32 v[110:111], v[110:111], v[118:119]
	v_rcp_f32_e32 v124, v124
	v_rcp_f32_e32 v125, v125
	v_pk_mul_f32 v[102:103], v[110:111], v[102:103]
	v_pk_mul_f32 v[110:111], v[112:113], v[120:121]
	v_cvt_pk_f16_f32 v102, v102, v103
	v_pk_mul_f32 v[104:105], v[110:111], v[104:105]
	s_and_b64 vcc, exec, s[0:1]
	v_cvt_pk_f16_f32 v103, v104, v105
	v_pk_mul_f32 v[104:105], v[106:107], v[122:123]
	s_mov_b32 s36, s35
	v_pk_mul_f32 v[98:99], v[104:105], v[98:99]
	s_mov_b32 s8, s2
	v_cvt_pk_f16_f32 v104, v98, v99
	v_pk_mul_f32 v[98:99], v[108:109], v[124:125]
	s_mov_b64 s[16:17], s[6:7]
	v_pk_mul_f32 v[98:99], v[98:99], v[100:101]
	v_mul_f32_e32 v100, 0xbfb8aa3b, v96
	v_cvt_pk_f16_f32 v105, v98, v99
	v_or_b32_e32 v98, 16, v140
	v_mad_i64_i32 v[98:99], s[10:11], v98, s3, v[114:115]
	v_lshl_add_u64 v[98:99], v[98:99], 0, v[116:117]
	global_store_dwordx4 v[98:99], v[102:105], off
	v_mul_f32_e32 v98, 0xbfb8aa3b, v94
	v_mul_f32_e32 v99, 0xbfb8aa3b, v95
	v_exp_f32_e32 v98, v98
	v_exp_f32_e32 v99, v99
	v_mul_f32_e32 v101, 0xbfb8aa3b, v97
	v_exp_f32_e32 v100, v100
	v_exp_f32_e32 v101, v101
	v_mul_f32_e32 v102, 0xbfb8aa3b, v90
	v_mul_f32_e32 v103, 0xbfb8aa3b, v91
	v_exp_f32_e32 v102, v102
	v_exp_f32_e32 v103, v103
	v_mul_f32_e32 v104, 0xbfb8aa3b, v92
	v_mul_f32_e32 v105, 0xbfb8aa3b, v93
	v_add_f32_e32 v98, 1.0, v98
	v_add_f32_e32 v99, 1.0, v99
	v_exp_f32_e32 v104, v104
	v_exp_f32_e32 v105, v105
	v_rcp_f32_e32 v98, v98
	v_rcp_f32_e32 v99, v99
	v_add_f32_e32 v100, 1.0, v100
	v_add_f32_e32 v101, 1.0, v101
	v_rcp_f32_e32 v100, v100
	v_rcp_f32_e32 v101, v101
	v_add_f32_e32 v102, 1.0, v102
	v_add_f32_e32 v103, 1.0, v103
	v_rcp_f32_e32 v102, v102
	v_rcp_f32_e32 v103, v103
	v_add_f32_e32 v104, 1.0, v104
	v_add_f32_e32 v105, 1.0, v105
	v_pk_mul_f32 v[94:95], v[94:95], v[98:99]
	v_rcp_f32_e32 v104, v104
	v_rcp_f32_e32 v105, v105
	v_pk_mul_f32 v[86:87], v[94:95], v[86:87]
	v_pk_mul_f32 v[94:95], v[96:97], v[100:101]
	v_cvt_pk_f16_f32 v86, v86, v87
	v_pk_mul_f32 v[88:89], v[94:95], v[88:89]
	s_mov_b64 s[14:15], s[4:5]
	v_cvt_pk_f16_f32 v87, v88, v89
	v_pk_mul_f32 v[88:89], v[90:91], v[102:103]
	s_nop 0
	v_pk_mul_f32 v[82:83], v[88:89], v[82:83]
	s_nop 0
	v_cvt_pk_f16_f32 v88, v82, v83
	v_pk_mul_f32 v[82:83], v[92:93], v[104:105]
	s_nop 0
	v_pk_mul_f32 v[82:83], v[82:83], v[84:85]
	v_mul_f32_e32 v84, 0xbfb8aa3b, v80
	v_cvt_pk_f16_f32 v89, v82, v83
	v_or_b32_e32 v82, 32, v140
	v_mad_i64_i32 v[82:83], s[10:11], v82, s3, v[114:115]
	v_lshl_add_u64 v[82:83], v[82:83], 0, v[116:117]
	global_store_dwordx4 v[82:83], v[86:89], off
	v_mul_f32_e32 v82, 0xbfb8aa3b, v78
	v_mul_f32_e32 v83, 0xbfb8aa3b, v79
	v_exp_f32_e32 v82, v82
	v_exp_f32_e32 v83, v83
	v_mul_f32_e32 v85, 0xbfb8aa3b, v81
	v_exp_f32_e32 v84, v84
	v_exp_f32_e32 v85, v85
	v_mul_f32_e32 v86, 0xbfb8aa3b, v74
	v_mul_f32_e32 v87, 0xbfb8aa3b, v75
	v_exp_f32_e32 v86, v86
	v_exp_f32_e32 v87, v87
	v_mul_f32_e32 v88, 0xbfb8aa3b, v76
	v_mul_f32_e32 v89, 0xbfb8aa3b, v77
	v_add_f32_e32 v82, 1.0, v82
	v_add_f32_e32 v83, 1.0, v83
	v_exp_f32_e32 v88, v88
	v_exp_f32_e32 v89, v89
	v_rcp_f32_e32 v82, v82
	v_rcp_f32_e32 v83, v83
	v_add_f32_e32 v84, 1.0, v84
	v_add_f32_e32 v85, 1.0, v85
	v_rcp_f32_e32 v84, v84
	v_rcp_f32_e32 v85, v85
	v_add_f32_e32 v86, 1.0, v86
	v_add_f32_e32 v87, 1.0, v87
	v_rcp_f32_e32 v86, v86
	v_rcp_f32_e32 v87, v87
	v_add_f32_e32 v88, 1.0, v88
	v_add_f32_e32 v89, 1.0, v89
	v_pk_mul_f32 v[78:79], v[78:79], v[82:83]
	v_rcp_f32_e32 v88, v88
	v_rcp_f32_e32 v89, v89
	v_pk_mul_f32 v[70:71], v[78:79], v[70:71]
	v_pk_mul_f32 v[78:79], v[80:81], v[84:85]
	v_cvt_pk_f16_f32 v70, v70, v71
	v_pk_mul_f32 v[72:73], v[78:79], v[72:73]
	s_nop 0
	v_cvt_pk_f16_f32 v71, v72, v73
	v_pk_mul_f32 v[72:73], v[74:75], v[86:87]
	v_add_u32_e32 v74, 0x80, v140
	v_pk_mul_f32 v[66:67], v[72:73], v[66:67]
	s_nop 0
	v_cvt_pk_f16_f32 v72, v66, v67
	v_pk_mul_f32 v[66:67], v[76:77], v[88:89]
	s_nop 0
	v_pk_mul_f32 v[66:67], v[66:67], v[68:69]
	v_mul_f32_e32 v68, 0xbfb8aa3b, v64
	v_cvt_pk_f16_f32 v73, v66, v67
	v_or_b32_e32 v66, 48, v140
	v_mad_i64_i32 v[66:67], s[10:11], v66, s3, v[114:115]
	v_lshl_add_u64 v[66:67], v[66:67], 0, v[116:117]
	global_store_dwordx4 v[66:67], v[70:73], off
	v_mul_f32_e32 v66, 0xbfb8aa3b, v62
	v_mul_f32_e32 v67, 0xbfb8aa3b, v63
	v_exp_f32_e32 v66, v66
	v_exp_f32_e32 v67, v67
	v_mul_f32_e32 v69, 0xbfb8aa3b, v65
	v_exp_f32_e32 v68, v68
	v_exp_f32_e32 v69, v69
	v_mul_f32_e32 v70, 0xbfb8aa3b, v58
	v_mul_f32_e32 v71, 0xbfb8aa3b, v59
	v_exp_f32_e32 v70, v70
	v_exp_f32_e32 v71, v71
	v_mul_f32_e32 v72, 0xbfb8aa3b, v60
	v_mul_f32_e32 v73, 0xbfb8aa3b, v61
	v_add_f32_e32 v66, 1.0, v66
	v_add_f32_e32 v67, 1.0, v67
	v_exp_f32_e32 v72, v72
	v_exp_f32_e32 v73, v73
	v_rcp_f32_e32 v66, v66
	v_rcp_f32_e32 v67, v67
	v_add_f32_e32 v68, 1.0, v68
	v_add_f32_e32 v69, 1.0, v69
	v_rcp_f32_e32 v68, v68
	v_rcp_f32_e32 v69, v69
	v_add_f32_e32 v70, 1.0, v70
	v_add_f32_e32 v71, 1.0, v71
	v_rcp_f32_e32 v70, v70
	v_rcp_f32_e32 v71, v71
	v_add_f32_e32 v72, 1.0, v72
	v_add_f32_e32 v73, 1.0, v73
	v_pk_mul_f32 v[62:63], v[62:63], v[66:67]
	v_rcp_f32_e32 v72, v72
	v_rcp_f32_e32 v73, v73
	v_pk_mul_f32 v[54:55], v[62:63], v[54:55]
	v_pk_mul_f32 v[62:63], v[64:65], v[68:69]
	v_cvt_pk_f16_f32 v54, v54, v55
	v_pk_mul_f32 v[56:57], v[62:63], v[56:57]
	s_nop 0
	v_cvt_pk_f16_f32 v55, v56, v57
	v_pk_mul_f32 v[56:57], v[58:59], v[70:71]
	s_nop 0
	v_pk_mul_f32 v[50:51], v[56:57], v[50:51]
	s_nop 0
	v_cvt_pk_f16_f32 v56, v50, v51
	v_pk_mul_f32 v[50:51], v[60:61], v[72:73]
	s_nop 0
	v_pk_mul_f32 v[50:51], v[50:51], v[52:53]
	v_mul_f32_e32 v52, 0xbfb8aa3b, v48
	v_cvt_pk_f16_f32 v57, v50, v51
	v_mad_i64_i32 v[50:51], s[10:11], v74, s3, v[114:115]
	v_lshl_add_u64 v[50:51], v[50:51], 0, v[116:117]
	global_store_dwordx4 v[50:51], v[54:57], off
	v_mul_f32_e32 v50, 0xbfb8aa3b, v46
	v_mul_f32_e32 v51, 0xbfb8aa3b, v47
	v_exp_f32_e32 v50, v50
	v_exp_f32_e32 v51, v51
	v_mul_f32_e32 v53, 0xbfb8aa3b, v49
	v_exp_f32_e32 v52, v52
	v_exp_f32_e32 v53, v53
	v_mul_f32_e32 v54, 0xbfb8aa3b, v42
	v_mul_f32_e32 v55, 0xbfb8aa3b, v43
	v_exp_f32_e32 v54, v54
	v_exp_f32_e32 v55, v55
	v_mul_f32_e32 v56, 0xbfb8aa3b, v44
	v_mul_f32_e32 v57, 0xbfb8aa3b, v45
	v_add_f32_e32 v50, 1.0, v50
	v_add_f32_e32 v51, 1.0, v51
	v_exp_f32_e32 v56, v56
	v_exp_f32_e32 v57, v57
	v_rcp_f32_e32 v50, v50
	v_rcp_f32_e32 v51, v51
	v_add_f32_e32 v52, 1.0, v52
	v_add_f32_e32 v53, 1.0, v53
	v_rcp_f32_e32 v52, v52
	v_rcp_f32_e32 v53, v53
	v_add_f32_e32 v54, 1.0, v54
	v_add_f32_e32 v55, 1.0, v55
	v_rcp_f32_e32 v54, v54
	v_rcp_f32_e32 v55, v55
	v_add_f32_e32 v56, 1.0, v56
	v_add_f32_e32 v57, 1.0, v57
	v_pk_mul_f32 v[46:47], v[46:47], v[50:51]
	v_rcp_f32_e32 v56, v56
	v_rcp_f32_e32 v57, v57
	v_pk_mul_f32 v[38:39], v[46:47], v[38:39]
	v_pk_mul_f32 v[46:47], v[48:49], v[52:53]
	v_cvt_pk_f16_f32 v38, v38, v39
	v_pk_mul_f32 v[40:41], v[46:47], v[40:41]
	s_nop 0
	v_cvt_pk_f16_f32 v39, v40, v41
	v_pk_mul_f32 v[40:41], v[42:43], v[54:55]
	s_nop 0
	v_pk_mul_f32 v[34:35], v[40:41], v[34:35]
	s_nop 0
	v_cvt_pk_f16_f32 v40, v34, v35
	v_pk_mul_f32 v[34:35], v[44:45], v[56:57]
	s_nop 0
	v_pk_mul_f32 v[34:35], v[34:35], v[36:37]
	v_mul_f32_e32 v36, 0xbfb8aa3b, v30
	v_cvt_pk_f16_f32 v41, v34, v35
	v_add_u32_e32 v34, 0x90, v140
	v_mad_i64_i32 v[34:35], s[10:11], v34, s3, v[114:115]
	v_lshl_add_u64 v[34:35], v[34:35], 0, v[116:117]
	global_store_dwordx4 v[34:35], v[38:41], off
	v_mul_f32_e32 v34, 0xbfb8aa3b, v28
	v_mul_f32_e32 v35, 0xbfb8aa3b, v29
	v_exp_f32_e32 v34, v34
	v_exp_f32_e32 v35, v35
	v_mul_f32_e32 v37, 0xbfb8aa3b, v31
	v_exp_f32_e32 v36, v36
	v_exp_f32_e32 v37, v37
	v_mul_f32_e32 v38, 0xbfb8aa3b, v24
	v_mul_f32_e32 v39, 0xbfb8aa3b, v25
	v_exp_f32_e32 v38, v38
	v_exp_f32_e32 v39, v39
	v_mul_f32_e32 v40, 0xbfb8aa3b, v26
	v_mul_f32_e32 v41, 0xbfb8aa3b, v27
	v_add_f32_e32 v34, 1.0, v34
	v_add_f32_e32 v35, 1.0, v35
	v_exp_f32_e32 v40, v40
	v_exp_f32_e32 v41, v41
	v_rcp_f32_e32 v34, v34
	v_rcp_f32_e32 v35, v35
	v_add_f32_e32 v36, 1.0, v36
	v_add_f32_e32 v37, 1.0, v37
	v_rcp_f32_e32 v36, v36
	v_rcp_f32_e32 v37, v37
	v_add_f32_e32 v38, 1.0, v38
	v_add_f32_e32 v39, 1.0, v39
	v_rcp_f32_e32 v38, v38
	v_rcp_f32_e32 v39, v39
	v_add_f32_e32 v40, 1.0, v40
	v_add_f32_e32 v41, 1.0, v41
	v_pk_mul_f32 v[28:29], v[28:29], v[34:35]
	v_rcp_f32_e32 v40, v40
	v_rcp_f32_e32 v41, v41
	v_pk_mul_f32 v[20:21], v[28:29], v[20:21]
	v_pk_mul_f32 v[28:29], v[30:31], v[36:37]
	v_cvt_pk_f16_f32 v20, v20, v21
	v_pk_mul_f32 v[22:23], v[28:29], v[22:23]
	s_nop 0
	v_cvt_pk_f16_f32 v21, v22, v23
	v_pk_mul_f32 v[22:23], v[24:25], v[38:39]
	s_nop 0
	v_pk_mul_f32 v[16:17], v[22:23], v[16:17]
	s_nop 0
	v_cvt_pk_f16_f32 v22, v16, v17
	v_pk_mul_f32 v[16:17], v[26:27], v[40:41]
	s_nop 0
	v_pk_mul_f32 v[16:17], v[16:17], v[18:19]
	v_mul_f32_e32 v18, 0xbfb8aa3b, v14
	v_cvt_pk_f16_f32 v23, v16, v17
	v_add_u32_e32 v16, 0xa0, v140
	v_mad_i64_i32 v[16:17], s[10:11], v16, s3, v[114:115]
	v_lshl_add_u64 v[16:17], v[16:17], 0, v[116:117]
	global_store_dwordx4 v[16:17], v[20:23], off
	v_mul_f32_e32 v16, 0xbfb8aa3b, v12
	v_mul_f32_e32 v17, 0xbfb8aa3b, v13
	v_exp_f32_e32 v16, v16
	v_exp_f32_e32 v17, v17
	v_mul_f32_e32 v19, 0xbfb8aa3b, v15
	v_exp_f32_e32 v18, v18
	v_exp_f32_e32 v19, v19
	v_mul_f32_e32 v20, 0xbfb8aa3b, v8
	v_mul_f32_e32 v21, 0xbfb8aa3b, v9
	v_exp_f32_e32 v20, v20
	v_exp_f32_e32 v21, v21
	v_mul_f32_e32 v22, 0xbfb8aa3b, v10
	v_mul_f32_e32 v23, 0xbfb8aa3b, v11
	v_add_f32_e32 v16, 1.0, v16
	v_add_f32_e32 v17, 1.0, v17
	v_exp_f32_e32 v22, v22
	v_exp_f32_e32 v23, v23
	v_rcp_f32_e32 v16, v16
	v_rcp_f32_e32 v17, v17
	v_add_f32_e32 v18, 1.0, v18
	v_add_f32_e32 v19, 1.0, v19
	v_rcp_f32_e32 v18, v18
	v_rcp_f32_e32 v19, v19
	v_add_f32_e32 v20, 1.0, v20
	v_add_f32_e32 v21, 1.0, v21
	v_rcp_f32_e32 v20, v20
	v_rcp_f32_e32 v21, v21
	v_add_f32_e32 v22, 1.0, v22
	v_add_f32_e32 v23, 1.0, v23
	v_pk_mul_f32 v[12:13], v[12:13], v[16:17]
	v_rcp_f32_e32 v22, v22
	v_rcp_f32_e32 v23, v23
	v_pk_mul_f32 v[4:5], v[12:13], v[4:5]
	v_pk_mul_f32 v[12:13], v[14:15], v[18:19]
	v_cvt_pk_f16_f32 v4, v4, v5
	v_pk_mul_f32 v[6:7], v[12:13], v[6:7]
	s_nop 0
	v_cvt_pk_f16_f32 v5, v6, v7
	v_pk_mul_f32 v[6:7], v[8:9], v[20:21]
	s_nop 0
	v_pk_mul_f32 v[0:1], v[6:7], v[0:1]
	s_nop 0
	v_cvt_pk_f16_f32 v6, v0, v1
	v_pk_mul_f32 v[0:1], v[10:11], v[22:23]
	s_nop 0
	v_pk_mul_f32 v[0:1], v[0:1], v[2:3]
	s_nop 0
	v_cvt_pk_f16_f32 v7, v0, v1
	v_add_u32_e32 v0, 0xb0, v140
	v_mad_i64_i32 v[0:1], s[10:11], v0, s3, v[114:115]
	v_lshl_add_u64 v[0:1], v[0:1], 0, v[116:117]
	global_store_dwordx4 v[0:1], v[4:7], off
	s_cmp_lg_u32 s34, 1
	s_cbranch_scc1 .Lups_skip
	s_and_b32 s0, s91, 63
	s_cmp_gt_u32 s0, 5
	s_cbranch_scc1 .Lups_skip
	s_cmp_gt_u32 s91, 196
	s_cbranch_scc1 .Lups_skip
	s_waitcnt vmcnt(0)
	s_barrier
	v_readlane_b32 s0, v251, 36
	s_cmp_lg_u32 s0, 0
	s_cbranch_scc1 .Lups_skip
	buffer_wbl2 sc1
	s_waitcnt vmcnt(0)
	v_readlane_b32 s2, v255, 45
	v_readlane_b32 s3, v254, 25
	s_lshl_b32 s2, s2, 1
	s_cmp_eq_u32 s3, 0
	s_cselect_b32 s3, 1, 0
	s_add_i32 s2, s2, s3
	s_lshl_b32 s2, s2, 2
	s_add_i32 s2, s2, 14016
	v_readlane_b32 s0, v251, 32
	v_readlane_b32 s1, v251, 33
	s_add_u32 s0, s0, s2
	s_addc_u32 s1, s1, 0
	s_mov_b64 s[2:3], exec
	s_mov_b64 exec, 1
	global_atomic_add v33, v248, s[0:1]
	s_mov_b64 exec, s[2:3]

.LBB0_1365:
	s_add_i32 s46, s14, 2
	s_add_u32 s12, s10, 0x100
	s_addc_u32 s13, s11, 0
	s_add_i32 s47, 0, 0x10000
	v_add_u32_e32 v134, s47, v230
	ds_read_b128 v[106:109], v134
	ds_read_b128 v[114:117], v134 offset:2048
	ds_read_b128 v[110:113], v134 offset:1024
	ds_read_b128 v[134:137], v134 offset:3072
	s_cmp_eq_u32 s43, s14
	s_cselect_b32 s14, s8, s44
	s_cselect_b32 s17, s7, s13
	s_cselect_b32 s16, s6, s12
	s_cselect_b32 s15, s9, s45
	v_lshl_add_u64 v[178:179], s[10:11], 0, v[184:185]
	s_add_i32 m0, s24, 0xc000
	ds_read_b128 v[138:141], v232
	ds_read_b128 v[154:157], v232 offset:2048
	ds_read_b128 v[162:165], v232 offset:4096
	ds_read_b128 v[170:173], v232 offset:6144
	ds_read_b128 v[150:153], v232 offset:1024
	ds_read_b128 v[158:161], v232 offset:3072
	ds_read_b128 v[166:169], v232 offset:5120
	ds_read_b128 v[174:177], v232 offset:7168
	global_load_lds_dwordx4 v[178:179], off
	v_lshl_add_u64 v[178:179], s[10:11], 0, v[186:187]
	s_add_i32 m0, s24, 0xe000
	s_nop 0
	global_load_lds_dwordx4 v[178:179], off
	s_waitcnt lgkmcnt(8)
	s_barrier
	s_waitcnt lgkmcnt(7)
	v_mfma_f32_16x16x32_f16 v[146:149], v[106:109], v[138:141], v[146:149]
	v_mfma_f32_16x16x32_f16 v[142:145], v[114:117], v[138:141], v[142:145]
	s_waitcnt lgkmcnt(6)
	v_mfma_f32_16x16x32_f16 v[130:133], v[106:109], v[154:157], v[130:133]
	v_mfma_f32_16x16x32_f16 v[122:125], v[114:117], v[154:157], v[122:125]
	s_waitcnt lgkmcnt(5)
	v_mfma_f32_16x16x32_f16 v[94:97], v[106:109], v[162:165], v[94:97]
	v_mfma_f32_16x16x32_f16 v[90:93], v[114:117], v[162:165], v[90:93]
	s_waitcnt lgkmcnt(4)
	v_mfma_f32_16x16x32_f16 v[78:81], v[106:109], v[170:173], v[78:81]
	v_mfma_f32_16x16x32_f16 v[74:77], v[114:117], v[170:173], v[74:77]
	s_waitcnt lgkmcnt(3)
	v_mfma_f32_16x16x32_f16 v[146:149], v[110:113], v[150:153], v[146:149]
	v_mfma_f32_16x16x32_f16 v[142:145], v[134:137], v[150:153], v[142:145]
	s_waitcnt lgkmcnt(2)
	v_mfma_f32_16x16x32_f16 v[130:133], v[110:113], v[158:161], v[130:133]
	v_mfma_f32_16x16x32_f16 v[122:125], v[134:137], v[158:161], v[122:125]
	s_waitcnt lgkmcnt(1)
	v_mfma_f32_16x16x32_f16 v[94:97], v[110:113], v[166:169], v[94:97]
	v_mfma_f32_16x16x32_f16 v[90:93], v[134:137], v[166:169], v[90:93]
	s_waitcnt lgkmcnt(0)
	v_mfma_f32_16x16x32_f16 v[78:81], v[110:113], v[174:177], v[78:81]
	v_mfma_f32_16x16x32_f16 v[74:77], v[134:137], v[174:177], v[74:77]
	s_barrier
	s_add_i32 s48, 0, 0x14000
	s_add_i32 s10, s47, s23
	v_add_u32_e32 v196, s48, v230
	v_lshl_add_u64 v[200:201], s[14:15], 0, v[32:33]
	s_mov_b32 m0, s10
	ds_read_b128 v[178:181], v196
	ds_read_b128 v[192:195], v196 offset:2048
	ds_read_b128 v[188:191], v196 offset:1024
	ds_read_b128 v[196:199], v196 offset:3072
	global_load_lds_dwordx4 v[200:201], off
	v_lshl_add_u64 v[202:203], s[14:15], 0, v[182:183]
	s_add_i32 m0, s10, 0x2000
	s_nop 0
	global_load_lds_dwordx4 v[202:203], off
	s_barrier
	s_waitcnt lgkmcnt(2)
	v_mfma_f32_16x16x32_f16 v[126:129], v[178:181], v[138:141], v[126:129]
	v_mfma_f32_16x16x32_f16 v[118:121], v[192:195], v[138:141], v[118:121]
	v_mfma_f32_16x16x32_f16 v[102:105], v[178:181], v[154:157], v[102:105]
	v_mfma_f32_16x16x32_f16 v[98:101], v[192:195], v[154:157], v[98:101]
	v_mfma_f32_16x16x32_f16 v[86:89], v[178:181], v[162:165], v[86:89]
	v_mfma_f32_16x16x32_f16 v[82:85], v[192:195], v[162:165], v[82:85]
	v_mfma_f32_16x16x32_f16 v[70:73], v[178:181], v[170:173], v[70:73]
	v_mfma_f32_16x16x32_f16 v[66:69], v[192:195], v[170:173], v[66:69]
	s_waitcnt lgkmcnt(0)
	v_mfma_f32_16x16x32_f16 v[126:129], v[188:191], v[150:153], v[126:129]
	v_mfma_f32_16x16x32_f16 v[118:121], v[196:199], v[150:153], v[118:121]
	v_mfma_f32_16x16x32_f16 v[102:105], v[188:191], v[158:161], v[102:105]
	v_mfma_f32_16x16x32_f16 v[98:101], v[196:199], v[158:161], v[98:101]
	v_mfma_f32_16x16x32_f16 v[86:89], v[188:191], v[166:169], v[86:89]
	v_mfma_f32_16x16x32_f16 v[82:85], v[196:199], v[166:169], v[82:85]
	v_mfma_f32_16x16x32_f16 v[70:73], v[188:191], v[174:177], v[70:73]
	v_mfma_f32_16x16x32_f16 v[66:69], v[196:199], v[174:177], v[66:69]
	s_mov_b32 m0, s24
	v_lshl_add_u64 v[204:205], s[16:17], 0, v[32:33]
	s_barrier
	ds_read_b128 v[138:141], v232 offset:16384
	ds_read_b128 v[154:157], v232 offset:18432
	ds_read_b128 v[162:165], v232 offset:20480
	ds_read_b128 v[170:173], v232 offset:22528
	ds_read_b128 v[150:153], v232 offset:17408
	ds_read_b128 v[158:161], v232 offset:19456
	ds_read_b128 v[166:169], v232 offset:21504
	ds_read_b128 v[174:177], v232 offset:23552
	global_load_lds_dwordx4 v[204:205], off
	v_lshl_add_u64 v[206:207], s[16:17], 0, v[182:183]
	s_mov_b32 m0, s25
	s_nop 0
	global_load_lds_dwordx4 v[206:207], off
	s_barrier
	s_waitcnt lgkmcnt(7)
	v_mfma_f32_16x16x32_f16 v[62:65], v[106:109], v[138:141], v[62:65]
	v_mfma_f32_16x16x32_f16 v[58:61], v[114:117], v[138:141], v[58:61]
	s_waitcnt lgkmcnt(6)
	v_mfma_f32_16x16x32_f16 v[46:49], v[106:109], v[154:157], v[46:49]
	v_mfma_f32_16x16x32_f16 v[42:45], v[114:117], v[154:157], v[42:45]
	s_waitcnt lgkmcnt(5)
	v_mfma_f32_16x16x32_f16 v[28:31], v[106:109], v[162:165], v[28:31]
	v_mfma_f32_16x16x32_f16 v[24:27], v[114:117], v[162:165], v[24:27]
	s_waitcnt lgkmcnt(4)
	v_mfma_f32_16x16x32_f16 v[12:15], v[106:109], v[170:173], v[12:15]
	v_mfma_f32_16x16x32_f16 v[8:11], v[114:117], v[170:173], v[8:11]
	s_waitcnt lgkmcnt(3)
	v_mfma_f32_16x16x32_f16 v[62:65], v[110:113], v[150:153], v[62:65]
	v_mfma_f32_16x16x32_f16 v[58:61], v[134:137], v[150:153], v[58:61]
	s_waitcnt lgkmcnt(2)
	v_mfma_f32_16x16x32_f16 v[46:49], v[110:113], v[158:161], v[46:49]
	v_mfma_f32_16x16x32_f16 v[42:45], v[134:137], v[158:161], v[42:45]
	s_waitcnt lgkmcnt(1)
	v_mfma_f32_16x16x32_f16 v[28:31], v[110:113], v[166:169], v[28:31]
	v_mfma_f32_16x16x32_f16 v[24:27], v[134:137], v[166:169], v[24:27]
	s_waitcnt lgkmcnt(0)
	v_mfma_f32_16x16x32_f16 v[12:15], v[110:113], v[174:177], v[12:15]
	v_mfma_f32_16x16x32_f16 v[8:11], v[134:137], v[174:177], v[8:11]
	s_barrier
	s_add_u32 s10, s14, 0xb0000
	s_addc_u32 s11, s15, 0
	s_add_i32 s47, s48, s23
	v_lshl_add_u64 v[106:107], s[10:11], 0, v[32:33]
	s_mov_b32 m0, s47
	s_nop 0
	global_load_lds_dwordx4 v[106:107], off
	v_lshl_add_u64 v[106:107], s[10:11], 0, v[182:183]
	s_add_i32 m0, s47, 0x2000
	s_nop 0
	global_load_lds_dwordx4 v[106:107], off
	s_waitcnt vmcnt(6)
	s_barrier
	v_mfma_f32_16x16x32_f16 v[54:57], v[178:181], v[138:141], v[54:57]
	v_mfma_f32_16x16x32_f16 v[50:53], v[192:195], v[138:141], v[50:53]
	v_mfma_f32_16x16x32_f16 v[38:41], v[178:181], v[154:157], v[38:41]
	v_mfma_f32_16x16x32_f16 v[34:37], v[192:195], v[154:157], v[34:37]
	v_mfma_f32_16x16x32_f16 v[20:23], v[178:181], v[162:165], v[20:23]
	v_mfma_f32_16x16x32_f16 v[16:19], v[192:195], v[162:165], v[16:19]
	v_mfma_f32_16x16x32_f16 v[4:7], v[178:181], v[170:173], v[4:7]
	v_mfma_f32_16x16x32_f16 v[0:3], v[192:195], v[170:173], v[0:3]
	v_mfma_f32_16x16x32_f16 v[54:57], v[188:191], v[150:153], v[54:57]
	v_mfma_f32_16x16x32_f16 v[50:53], v[196:199], v[150:153], v[50:53]
	v_mfma_f32_16x16x32_f16 v[38:41], v[188:191], v[158:161], v[38:41]
	v_mfma_f32_16x16x32_f16 v[34:37], v[196:199], v[158:161], v[34:37]
	v_mfma_f32_16x16x32_f16 v[20:23], v[188:191], v[166:169], v[20:23]
	v_mfma_f32_16x16x32_f16 v[16:19], v[196:199], v[166:169], v[16:19]
	v_mfma_f32_16x16x32_f16 v[4:7], v[188:191], v[174:177], v[4:7]
	v_mfma_f32_16x16x32_f16 v[0:3], v[196:199], v[174:177], v[0:3]
	s_add_i32 s47, 0, 0x18000
	v_add_u32_e32 v134, s47, v230
	s_barrier
	ds_read_b128 v[106:109], v134
	ds_read_b128 v[114:117], v134 offset:2048
	ds_read_b128 v[110:113], v134 offset:1024
	ds_read_b128 v[134:137], v134 offset:3072
	s_add_u32 s10, s16, 0xb0000
	s_addc_u32 s11, s17, 0
	s_mov_b32 m0, s26
	v_lshl_add_u64 v[178:179], s[10:11], 0, v[32:33]
	ds_read_b128 v[138:141], v232 offset:32768
	ds_read_b128 v[154:157], v232 offset:34816
	ds_read_b128 v[162:165], v232 offset:36864
	ds_read_b128 v[170:173], v232 offset:38912
	ds_read_b128 v[150:153], v232 offset:33792
	ds_read_b128 v[158:161], v232 offset:35840
	ds_read_b128 v[166:169], v232 offset:37888
	ds_read_b128 v[174:177], v232 offset:39936
	global_load_lds_dwordx4 v[178:179], off
	v_lshl_add_u64 v[178:179], s[10:11], 0, v[182:183]
	s_mov_b32 m0, s27
	s_nop 0
	global_load_lds_dwordx4 v[178:179], off
	s_waitcnt lgkmcnt(8)
	s_barrier
	s_waitcnt lgkmcnt(7)
	v_mfma_f32_16x16x32_f16 v[146:149], v[106:109], v[138:141], v[146:149]
	v_mfma_f32_16x16x32_f16 v[142:145], v[114:117], v[138:141], v[142:145]
	s_waitcnt lgkmcnt(6)
	v_mfma_f32_16x16x32_f16 v[130:133], v[106:109], v[154:157], v[130:133]
	v_mfma_f32_16x16x32_f16 v[122:125], v[114:117], v[154:157], v[122:125]
	s_waitcnt lgkmcnt(5)
	v_mfma_f32_16x16x32_f16 v[94:97], v[106:109], v[162:165], v[94:97]
	v_mfma_f32_16x16x32_f16 v[90:93], v[114:117], v[162:165], v[90:93]
	s_waitcnt lgkmcnt(4)
	v_mfma_f32_16x16x32_f16 v[78:81], v[106:109], v[170:173], v[78:81]
	v_mfma_f32_16x16x32_f16 v[74:77], v[114:117], v[170:173], v[74:77]
	s_waitcnt lgkmcnt(3)
	v_mfma_f32_16x16x32_f16 v[146:149], v[110:113], v[150:153], v[146:149]
	v_mfma_f32_16x16x32_f16 v[142:145], v[134:137], v[150:153], v[142:145]
	s_waitcnt lgkmcnt(2)
	v_mfma_f32_16x16x32_f16 v[130:133], v[110:113], v[158:161], v[130:133]
	v_mfma_f32_16x16x32_f16 v[122:125], v[134:137], v[158:161], v[122:125]
	s_waitcnt lgkmcnt(1)
	v_mfma_f32_16x16x32_f16 v[94:97], v[110:113], v[166:169], v[94:97]
	v_mfma_f32_16x16x32_f16 v[90:93], v[134:137], v[166:169], v[90:93]
	s_waitcnt lgkmcnt(0)
	v_mfma_f32_16x16x32_f16 v[78:81], v[110:113], v[174:177], v[78:81]
	v_mfma_f32_16x16x32_f16 v[74:77], v[134:137], v[174:177], v[74:77]
	s_barrier
	s_add_i32 s16, 0, 0x1c000
	s_add_i32 s10, s47, s23
	v_add_u32_e32 v196, s16, v230
	v_lshl_add_u64 v[200:201], v[200:201], 0, s[84:85]
	s_mov_b32 m0, s10
	ds_read_b128 v[178:181], v196
	ds_read_b128 v[192:195], v196 offset:2048
	ds_read_b128 v[188:191], v196 offset:1024
	ds_read_b128 v[196:199], v196 offset:3072
	global_load_lds_dwordx4 v[200:201], off
	v_lshl_add_u64 v[200:201], v[202:203], 0, s[84:85]
	s_add_i32 m0, s10, 0x2000
	s_nop 0
	global_load_lds_dwordx4 v[200:201], off
	s_barrier
	s_waitcnt lgkmcnt(2)
	v_mfma_f32_16x16x32_f16 v[126:129], v[178:181], v[138:141], v[126:129]
	v_mfma_f32_16x16x32_f16 v[118:121], v[192:195], v[138:141], v[118:121]
	v_mfma_f32_16x16x32_f16 v[102:105], v[178:181], v[154:157], v[102:105]
	v_mfma_f32_16x16x32_f16 v[98:101], v[192:195], v[154:157], v[98:101]
	v_mfma_f32_16x16x32_f16 v[86:89], v[178:181], v[162:165], v[86:89]
	v_mfma_f32_16x16x32_f16 v[82:85], v[192:195], v[162:165], v[82:85]
	v_mfma_f32_16x16x32_f16 v[70:73], v[178:181], v[170:173], v[70:73]
	v_mfma_f32_16x16x32_f16 v[66:69], v[192:195], v[170:173], v[66:69]
	s_waitcnt lgkmcnt(0)
	v_mfma_f32_16x16x32_f16 v[126:129], v[188:191], v[150:153], v[126:129]
	v_mfma_f32_16x16x32_f16 v[118:121], v[196:199], v[150:153], v[118:121]
	v_mfma_f32_16x16x32_f16 v[102:105], v[188:191], v[158:161], v[102:105]
	v_mfma_f32_16x16x32_f16 v[98:101], v[196:199], v[158:161], v[98:101]
	v_mfma_f32_16x16x32_f16 v[86:89], v[188:191], v[166:169], v[86:89]
	v_mfma_f32_16x16x32_f16 v[82:85], v[196:199], v[166:169], v[82:85]
	v_mfma_f32_16x16x32_f16 v[70:73], v[188:191], v[174:177], v[70:73]
	v_mfma_f32_16x16x32_f16 v[66:69], v[196:199], v[174:177], v[66:69]
	s_mov_b32 m0, s29
	v_lshl_add_u64 v[200:201], v[204:205], 0, s[84:85]
	s_barrier
	ds_read_b128 v[138:141], v232 offset:49152
	ds_read_b128 v[154:157], v232 offset:51200
	ds_read_b128 v[162:165], v232 offset:53248
	ds_read_b128 v[170:173], v232 offset:55296
	ds_read_b128 v[150:153], v232 offset:50176
	ds_read_b128 v[158:161], v232 offset:52224
	ds_read_b128 v[166:169], v232 offset:54272
	ds_read_b128 v[174:177], v232 offset:56320
	global_load_lds_dwordx4 v[200:201], off
	v_lshl_add_u64 v[200:201], v[206:207], 0, s[84:85]
	s_mov_b32 m0, s30
	s_nop 0
	global_load_lds_dwordx4 v[200:201], off
	s_barrier
	s_waitcnt lgkmcnt(7)
	v_mfma_f32_16x16x32_f16 v[62:65], v[106:109], v[138:141], v[62:65]
	v_mfma_f32_16x16x32_f16 v[58:61], v[114:117], v[138:141], v[58:61]
	s_waitcnt lgkmcnt(6)
	v_mfma_f32_16x16x32_f16 v[46:49], v[106:109], v[154:157], v[46:49]
	v_mfma_f32_16x16x32_f16 v[42:45], v[114:117], v[154:157], v[42:45]
	s_waitcnt lgkmcnt(5)
	v_mfma_f32_16x16x32_f16 v[28:31], v[106:109], v[162:165], v[28:31]
	v_mfma_f32_16x16x32_f16 v[24:27], v[114:117], v[162:165], v[24:27]
	s_waitcnt lgkmcnt(4)
	v_mfma_f32_16x16x32_f16 v[12:15], v[106:109], v[170:173], v[12:15]
	v_mfma_f32_16x16x32_f16 v[8:11], v[114:117], v[170:173], v[8:11]
	s_waitcnt lgkmcnt(3)
	v_mfma_f32_16x16x32_f16 v[62:65], v[110:113], v[150:153], v[62:65]
	v_mfma_f32_16x16x32_f16 v[58:61], v[134:137], v[150:153], v[58:61]
	s_waitcnt lgkmcnt(2)
	v_mfma_f32_16x16x32_f16 v[46:49], v[110:113], v[158:161], v[46:49]
	v_mfma_f32_16x16x32_f16 v[42:45], v[134:137], v[158:161], v[42:45]
	s_waitcnt lgkmcnt(1)
	v_mfma_f32_16x16x32_f16 v[28:31], v[110:113], v[166:169], v[28:31]
	v_mfma_f32_16x16x32_f16 v[24:27], v[134:137], v[166:169], v[24:27]
	s_waitcnt lgkmcnt(0)
	v_mfma_f32_16x16x32_f16 v[12:15], v[110:113], v[174:177], v[12:15]
	v_mfma_f32_16x16x32_f16 v[8:11], v[134:137], v[174:177], v[8:11]
	s_barrier
	s_add_u32 s10, s14, 0xb0080
	s_addc_u32 s11, s15, 0
	s_add_i32 s14, s16, s23
	v_lshl_add_u64 v[106:107], s[10:11], 0, v[32:33]
	s_mov_b32 m0, s14
	s_nop 0
	global_load_lds_dwordx4 v[106:107], off
	v_lshl_add_u64 v[106:107], s[10:11], 0, v[182:183]
	s_add_i32 m0, s14, 0x2000
	s_nop 0
	global_load_lds_dwordx4 v[106:107], off
	s_waitcnt vmcnt(6)
	s_barrier
	v_mfma_f32_16x16x32_f16 v[54:57], v[178:181], v[138:141], v[54:57]
	v_mfma_f32_16x16x32_f16 v[50:53], v[192:195], v[138:141], v[50:53]
	v_mfma_f32_16x16x32_f16 v[38:41], v[178:181], v[154:157], v[38:41]
	v_mfma_f32_16x16x32_f16 v[34:37], v[192:195], v[154:157], v[34:37]
	v_mfma_f32_16x16x32_f16 v[20:23], v[178:181], v[162:165], v[20:23]
	v_mfma_f32_16x16x32_f16 v[16:19], v[192:195], v[162:165], v[16:19]
	v_mfma_f32_16x16x32_f16 v[4:7], v[178:181], v[170:173], v[4:7]
	v_mfma_f32_16x16x32_f16 v[0:3], v[192:195], v[170:173], v[0:3]
	v_mfma_f32_16x16x32_f16 v[54:57], v[188:191], v[150:153], v[54:57]
	v_mfma_f32_16x16x32_f16 v[50:53], v[196:199], v[150:153], v[50:53]
	v_mfma_f32_16x16x32_f16 v[38:41], v[188:191], v[158:161], v[38:41]
	v_mfma_f32_16x16x32_f16 v[34:37], v[196:199], v[158:161], v[34:37]
	v_mfma_f32_16x16x32_f16 v[20:23], v[188:191], v[166:169], v[20:23]
	v_mfma_f32_16x16x32_f16 v[16:19], v[196:199], v[166:169], v[16:19]
	v_mfma_f32_16x16x32_f16 v[4:7], v[188:191], v[174:177], v[4:7]
	v_mfma_f32_16x16x32_f16 v[0:3], v[196:199], v[174:177], v[0:3]
	s_add_u32 s44, s44, 0x100
	s_addc_u32 s45, s45, 0
	s_cmp_ge_u32 s46, s42
	s_mov_b64 s[10:11], s[12:13]
	s_mov_b32 s14, s46
	s_barrier
	s_cbranch_scc0 .LBB0_1365
	s_cmp_eq_u32 s40, 0
	s_cselect_b32 s6, 0x9000, 0
	v_lshl_or_b32 v106, s41, 8, v231
	s_add_u32 s6, s31, s6
	s_addc_u32 s7, s34, 0
	v_ashrrev_i32_e32 v107, 31, v106
	v_lshl_add_u64 v[116:117], v[106:107], 2, s[6:7]
	global_load_dwordx4 v[108:111], v[116:117], off offset:16
	global_load_dwordx4 v[112:115], v[116:117], off
	s_cmp_eq_u32 s39, 0
	s_waitcnt vmcnt(0)
	v_pk_mul_f32 v[194:195], v[110:111], 0.5 op_sel_hi:[1,0]
	v_pk_mul_f32 v[198:199], v[114:115], 0.5 op_sel_hi:[1,0]
	v_pk_mul_f32 v[202:203], v[112:113], 0.5 op_sel_hi:[1,0]
	v_pk_mul_f32 v[200:201], v[108:109], 0.5 op_sel_hi:[1,0]
	global_load_dwordx4 v[108:111], v[116:117], off offset:528
	global_load_dwordx4 v[112:115], v[116:117], off offset:512
	s_waitcnt vmcnt(0)
	v_pk_mul_f32 v[188:189], v[110:111], 0.5 op_sel_hi:[1,0]
	v_pk_mul_f32 v[196:197], v[112:113], 0.5 op_sel_hi:[1,0]
	v_lshl_add_u32 v112, s40, 8, v229
	v_pk_mul_f32 v[190:191], v[114:115], 0.5 op_sel_hi:[1,0]
	v_pk_mul_f32 v[192:193], v[108:109], 0.5 op_sel_hi:[1,0]
	v_or_b32_e32 v114, 16, v112
	v_or_b32_e32 v110, 32, v112
	v_or_b32_e32 v108, 48, v112
	v_ashrrev_i32_e32 v113, 31, v112
	v_ashrrev_i32_e32 v115, 31, v114
	v_ashrrev_i32_e32 v111, 31, v110
	v_ashrrev_i32_e32 v109, 31, v108
	s_cbranch_scc1 .LBB0_1368
	s_add_i32 s96, s39, -1
	s_lshl_b64 s[6:7], s[96:97], 20
	v_readlane_b32 s8, v252, 11
	v_readlane_b32 s9, v252, 12
	s_add_u32 s6, s8, s6
	s_addc_u32 s7, s9, s7
	v_lshlrev_b64 v[138:139], 2, v[106:107]
	v_lshrrev_b32_e32 v150, 5, v220
	v_mul_u32_u24_e32 v150, 48, v150
	s_nop 0
	v_sub_co_u32_e32 v138, vcc, v138, v150
	s_nop 1
	v_subbrev_co_u32_e32 v139, vcc, 0, v139, vcc
	v_lshl_add_u64 v[138:139], s[6:7], 0, v[138:139]
	s_mov_b64 s[6:7], 0x80000
	v_lshlrev_b64 v[204:205], 12, v[112:113]
	v_lshl_add_u64 v[204:205], v[204:205], 0, v[138:139]
	v_lshl_add_u64 v[212:213], v[204:205], 0, s[6:7]
	v_lshlrev_b64 v[206:207], 12, v[114:115]
	v_lshl_add_u64 v[206:207], v[206:207], 0, v[138:139]
	v_lshl_add_u64 v[214:215], v[206:207], 0, s[6:7]
	v_lshlrev_b64 v[208:209], 12, v[110:111]
	v_lshl_add_u64 v[208:209], v[208:209], 0, v[138:139]
	v_lshl_add_u64 v[216:217], v[208:209], 0, s[6:7]
	v_lshlrev_b64 v[210:211], 12, v[108:109]
	v_lshl_add_u64 v[210:211], v[210:211], 0, v[138:139]
	v_lshl_add_u64 v[218:219], v[210:211], 0, s[6:7]
	s_waitcnt vmcnt(0)
	v_pk_mul_f32 v[152:153], v[146:147], v[202:203]
	v_pk_mul_f32 v[154:155], v[148:149], v[198:199]
	v_pk_mul_f32 v[156:157], v[142:143], v[200:201]
	v_pk_mul_f32 v[158:159], v[144:145], v[194:195]
	s_nop 1
	v_permlane32_swap_b32_e32 v152, v156
	v_permlane32_swap_b32_e32 v153, v157
	v_permlane32_swap_b32_e32 v154, v158
	v_permlane32_swap_b32_e32 v155, v159
	s_nop 0
	global_store_dwordx4 v[204:205], v[152:155], off
	global_store_dwordx4 v[204:205], v[156:159], off offset:64
	v_pk_mul_f32 v[160:161], v[126:127], v[196:197]
	v_pk_mul_f32 v[162:163], v[128:129], v[190:191]
	v_pk_mul_f32 v[164:165], v[118:119], v[192:193]
	v_pk_mul_f32 v[166:167], v[120:121], v[188:189]
	s_nop 1
	v_permlane32_swap_b32_e32 v160, v164
	v_permlane32_swap_b32_e32 v161, v165
	v_permlane32_swap_b32_e32 v162, v166
	v_permlane32_swap_b32_e32 v163, v167
	s_nop 0
	global_store_dwordx4 v[204:205], v[160:163], off offset:512
	global_store_dwordx4 v[204:205], v[164:167], off offset:576
	v_pk_mul_f32 v[168:169], v[130:131], v[202:203]
	v_pk_mul_f32 v[170:171], v[132:133], v[198:199]
	v_pk_mul_f32 v[172:173], v[122:123], v[200:201]
	v_pk_mul_f32 v[174:175], v[124:125], v[194:195]
	s_nop 1
	v_permlane32_swap_b32_e32 v168, v172
	v_permlane32_swap_b32_e32 v169, v173
	v_permlane32_swap_b32_e32 v170, v174
	v_permlane32_swap_b32_e32 v171, v175
	s_nop 0
	global_store_dwordx4 v[206:207], v[168:171], off
	global_store_dwordx4 v[206:207], v[172:175], off offset:64
	v_pk_mul_f32 v[176:177], v[102:103], v[196:197]
	v_pk_mul_f32 v[178:179], v[104:105], v[190:191]
	v_pk_mul_f32 v[180:181], v[98:99], v[192:193]
	v_pk_mul_f32 v[182:183], v[100:101], v[188:189]
	s_nop 1
	v_permlane32_swap_b32_e32 v176, v180
	v_permlane32_swap_b32_e32 v177, v181
	v_permlane32_swap_b32_e32 v178, v182
	v_permlane32_swap_b32_e32 v179, v183
	s_nop 0
	global_store_dwordx4 v[206:207], v[176:179], off offset:512
	global_store_dwordx4 v[206:207], v[180:183], off offset:576
	v_pk_mul_f32 v[152:153], v[94:95], v[202:203]
	v_pk_mul_f32 v[154:155], v[96:97], v[198:199]
	v_pk_mul_f32 v[156:157], v[90:91], v[200:201]
	v_pk_mul_f32 v[158:159], v[92:93], v[194:195]
	s_nop 1
	v_permlane32_swap_b32_e32 v152, v156
	v_permlane32_swap_b32_e32 v153, v157
	v_permlane32_swap_b32_e32 v154, v158
	v_permlane32_swap_b32_e32 v155, v159
	s_nop 0
	global_store_dwordx4 v[208:209], v[152:155], off
	global_store_dwordx4 v[208:209], v[156:159], off offset:64
	v_pk_mul_f32 v[160:161], v[86:87], v[196:197]
	v_pk_mul_f32 v[162:163], v[88:89], v[190:191]
	v_pk_mul_f32 v[164:165], v[82:83], v[192:193]
	v_pk_mul_f32 v[166:167], v[84:85], v[188:189]
	s_nop 1
	v_permlane32_swap_b32_e32 v160, v164
	v_permlane32_swap_b32_e32 v161, v165
	v_permlane32_swap_b32_e32 v162, v166
	v_permlane32_swap_b32_e32 v163, v167
	s_nop 0
	global_store_dwordx4 v[208:209], v[160:163], off offset:512
	global_store_dwordx4 v[208:209], v[164:167], off offset:576
	v_pk_mul_f32 v[168:169], v[78:79], v[202:203]
	v_pk_mul_f32 v[170:171], v[80:81], v[198:199]
	v_pk_mul_f32 v[172:173], v[74:75], v[200:201]
	v_pk_mul_f32 v[174:175], v[76:77], v[194:195]
	s_nop 1
	v_permlane32_swap_b32_e32 v168, v172
	v_permlane32_swap_b32_e32 v169, v173
	v_permlane32_swap_b32_e32 v170, v174
	v_permlane32_swap_b32_e32 v171, v175
	s_nop 0
	global_store_dwordx4 v[210:211], v[168:171], off
	global_store_dwordx4 v[210:211], v[172:175], off offset:64
	v_pk_mul_f32 v[176:177], v[70:71], v[196:197]
	v_pk_mul_f32 v[178:179], v[72:73], v[190:191]
	v_pk_mul_f32 v[180:181], v[66:67], v[192:193]
	v_pk_mul_f32 v[182:183], v[68:69], v[188:189]
	s_nop 1
	v_permlane32_swap_b32_e32 v176, v180
	v_permlane32_swap_b32_e32 v177, v181
	v_permlane32_swap_b32_e32 v178, v182
	v_permlane32_swap_b32_e32 v179, v183
	s_nop 0
	global_store_dwordx4 v[210:211], v[176:179], off offset:512
	global_store_dwordx4 v[210:211], v[180:183], off offset:576
	v_pk_mul_f32 v[152:153], v[62:63], v[202:203]
	v_pk_mul_f32 v[154:155], v[64:65], v[198:199]
	v_pk_mul_f32 v[156:157], v[58:59], v[200:201]
	v_pk_mul_f32 v[158:159], v[60:61], v[194:195]
	s_nop 1
	v_permlane32_swap_b32_e32 v152, v156
	v_permlane32_swap_b32_e32 v153, v157
	v_permlane32_swap_b32_e32 v154, v158
	v_permlane32_swap_b32_e32 v155, v159
	s_nop 0
	global_store_dwordx4 v[212:213], v[152:155], off
	global_store_dwordx4 v[212:213], v[156:159], off offset:64
	v_pk_mul_f32 v[160:161], v[54:55], v[196:197]
	v_pk_mul_f32 v[162:163], v[56:57], v[190:191]
	v_pk_mul_f32 v[164:165], v[50:51], v[192:193]
	v_pk_mul_f32 v[166:167], v[52:53], v[188:189]
	s_nop 1
	v_permlane32_swap_b32_e32 v160, v164
	v_permlane32_swap_b32_e32 v161, v165
	v_permlane32_swap_b32_e32 v162, v166
	v_permlane32_swap_b32_e32 v163, v167
	s_nop 0
	global_store_dwordx4 v[212:213], v[160:163], off offset:512
	global_store_dwordx4 v[212:213], v[164:167], off offset:576
	v_pk_mul_f32 v[168:169], v[46:47], v[202:203]
	v_pk_mul_f32 v[170:171], v[48:49], v[198:199]
	v_pk_mul_f32 v[172:173], v[42:43], v[200:201]
	v_pk_mul_f32 v[174:175], v[44:45], v[194:195]
	s_nop 1
	v_permlane32_swap_b32_e32 v168, v172
	v_permlane32_swap_b32_e32 v169, v173
	v_permlane32_swap_b32_e32 v170, v174
	v_permlane32_swap_b32_e32 v171, v175
	s_nop 0
	global_store_dwordx4 v[214:215], v[168:171], off
	global_store_dwordx4 v[214:215], v[172:175], off offset:64
	v_pk_mul_f32 v[176:177], v[38:39], v[196:197]
	v_pk_mul_f32 v[178:179], v[40:41], v[190:191]
	v_pk_mul_f32 v[180:181], v[34:35], v[192:193]
	v_pk_mul_f32 v[182:183], v[36:37], v[188:189]
	s_nop 1
	v_permlane32_swap_b32_e32 v176, v180
	v_permlane32_swap_b32_e32 v177, v181
	v_permlane32_swap_b32_e32 v178, v182
	v_permlane32_swap_b32_e32 v179, v183
	s_nop 0
	global_store_dwordx4 v[214:215], v[176:179], off offset:512
	global_store_dwordx4 v[214:215], v[180:183], off offset:576
	v_pk_mul_f32 v[152:153], v[28:29], v[202:203]
	v_pk_mul_f32 v[154:155], v[30:31], v[198:199]
	v_pk_mul_f32 v[156:157], v[24:25], v[200:201]
	v_pk_mul_f32 v[158:159], v[26:27], v[194:195]
	s_nop 1
	v_permlane32_swap_b32_e32 v152, v156
	v_permlane32_swap_b32_e32 v153, v157
	v_permlane32_swap_b32_e32 v154, v158
	v_permlane32_swap_b32_e32 v155, v159
	s_nop 0
	global_store_dwordx4 v[216:217], v[152:155], off
	global_store_dwordx4 v[216:217], v[156:159], off offset:64
	v_pk_mul_f32 v[160:161], v[20:21], v[196:197]
	v_pk_mul_f32 v[162:163], v[22:23], v[190:191]
	v_pk_mul_f32 v[164:165], v[16:17], v[192:193]
	v_pk_mul_f32 v[166:167], v[18:19], v[188:189]
	s_nop 1
	v_permlane32_swap_b32_e32 v160, v164
	v_permlane32_swap_b32_e32 v161, v165
	v_permlane32_swap_b32_e32 v162, v166
	v_permlane32_swap_b32_e32 v163, v167
	s_nop 0
	global_store_dwordx4 v[216:217], v[160:163], off offset:512
	global_store_dwordx4 v[216:217], v[164:167], off offset:576
	v_pk_mul_f32 v[168:169], v[12:13], v[202:203]
	v_pk_mul_f32 v[170:171], v[14:15], v[198:199]
	v_pk_mul_f32 v[172:173], v[8:9], v[200:201]
	v_pk_mul_f32 v[174:175], v[10:11], v[194:195]
	s_nop 1
	v_permlane32_swap_b32_e32 v168, v172
	v_permlane32_swap_b32_e32 v169, v173
	v_permlane32_swap_b32_e32 v170, v174
	v_permlane32_swap_b32_e32 v171, v175
	s_nop 0
	global_store_dwordx4 v[218:219], v[168:171], off
	global_store_dwordx4 v[218:219], v[172:175], off offset:64
	v_pk_mul_f32 v[176:177], v[4:5], v[196:197]
	v_pk_mul_f32 v[178:179], v[6:7], v[190:191]
	v_pk_mul_f32 v[180:181], v[0:1], v[192:193]
	v_pk_mul_f32 v[182:183], v[2:3], v[188:189]
	s_nop 1
	v_permlane32_swap_b32_e32 v176, v180
	v_permlane32_swap_b32_e32 v177, v181
	v_permlane32_swap_b32_e32 v178, v182
	v_permlane32_swap_b32_e32 v179, v183
	s_nop 0
	global_store_dwordx4 v[218:219], v[176:179], off offset:512
	global_store_dwordx4 v[218:219], v[180:183], off offset:576
	s_cbranch_execnz .LBB0_1352
	s_branch .LBB0_1351
